# attention: scores masked in place with -inf, 271 redundant p-mask cndmasks and 46 canonicalize ops removed
# speedup vs baseline: 1.0100x; 1.0041x over previous
.LBB0_244:
	s_cmpk_gt_i32 s71, 0x2fff
	v_writelane_b32 v253, s72, 43
	s_cbranch_scc1 .LBB0_248
	s_waitcnt vmcnt(10)
	v_ashrrev_i32_e32 v5, 4, v0
	v_bfe_u32 v1, v0, 2, 2
	v_lshlrev_b32_e32 v154, 2, v5
	s_mul_i32 s0, s72, 0x2400
	v_lshlrev_b32_e32 v6, 3, v0
	v_or_b32_e32 v1, v154, v1
	s_movk_i32 s1, 0x90
	s_add_i32 s0, s0, 0
	v_lshlrev_b32_e32 v2, 3, v5
	v_mul_lo_u32 v1, v1, s1
	v_and_b32_e32 v5, 24, v6
	v_add3_u32 v169, s0, v1, v5
	v_add_u32_e32 v1, 64, v246
	v_cmp_lt_i32_e32 vcc, v241, v1
	v_ashrrev_i32_e32 v155, 31, v154
	s_waitcnt vmcnt(9)
	v_not_b32_e32 v10, 63
	v_cndmask_b32_e32 v5, v174, v241, vcc
	v_cmp_lt_i32_e32 vcc, v240, v1
	v_and_b32_e32 v166, 15, v0
	v_lshl_add_u64 v[156:157], v[154:155], 1, s[2:3]
	v_cndmask_b32_e32 v1, v174, v240, vcc
	v_lshlrev_b32_e32 v171, 2, v1
	v_add_u32_e32 v1, 64, v0
	v_ashrrev_i32_e32 v172, 3, v1
	v_add_u32_e32 v1, 0x80, v0
	v_ashrrev_i32_e32 v155, 3, v0
	v_ashrrev_i32_e32 v173, 3, v1
	v_add_u32_e32 v1, 0xc0, v0
	v_lshl_or_b32 v211, v0, 2, v10
	v_add_u32_e32 v0, 0xfff00000, v154
	v_cmp_eq_u32_e64 s[36:37], 0, v0
	v_cmp_eq_u32_e64 s[4:5], -16, v0
	v_add_u32_e32 v0, 0xfff00020, v154
	v_cmp_eq_u32_e64 s[6:7], 0, v0
	v_cmp_eq_u32_e64 s[8:9], -16, v0
	v_add_u32_e32 v0, 0xfff00040, v154
	v_and_b32_e32 v4, 56, v6
	v_ashrrev_i32_e32 v182, 3, v1
	v_cmp_eq_u32_e64 s[10:11], 0, v0
	v_cmp_eq_u32_e64 s[12:13], -16, v0
	v_add_u32_e32 v0, 0xfff00060, v154
	v_lshlrev_b32_e32 v167, 4, v166
	v_ashrrev_i32_e32 v3, 31, v2
	v_lshl_add_u32 v7, v4, 1, s0
	v_or_b32_e32 v8, 0xffffffc0, v166
	v_lshlrev_b32_e32 v170, 2, v5
	v_mul_lo_u32 v1, v155, s1
	v_mul_lo_u32 v5, v172, s1
	v_mul_lo_u32 v6, v173, s1
	v_mul_lo_u32 v9, v182, s1
	v_add_u32_e32 v11, 32, v155
	s_waitcnt vmcnt(8)
	v_add_u32_e32 v12, 32, v172
	v_add_u32_e32 v13, 32, v173
	v_add_u32_e32 v14, 32, v182
	v_add_u32_e32 v15, 64, v155
	s_waitcnt vmcnt(7)
	v_add_u32_e32 v16, 64, v172
	v_add_u32_e32 v17, 64, v173
	v_add_u32_e32 v18, 64, v182
	v_lshlrev_b32_e32 v213, 4, v155
	v_lshlrev_b32_e32 v215, 4, v172
	v_lshlrev_b32_e32 v217, 4, v173
	v_lshlrev_b32_e32 v219, 4, v182
	v_cmp_eq_u32_e64 s[14:15], 0, v0
	v_cmp_eq_u32_e64 s[16:17], -16, v0
	v_add_u32_e32 v0, 0xfff00080, v154
	s_mov_b32 s57, 0
	v_mov_b32_e32 v153, 0
	v_add_u32_e32 v187, 32, v154
	v_add_u32_e32 v192, 64, v154
	v_add_u32_e32 v197, 0x60, v154
	v_add_u32_e32 v198, 0x80, v154
	v_add_u32_e32 v199, 0xa0, v154
	v_add_u32_e32 v195, 0x120, v154
	v_lshlrev_b32_e32 v204, 2, v155
	v_lshlrev_b32_e32 v205, 2, v172
	v_lshlrev_b32_e32 v206, 2, v173
	v_lshlrev_b32_e32 v207, 2, v182
	v_lshlrev_b32_e32 v208, 2, v8
	v_lshlrev_b32_e32 v209, 2, v166
	v_add_u32_e32 v210, 0x140, v154
	v_add_u32_e32 v212, 0x160, v154
	s_mov_b32 s79, s76
	s_bfe_u32 s72, s76, 0x30006
	v_add_u32_e32 v214, 0xfffffc00, v213
	v_add_u32_e32 v216, 0xfffffc00, v215
	v_add_u32_e32 v218, 0xfffffc00, v217
	v_add_u32_e32 v220, 0xfffffc00, v219
	v_lshlrev_b32_e32 v221, 4, v8
	v_add_u32_e32 v222, 0xfffffe00, v213
	v_add_u32_e32 v223, 0xfffffe00, v215
	v_add_u32_e32 v224, 0xfffffe00, v217
	v_add_u32_e32 v225, 0xfffffe00, v219
	v_or_b32_e32 v226, 0xfffffe00, v167
	v_or_b32_e32 v227, 0xffffff00, v167
	v_or_b32_e32 v228, 0x100, v167
	v_lshlrev_b32_e32 v229, 4, v11
	v_lshlrev_b32_e32 v230, 4, v12
	v_lshlrev_b32_e32 v231, 4, v13
	v_lshlrev_b32_e32 v232, 4, v14
	v_or_b32_e32 v233, 0x200, v167
	v_or_b32_e32 v234, 0x300, v167
	v_lshlrev_b32_e32 v235, 4, v15
	v_lshlrev_b32_e32 v236, 4, v16
	v_lshlrev_b32_e32 v237, 4, v17
	v_lshlrev_b32_e32 v238, 4, v18
	v_or_b32_e32 v239, 0x400, v167
	v_or_b32_e32 v240, 0x500, v167
	v_cmp_eq_u32_e64 s[18:19], 0, v0
	v_cmp_eq_u32_e64 s[20:21], -16, v0
	v_lshlrev_b64 v[158:159], 1, v[2:3]
	s_mov_b32 s58, 0x3e38aa3b
	v_lshlrev_b32_e32 v152, 1, v4
	v_add_u32_e32 v241, v7, v1
	v_add_u32_e32 v242, v7, v5
	v_add_u32_e32 v243, v7, v6
	v_add_u32_e32 v244, v7, v9
	s_mov_b32 s73, 0xf149f2ca
	v_mov_b32_e32 v245, 0x178
	v_mov_b32_e32 v246, 0xff800000
	v_mov_b32_e32 v247, 0xbe
	v_mov_b32_e32 v248, 0x8f
.LBB0_246:
	s_lshl_b32 s1, s71, 2
	s_and_b32 s22, s1, 0xffffff00
	s_lshr_b32 s0, s71, 3
	s_bfe_u32 s56, s71, 0x30003
	s_or_b32 s24, s22, s72
	s_cmp_lt_i32 s24, 0x8000
	s_movk_i32 s22, 0xfff
	s_cselect_b32 s75, s22, 0x1fff
	s_bfe_u32 s0, s0, 0x10002
	s_andn2_b32 s74, s1, s75
	s_mul_i32 s0, s0, 0x1800000
	s_add_u32 s0, s96, s0
	s_addc_u32 s1, s97, 0
	s_lshl_b32 s22, s71, 4
	s_and_b32 s22, s22, 0x180
	s_add_u32 s22, s0, s22
	v_or_b32_e32 v162, s24, v167
	s_addc_u32 s23, s1, 0
	v_ashrrev_i32_e32 v163, 31, v162
	v_lshl_add_u64 v[12:13], s[22:23], 0, v[158:159]
	v_lshlrev_b64 v[0:1], 9, v[162:163]
	v_lshl_add_u64 v[8:9], v[12:13], 0, v[0:1]
	global_load_dwordx4 v[0:3], v[8:9], off
	v_or_b32_e32 v160, 8, v162
	v_ashrrev_i32_e32 v161, 31, v160
	s_add_u32 s68, s22, 0x3000000
	s_addc_u32 s69, s23, 0
	s_lshl_b32 s98, s74, 9
	s_add_u32 s100, s68, s98
	s_addc_u32 s101, s69, 0
	s_add_u32 s98, s100, 0x3000000
	s_addc_u32 s99, s101, 0
	s_sub_i32 s76, s24, s74
	s_sub_i32 s0, s76, 64
	s_waitcnt vmcnt(7)
	v_add_u32_e32 v20, s0, v172
	v_min_i32_e32 v21, s75, v20
	s_waitcnt vmcnt(6)
	v_add_u32_e32 v24, s0, v173
	v_min_i32_e32 v25, s75, v24
	s_waitcnt vmcnt(5)
	v_add_u32_e32 v28, s0, v182
	v_min_i32_e32 v29, s75, v28
	s_waitcnt vmcnt(2)
	v_add_u32_e32 v40, s0, v166
	v_min_i32_e32 v32, s75, v40
	v_add_u32_e32 v41, 16, v40
	s_movk_i32 s1, 0xffef
	v_min_i32_e32 v41, s75, v41
	v_or_b32_e32 v128, 32, v166
	v_add_u32_e32 v56, s0, v128
	v_add_u32_e32 v149, s76, v155
	v_add_u32_e32 v150, s76, v172
	v_add_u32_e32 v151, s76, v173
	v_add_u32_e32 v252, s76, v182
	v_or_b32_e32 v251, s76, v167
	v_subrev_u32_e32 v250, s76, v251
	v_or_b32_e32 v144, 8, v251
	v_subrev_u32_e32 v249, s76, v144
	v_add_u32_e32 v196, 0x60, v155
	v_add_u32_e32 v168, 0x60, v172
	v_add_u32_e32 v193, 0x60, v173
	v_add_u32_e32 v194, 0x60, v182
	v_add_u32_e32 v186, s76, v206
	s_waitcnt vmcnt(0)
	v_lshlrev_b32_e32 v4, 16, v0
	v_and_b32_e32 v5, 0xffff0000, v0
	v_lshlrev_b32_e32 v0, 16, v1
	v_and_b32_e32 v1, 0xffff0000, v1
	v_pk_mul_f32 v[4:5], v[4:5], s[58:59] op_sel_hi:[1,0]
	v_pk_mul_f32 v[0:1], v[0:1], s[58:59] op_sel_hi:[1,0]
	v_cvt_pk_bf16_f32 v4, v4, v5
	v_cvt_pk_bf16_f32 v5, v0, v1
	v_lshlrev_b32_e32 v0, 16, v2
	v_and_b32_e32 v1, 0xffff0000, v2
	v_pk_mul_f32 v[0:1], v[0:1], s[58:59] op_sel_hi:[1,0]
	s_nop 0
	v_cvt_pk_bf16_f32 v6, v0, v1
	v_lshlrev_b32_e32 v0, 16, v3
	v_and_b32_e32 v1, 0xffff0000, v3
	v_pk_mul_f32 v[0:1], v[0:1], s[58:59] op_sel_hi:[1,0]
	s_nop 0
	v_cvt_pk_bf16_f32 v7, v0, v1
	global_load_dwordx4 v[0:3], v[8:9], off offset:64
	s_waitcnt vmcnt(0)
	v_lshlrev_b32_e32 v8, 16, v0
	v_and_b32_e32 v9, 0xffff0000, v0
	v_lshlrev_b32_e32 v0, 16, v1
	v_and_b32_e32 v1, 0xffff0000, v1
	v_pk_mul_f32 v[8:9], v[8:9], s[58:59] op_sel_hi:[1,0]
	v_pk_mul_f32 v[0:1], v[0:1], s[58:59] op_sel_hi:[1,0]
	v_cvt_pk_bf16_f32 v8, v8, v9
	v_cvt_pk_bf16_f32 v9, v0, v1
	v_lshlrev_b32_e32 v0, 16, v2
	v_and_b32_e32 v1, 0xffff0000, v2
	v_pk_mul_f32 v[0:1], v[0:1], s[58:59] op_sel_hi:[1,0]
	s_nop 0
	v_cvt_pk_bf16_f32 v10, v0, v1
	v_lshlrev_b32_e32 v0, 16, v3
	v_and_b32_e32 v1, 0xffff0000, v3
	v_pk_mul_f32 v[0:1], v[0:1], s[58:59] op_sel_hi:[1,0]
	s_nop 0
	v_cvt_pk_bf16_f32 v11, v0, v1
	v_lshlrev_b64 v[0:1], 9, v[160:161]
	v_lshl_add_u64 v[16:17], v[12:13], 0, v[0:1]
	global_load_dwordx4 v[0:3], v[16:17], off
	s_waitcnt vmcnt(0)
	v_lshlrev_b32_e32 v12, 16, v0
	v_and_b32_e32 v13, 0xffff0000, v0
	v_lshlrev_b32_e32 v0, 16, v1
	v_and_b32_e32 v1, 0xffff0000, v1
	v_pk_mul_f32 v[12:13], v[12:13], s[58:59] op_sel_hi:[1,0]
	v_pk_mul_f32 v[0:1], v[0:1], s[58:59] op_sel_hi:[1,0]
	v_cvt_pk_bf16_f32 v12, v12, v13
	v_cvt_pk_bf16_f32 v13, v0, v1
	v_lshlrev_b32_e32 v0, 16, v2
	v_and_b32_e32 v1, 0xffff0000, v2
	v_pk_mul_f32 v[0:1], v[0:1], s[58:59] op_sel_hi:[1,0]
	s_nop 0
	v_cvt_pk_bf16_f32 v14, v0, v1
	v_lshlrev_b32_e32 v0, 16, v3
	v_and_b32_e32 v1, 0xffff0000, v3
	v_pk_mul_f32 v[0:1], v[0:1], s[58:59] op_sel_hi:[1,0]
	s_nop 0
	v_cvt_pk_bf16_f32 v15, v0, v1
	global_load_dwordx4 v[0:3], v[16:17], off offset:64
	s_waitcnt vmcnt(0)
	v_lshlrev_b32_e32 v16, 16, v0
	v_and_b32_e32 v17, 0xffff0000, v0
	v_pk_mul_f32 v[16:17], v[16:17], s[58:59] op_sel_hi:[1,0]
	s_nop 0
	v_cvt_pk_bf16_f32 v0, v16, v17
	v_lshlrev_b32_e32 v16, 16, v1
	v_and_b32_e32 v17, 0xffff0000, v1
	v_pk_mul_f32 v[16:17], v[16:17], s[58:59] op_sel_hi:[1,0]
	s_nop 0
	v_cvt_pk_bf16_f32 v1, v16, v17
	v_lshlrev_b32_e32 v16, 16, v2
	v_and_b32_e32 v17, 0xffff0000, v2
	v_pk_mul_f32 v[16:17], v[16:17], s[58:59] op_sel_hi:[1,0]
	s_nop 0
	v_cvt_pk_bf16_f32 v2, v16, v17
	v_lshlrev_b32_e32 v16, 16, v3
	v_and_b32_e32 v17, 0xffff0000, v3
	v_pk_mul_f32 v[16:17], v[16:17], s[58:59] op_sel_hi:[1,0]
	s_nop 0
	v_cvt_pk_bf16_f32 v3, v16, v17
	v_lshl_add_u64 v[16:17], s[22:23], 0, v[152:153]
	s_mov_b64 s[22:23], 0x6000000
	v_lshl_add_u64 v[164:165], v[16:17], 0, s[22:23]
	v_add_u32_e32 v16, s0, v155
	s_sub_i32 s22, 0x80, s76
	s_nop 0
	v_med3_i32 v16, v16, 0, s75
	v_cmp_lt_i32_e32 vcc, -1, v20
	s_nop 1
	v_cndmask_b32_e32 v20, 0, v21, vcc
	v_cmp_lt_i32_e32 vcc, -1, v24
	s_nop 1
	v_cndmask_b32_e32 v24, 0, v25, vcc
	v_cmp_lt_i32_e32 vcc, -1, v28
	s_nop 1
	v_cndmask_b32_e32 v28, 0, v29, vcc
	v_lshl_add_u32 v16, v16, 9, v152
	global_load_dwordx4 v[16:19], v16, s[98:99]
	v_lshl_add_u32 v20, v20, 9, v152
	v_cmp_lt_i32_e32 vcc, -1, v40
	global_load_dwordx4 v[20:23], v20, s[98:99]
	v_lshl_add_u32 v24, v24, 9, v152
	v_cndmask_b32_e32 v32, 0, v32, vcc
	v_cmp_lt_i32_e32 vcc, s1, v40
	global_load_dwordx4 v[24:27], v24, s[98:99]
	v_lshl_add_u32 v28, v28, 9, v152
	v_cndmask_b32_e32 v40, 0, v41, vcc
	global_load_dwordx4 v[28:31], v28, s[98:99]
	v_lshl_add_u32 v36, v32, 9, v158
	v_lshl_add_u32 v40, v40, 9, v158
	s_sub_i32 s1, s76, 32
	global_load_dwordx4 v[32:35], v36, s[100:101]
	s_nop 0
	global_load_dwordx4 v[36:39], v36, s[100:101] offset:64
	s_nop 0
	global_load_dwordx4 v[48:51], v40, s[100:101]
	global_load_dwordx4 v[52:55], v40, s[100:101] offset:64
	v_add_u32_e32 v40, s1, v155
	v_med3_i32 v40, v40, 0, s75
	v_lshl_add_u32 v40, v40, 9, v152
	global_load_dwordx4 v[76:79], v40, s[98:99]
	v_add_u32_e32 v40, s1, v172
	v_med3_i32 v40, v40, 0, s75
	v_lshl_add_u32 v40, v40, 9, v152
	global_load_dwordx4 v[84:87], v40, s[98:99]
	v_add_u32_e32 v40, s1, v173
	v_med3_i32 v40, v40, 0, s75
	v_lshl_add_u32 v40, v40, 9, v152
	global_load_dwordx4 v[88:91], v40, s[98:99]
	v_add_u32_e32 v40, s1, v182
	s_min_i32 s1, s0, 0
	s_sub_i32 s1, 0, s1
	v_med3_i32 v40, v40, 0, s75
	v_lshl_add_u32 v40, v40, 9, v152
	global_load_dwordx4 v[92:95], v40, s[98:99]
	v_min_i32_e32 v40, s75, v56
	v_cmp_lt_i32_e32 vcc, -1, v56
	v_add_u32_e32 v56, 16, v56
	s_nop 0
	v_cndmask_b32_e32 v40, 0, v40, vcc
	v_med3_i32 v56, v56, 0, s75
	v_lshl_add_u32 v44, v40, 9, v158
	v_lshl_add_u32 v60, v56, 9, v158
	global_load_dwordx4 v[40:43], v44, s[100:101]
	s_nop 0
	global_load_dwordx4 v[44:47], v44, s[100:101] offset:64
	s_nop 0
	global_load_dwordx4 v[56:59], v60, s[100:101]
	s_nop 0
	global_load_dwordx4 v[60:63], v60, s[100:101] offset:64
	s_waitcnt vmcnt(15)
	ds_write_b128 v241, v[16:19]
	s_waitcnt vmcnt(14)
	ds_write_b128 v242, v[20:23]
	s_waitcnt vmcnt(13)
	ds_write_b128 v243, v[24:27]
	s_waitcnt vmcnt(12)
	ds_write_b128 v244, v[28:31]
	v_or_b32_e32 v24, 16, v166
	v_add_u32_e32 v24, s76, v24
	v_med3_i32 v16, v149, 0, s75
	v_lshl_add_u32 v16, v16, 9, v152
	global_load_dwordx4 v[64:67], v16, s[98:99]
	s_sub_i32 s0, s75, s0
	v_med3_i32 v16, v150, 0, s75
	v_lshl_add_u32 v16, v16, 9, v152
	global_load_dwordx4 v[68:71], v16, s[98:99]
	v_max_i32_e32 v147, s1, v250
	v_max_i32_e32 v148, s1, v249
	v_med3_i32 v16, v151, 0, s75
	v_lshl_add_u32 v16, v16, 9, v152
	global_load_dwordx4 v[72:75], v16, s[98:99]
	v_med3_i32 v16, v252, 0, s75
	v_lshl_add_u32 v16, v16, 9, v152
	global_load_dwordx4 v[80:83], v16, s[98:99]
	v_add_u32_e32 v16, s76, v166
	v_med3_i32 v16, v16, 0, s75
	v_med3_i32 v24, v24, 0, s75
	v_lshl_add_u32 v20, v16, 9, v158
	v_lshl_add_u32 v28, v24, 9, v158
	global_load_dwordx4 v[16:19], v20, s[100:101]
	s_nop 0
	global_load_dwordx4 v[20:23], v20, s[100:101] offset:64
	s_nop 0
	global_load_dwordx4 v[24:27], v28, s[100:101]
	s_nop 0
	global_load_dwordx4 v[28:31], v28, s[100:101] offset:64
	ds_read_b64_tr_b16 v[98:99], v169 offset:2304
	ds_read_b64_tr_b16 v[96:97], v169
	ds_read_b64_tr_b16 v[100:101], v169 offset:32
	ds_read_b64_tr_b16 v[102:103], v169 offset:2336
	ds_read_b64_tr_b16 v[116:117], v169 offset:64
	ds_read_b64_tr_b16 v[118:119], v169 offset:2368
	ds_read_b64_tr_b16 v[134:135], v169 offset:96
	ds_read_b64_tr_b16 v[136:137], v169 offset:2400
	s_waitcnt vmcnt(15)
	ds_write_b128 v241, v[76:79] offset:4608
	s_waitcnt vmcnt(14)
	ds_write_b128 v242, v[84:87] offset:4608
	s_waitcnt vmcnt(13)
	ds_write_b128 v243, v[88:91] offset:4608
	s_waitcnt vmcnt(12)
	ds_write_b128 v244, v[92:95] offset:4608
	v_mfma_f32_16x16x32_bf16 v[76:79], v[32:35], v[4:7], 0
	v_mfma_f32_16x16x32_bf16 v[32:35], v[32:35], v[12:15], 0
	v_mfma_f32_16x16x32_bf16 v[76:79], v[36:39], v[8:11], v[76:79]
	v_mfma_f32_16x16x32_bf16 v[84:87], v[48:51], v[4:7], 0
	v_mfma_f32_16x16x32_bf16 v[32:35], v[36:39], v[0:3], v[32:35]
	v_mfma_f32_16x16x32_bf16 v[36:39], v[48:51], v[12:15], 0
	v_add_u32_e32 v48, s22, v251
	v_min3_i32 v48, v48, s0, v245
	v_sub_u32_e32 v49, v154, v147
	v_sub_u32_e32 v146, v48, v147
	v_add_u32_e32 v48, s22, v144
	v_min3_i32 v48, v48, s0, v245
	v_add_u32_e32 v51, 1, v49
	v_sub_u32_e32 v145, v48, v148
	v_cmp_gt_u32_e64 s[0:1], v51, v146
	v_cmp_gt_u32_e32 vcc, v49, v146
	s_nop 0
	v_cndmask_b32_e64 v77, v77, v246, s[0:1]
	s_nop 0
	v_cndmask_b32_e32 v76, v76, v246, vcc
	v_max_f32_e32 v48, 0xf149f2ca, v76
	v_mfma_f32_16x16x32_bf16 v[84:87], v[52:55], v[8:11], v[84:87]
	v_max_f32_e32 v48, v48, v77
	v_add_u32_e32 v51, 2, v49
	v_cmp_gt_u32_e64 s[22:23], v51, v146
	v_mfma_f32_16x16x32_bf16 v[36:39], v[52:55], v[0:3], v[36:39]
	v_add_u32_e32 v52, 3, v49
	v_cmp_gt_u32_e64 s[24:25], v52, v146
	v_cndmask_b32_e64 v78, v78, v246, s[22:23]
	v_sub_u32_e32 v50, v154, v148
	v_cndmask_b32_e64 v79, v79, v246, s[24:25]
	v_max3_f32 v48, v48, v78, v79
	v_add_u32_e32 v51, 16, v49
	v_add_u32_e32 v52, 17, v49
	v_cmp_gt_u32_e64 s[26:27], v51, v146
	v_cmp_gt_u32_e64 s[28:29], v52, v146
	v_cmp_gt_u32_e64 s[38:39], v50, v145
	v_cndmask_b32_e64 v84, v84, v246, s[26:27]
	v_cndmask_b32_e64 v85, v85, v246, s[28:29]
	v_max3_f32 v48, v48, v84, v85
	v_add_u32_e32 v51, 18, v49
	v_add_u32_e32 v49, 19, v49
	v_cmp_gt_u32_e64 s[30:31], v51, v146
	v_cmp_gt_u32_e64 s[34:35], v49, v146
	v_add_u32_e32 v52, 3, v50
	v_cndmask_b32_e64 v86, v86, v246, s[30:31]
	v_cndmask_b32_e64 v87, v87, v246, s[34:35]
	v_max3_f32 v48, v48, v86, v87
	v_add_u32_e32 v51, 1, v50
	v_cmp_gt_u32_e64 s[40:41], v51, v145
	v_cndmask_b32_e64 v32, v32, v246, s[38:39]
	v_max_f32_e32 v49, 0xf149f2ca, v32
	v_cndmask_b32_e64 v33, v33, v246, s[40:41]
	v_max_f32_e32 v49, v49, v33
	v_add_u32_e32 v51, 2, v50
	v_cmp_gt_u32_e64 s[42:43], v51, v145
	v_cmp_gt_u32_e64 s[44:45], v52, v145
	s_nop 0
	v_cndmask_b32_e64 v34, v34, v246, s[42:43]
	v_cndmask_b32_e64 v35, v35, v246, s[44:45]
	v_max3_f32 v49, v49, v34, v35
	v_add_u32_e32 v51, 16, v50
	v_add_u32_e32 v52, 17, v50
	v_cmp_gt_u32_e64 s[46:47], v51, v145
	v_cmp_gt_u32_e64 s[48:49], v52, v145
	s_nop 0
	v_cndmask_b32_e64 v36, v36, v246, s[46:47]
	v_cndmask_b32_e64 v37, v37, v246, s[48:49]
	v_max3_f32 v49, v49, v36, v37
	v_add_u32_e32 v51, 18, v50
	v_add_u32_e32 v50, 19, v50
	v_cmp_gt_u32_e64 s[50:51], v51, v145
	v_cmp_gt_u32_e64 s[52:53], v50, v145
	s_nop 0
	v_cndmask_b32_e64 v38, v38, v246, s[50:51]
	v_cndmask_b32_e64 v39, v39, v246, s[52:53]
	v_max3_f32 v49, v49, v38, v39
	v_mov_b32_e32 v50, v48
	v_mov_b32_e32 v51, v48
	s_nop 1
	v_permlane32_swap_b32_e32 v50, v51
	v_max3_f32 v48, v48, v50, v51
	v_mov_b32_e32 v50, v49
	v_mov_b32_e32 v51, v49
	s_nop 1
	v_permlane32_swap_b32_e32 v50, v51
	v_max3_f32 v49, v49, v50, v51
	v_mov_b32_e32 v50, v48
	v_mov_b32_e32 v51, v48
	s_nop 1
	v_permlane16_swap_b32_e32 v50, v51
	v_max_f32_e32 v48, v48, v50
	v_mov_b32_e32 v50, v49
	v_mov_b32_e32 v88, v49
	s_nop 1
	v_permlane16_swap_b32_e32 v50, v88
	v_max3_f32 v129, v48, v51, s73
	v_sub_f32_e32 v48, 0xf149f2ca, v129
	v_max_f32_e32 v49, v49, v50
	v_exp_f32_e32 v50, v48
	v_sub_f32_e32 v48, v76, v129
	v_exp_f32_e32 v48, v48
	v_sub_f32_e32 v52, v77, v129
	v_max3_f32 v131, v49, v88, s73
	v_exp_f32_e32 v52, v52
	v_sub_f32_e32 v36, v36, v131
	v_sub_f32_e32 v53, v78, v129
	v_exp_f32_e32 v36, v36
	v_exp_f32_e32 v53, v53
	v_sub_f32_e32 v54, v79, v129
	v_cndmask_b32_e64 v51, v48, 0, vcc
	v_exp_f32_e32 v54, v54
	v_sub_f32_e32 v55, v84, v129
	v_add_f32_e32 v48, 0, v51
	v_exp_f32_e32 v55, v55
	v_sub_f32_e32 v76, v85, v129
	v_add_f32_e32 v48, v52, v48
	v_exp_f32_e32 v76, v76
	v_sub_f32_e32 v77, v86, v129
	v_cvt_pk_bf16_f32 v52, v51, v52
	v_cndmask_b32_e64 v51, v36, 0, s[46:47]
	v_sub_f32_e32 v36, v37, v131
	v_exp_f32_e32 v77, v77
	v_sub_f32_e32 v78, v87, v129
	v_exp_f32_e32 v36, v36
	v_add_f32_e32 v48, v53, v48
	v_exp_f32_e32 v78, v78
	v_add_f32_e32 v48, v54, v48
	v_sub_f32_e32 v32, v32, v131
	v_add_f32_e32 v48, v55, v48
	v_exp_f32_e32 v32, v32
	v_sub_f32_e32 v33, v33, v131
	v_add_f32_e32 v48, v76, v48
	v_cvt_pk_bf16_f32 v53, v53, v54
	v_cvt_pk_bf16_f32 v54, v55, v76
	v_exp_f32_e32 v33, v33
	v_sub_f32_e32 v34, v34, v131
	v_cndmask_b32_e64 v76, v36, 0, s[48:49]
	v_sub_f32_e32 v36, v38, v131
	v_add_f32_e32 v48, v77, v48
	v_exp_f32_e32 v34, v34
	v_sub_f32_e32 v35, v35, v131
	v_exp_f32_e32 v36, v36
	v_add_f32_e32 v130, v78, v48
	v_exp_f32_e32 v35, v35
	v_mul_f32_e32 v48, 0, v50
	v_fmac_f32_e32 v130, 0, v50
	v_cndmask_b32_e64 v50, v32, 0, s[38:39]
	v_add_f32_e32 v32, 0, v50
	v_cvt_pk_bf16_f32 v55, v77, v78
	v_add_f32_e32 v32, v33, v32
	v_cndmask_b32_e64 v77, v36, 0, s[50:51]
	v_sub_f32_e32 v36, v39, v131
	v_sub_f32_e32 v49, 0xf149f2ca, v131
	v_add_f32_e32 v32, v34, v32
	v_exp_f32_e32 v36, v36
	v_exp_f32_e32 v49, v49
	v_add_f32_e32 v32, v35, v32
	v_add_f32_e32 v32, v51, v32
	v_add_f32_e32 v32, v76, v32
	v_add_f32_e32 v32, v77, v32
	v_cndmask_b32_e64 v39, v36, 0, s[52:53]
	v_add_f32_e32 v132, v39, v32
	v_mul_f32_e32 v32, 0, v49
	v_fmac_f32_e32 v132, 0, v49
	v_cvt_pk_bf16_f32 v36, v50, v33
	v_cvt_pk_bf16_f32 v37, v34, v35
	v_cvt_pk_bf16_f32 v38, v51, v76
	v_cvt_pk_bf16_f32 v39, v77, v39
	v_mov_b32_e32 v49, v48
	v_mov_b32_e32 v50, v48
	v_mov_b32_e32 v51, v48
	v_mov_b32_e32 v33, v32
	v_mov_b32_e32 v34, v32
	v_mov_b32_e32 v35, v32
	s_waitcnt lgkmcnt(6)
	v_mfma_f32_16x16x32_bf16 v[112:115], v[116:119], v[52:55], v[48:51]
	v_mfma_f32_16x16x32_bf16 v[124:127], v[96:99], v[36:39], v[32:35]
	v_mfma_f32_16x16x32_bf16 v[108:111], v[100:103], v[36:39], v[32:35]
	v_mfma_f32_16x16x32_bf16 v[116:119], v[116:119], v[36:39], v[32:35]
	s_waitcnt lgkmcnt(4)
	v_mfma_f32_16x16x32_bf16 v[88:91], v[134:137], v[36:39], v[32:35]
	s_nop 2
	v_add_u32_e32 v32, 32, v155
	v_add_u32_e32 v32, s76, v32
	v_mfma_f32_16x16x32_bf16 v[120:123], v[96:99], v[52:55], v[48:51]
	s_nop 0
	v_med3_i32 v32, v32, 0, s75
	v_lshl_add_u32 v32, v32, 9, v152
	global_load_dwordx4 v[76:79], v32, s[98:99]
	v_add_u32_e32 v32, 32, v172
	v_add_u32_e32 v32, s76, v32
	v_mfma_f32_16x16x32_bf16 v[104:107], v[100:103], v[52:55], v[48:51]
	s_nop 0
	v_med3_i32 v32, v32, 0, s75
	v_lshl_add_u32 v32, v32, 9, v152
	global_load_dwordx4 v[84:87], v32, s[98:99]
	v_add_u32_e32 v32, 32, v173
	v_add_u32_e32 v32, s76, v32
	v_mfma_f32_16x16x32_bf16 v[96:99], v[134:137], v[52:55], v[48:51]
	s_nop 0
	v_med3_i32 v32, v32, 0, s75
	v_lshl_add_u32 v32, v32, 9, v152
	global_load_dwordx4 v[92:95], v32, s[98:99]
	v_add_u32_e32 v32, 32, v182
	v_add_u32_e32 v32, s76, v32
	v_or_b32_e32 v48, 48, v166
	v_add_u32_e32 v48, s76, v48
	v_med3_i32 v32, v32, 0, s75
	v_lshl_add_u32 v32, v32, 9, v152
	global_load_dwordx4 v[100:103], v32, s[98:99]
	v_add_u32_e32 v32, s76, v128
	s_nop 0
	v_med3_i32 v32, v32, 0, s75
	v_med3_i32 v48, v48, 0, s75
	v_lshl_add_u32 v36, v32, 9, v158
	v_lshl_add_u32 v52, v48, 9, v158
	global_load_dwordx4 v[32:35], v36, s[100:101]
	s_nop 0
	global_load_dwordx4 v[36:39], v36, s[100:101] offset:64
	s_nop 0
	global_load_dwordx4 v[48:51], v52, s[100:101]
	s_nop 0
	global_load_dwordx4 v[52:55], v52, s[100:101] offset:64
	ds_read_b64_tr_b16 v[136:137], v169 offset:6912
	ds_read_b64_tr_b16 v[134:135], v169 offset:4608
	ds_read_b64_tr_b16 v[138:139], v169 offset:4640
	ds_read_b64_tr_b16 v[140:141], v169 offset:6944
	ds_read_b64_tr_b16 v[176:177], v169 offset:4672
	ds_read_b64_tr_b16 v[178:179], v169 offset:6976
	ds_read_b64_tr_b16 v[188:189], v169 offset:4704
	ds_read_b64_tr_b16 v[190:191], v169 offset:7008
	s_waitcnt vmcnt(15)
	ds_write_b128 v241, v[64:67]
	s_waitcnt vmcnt(14)
	ds_write_b128 v242, v[68:71]
	s_waitcnt vmcnt(13)
	ds_write_b128 v243, v[72:75]
	s_waitcnt vmcnt(12)
	ds_write_b128 v244, v[80:83]
	v_mfma_f32_16x16x32_bf16 v[64:67], v[40:43], v[4:7], 0
	v_mfma_f32_16x16x32_bf16 v[40:43], v[40:43], v[12:15], 0
	v_mfma_f32_16x16x32_bf16 v[64:67], v[44:47], v[8:11], v[64:67]
	v_mfma_f32_16x16x32_bf16 v[68:71], v[56:59], v[4:7], 0
	v_mfma_f32_16x16x32_bf16 v[40:43], v[44:47], v[0:3], v[40:43]
	v_mfma_f32_16x16x32_bf16 v[44:47], v[56:59], v[12:15], 0
	v_sub_u32_e32 v56, v187, v147
	v_add_u32_e32 v59, 1, v56
	s_nop 2
	v_cmp_gt_u32_e64 s[0:1], v59, v146
	v_cmp_gt_u32_e32 vcc, v56, v146
	s_nop 0
	v_cndmask_b32_e64 v65, v65, v246, s[0:1]
	s_nop 0
	v_cndmask_b32_e32 v64, v64, v246, vcc
	v_max_f32_e32 v58, 0xf149f2ca, v64
	v_mfma_f32_16x16x32_bf16 v[68:71], v[60:63], v[8:11], v[68:71]
	v_max_f32_e32 v58, v58, v65
	v_add_u32_e32 v59, 2, v56
	v_cmp_gt_u32_e64 s[22:23], v59, v146
	v_mfma_f32_16x16x32_bf16 v[44:47], v[60:63], v[0:3], v[44:47]
	v_add_u32_e32 v60, 3, v56
	v_cmp_gt_u32_e64 s[24:25], v60, v146
	v_cndmask_b32_e64 v66, v66, v246, s[22:23]
	v_sub_u32_e32 v57, v187, v148
	v_cndmask_b32_e64 v67, v67, v246, s[24:25]
	v_max3_f32 v58, v58, v66, v67
	v_add_u32_e32 v59, 16, v56
	v_add_u32_e32 v60, 17, v56
	v_cmp_gt_u32_e64 s[26:27], v59, v146
	v_cmp_gt_u32_e64 s[28:29], v60, v146
	v_cmp_gt_u32_e64 s[38:39], v57, v145
	v_cndmask_b32_e64 v68, v68, v246, s[26:27]
	v_cndmask_b32_e64 v69, v69, v246, s[28:29]
	v_max3_f32 v58, v58, v68, v69
	v_add_u32_e32 v59, 18, v56
	v_add_u32_e32 v56, 19, v56
	v_cmp_gt_u32_e64 s[30:31], v59, v146
	v_cmp_gt_u32_e64 s[34:35], v56, v146
	v_add_u32_e32 v60, 3, v57
	v_cndmask_b32_e64 v70, v70, v246, s[30:31]
	v_cndmask_b32_e64 v71, v71, v246, s[34:35]
	v_max3_f32 v56, v58, v70, v71
	v_add_u32_e32 v59, 1, v57
	v_cmp_gt_u32_e64 s[40:41], v59, v145
	v_cndmask_b32_e64 v40, v40, v246, s[38:39]
	v_max_f32_e32 v58, 0xf149f2ca, v40
	v_cndmask_b32_e64 v41, v41, v246, s[40:41]
	v_max_f32_e32 v58, v58, v41
	v_add_u32_e32 v59, 2, v57
	v_cmp_gt_u32_e64 s[42:43], v59, v145
	v_cmp_gt_u32_e64 s[44:45], v60, v145
	s_nop 0
	v_cndmask_b32_e64 v42, v42, v246, s[42:43]
	v_cndmask_b32_e64 v43, v43, v246, s[44:45]
	v_max3_f32 v58, v58, v42, v43
	v_add_u32_e32 v59, 16, v57
	v_add_u32_e32 v60, 17, v57
	v_cmp_gt_u32_e64 s[46:47], v59, v145
	v_cmp_gt_u32_e64 s[48:49], v60, v145
	s_nop 0
	v_cndmask_b32_e64 v44, v44, v246, s[46:47]
	v_cndmask_b32_e64 v45, v45, v246, s[48:49]
	v_max3_f32 v58, v58, v44, v45
	v_add_u32_e32 v59, 18, v57
	v_add_u32_e32 v57, 19, v57
	v_cmp_gt_u32_e64 s[50:51], v59, v145
	v_cmp_gt_u32_e64 s[52:53], v57, v145
	s_nop 0
	v_cndmask_b32_e64 v46, v46, v246, s[50:51]
	v_cndmask_b32_e64 v47, v47, v246, s[52:53]
	v_max3_f32 v57, v58, v46, v47
	v_mov_b32_e32 v58, v56
	v_mov_b32_e32 v59, v56
	s_nop 1
	v_permlane32_swap_b32_e32 v58, v59
	v_max3_f32 v56, v56, v58, v59
	v_mov_b32_e32 v58, v57
	v_mov_b32_e32 v59, v57
	s_nop 1
	v_permlane32_swap_b32_e32 v58, v59
	v_max3_f32 v57, v57, v58, v59
	v_mov_b32_e32 v58, v56
	v_mov_b32_e32 v59, v56
	s_nop 1
	v_permlane16_swap_b32_e32 v58, v59
	v_max_f32_e32 v56, v56, v58
	v_mov_b32_e32 v58, v57
	v_mov_b32_e32 v61, v57
	v_max3_f32 v128, v129, v56, v59
	s_nop 0
	v_permlane16_swap_b32_e32 v58, v61
	v_sub_f32_e32 v56, v129, v128
	v_exp_f32_e32 v60, v56
	v_sub_f32_e32 v56, v64, v128
	v_max_f32_e32 v62, v57, v58
	v_exp_f32_e32 v56, v56
	v_sub_f32_e32 v58, v65, v128
	v_exp_f32_e32 v58, v58
	v_sub_f32_e32 v59, v66, v128
	v_exp_f32_e32 v59, v59
	v_sub_f32_e32 v63, v67, v128
	v_exp_f32_e32 v63, v63
	v_sub_f32_e32 v64, v68, v128
	v_exp_f32_e32 v64, v64
	v_sub_f32_e32 v65, v69, v128
	v_add_f32_e32 v57, 0, v56
	v_exp_f32_e32 v65, v65
	v_sub_f32_e32 v66, v70, v128
	v_add_f32_e32 v57, v58, v57
	v_exp_f32_e32 v66, v66
	v_sub_f32_e32 v67, v71, v128
	v_add_f32_e32 v57, v59, v57
	v_exp_f32_e32 v67, v67
	v_add_f32_e32 v57, v63, v57
	v_add_f32_e32 v57, v64, v57
	v_add_f32_e32 v57, v65, v57
	v_add_f32_e32 v57, v66, v57
	v_add_f32_e32 v129, v67, v57
	v_fmac_f32_e32 v129, v130, v60
	v_max3_f32 v130, v131, v62, v61
	v_sub_f32_e32 v40, v40, v130
	v_exp_f32_e32 v40, v40
	v_sub_f32_e32 v41, v41, v130
	v_exp_f32_e32 v41, v41
	v_sub_f32_e32 v42, v42, v130
	v_exp_f32_e32 v42, v42
	v_sub_f32_e32 v43, v43, v130
	v_exp_f32_e32 v43, v43
	v_sub_f32_e32 v44, v44, v130
	v_sub_f32_e32 v61, v131, v130
	v_exp_f32_e32 v44, v44
	v_sub_f32_e32 v45, v45, v130
	v_exp_f32_e32 v62, v61
	v_add_f32_e32 v61, 0, v40
	v_exp_f32_e32 v45, v45
	v_sub_f32_e32 v46, v46, v130
	v_add_f32_e32 v61, v41, v61
	v_exp_f32_e32 v46, v46
	v_sub_f32_e32 v47, v47, v130
	v_add_f32_e32 v61, v42, v61
	v_exp_f32_e32 v47, v47
	v_add_f32_e32 v61, v43, v61
	v_add_f32_e32 v61, v44, v61
	v_add_f32_e32 v61, v45, v61
	v_add_f32_e32 v61, v46, v61
	v_cvt_pk_bf16_f32 v56, v56, v58
	v_cvt_pk_bf16_f32 v57, v59, v63
	v_cvt_pk_bf16_f32 v58, v64, v65
	v_cvt_pk_bf16_f32 v59, v66, v67
	v_add_f32_e32 v131, v47, v61
	v_cvt_pk_bf16_f32 v40, v40, v41
	v_cvt_pk_bf16_f32 v41, v42, v43
	v_cvt_pk_bf16_f32 v42, v44, v45
	v_cvt_pk_bf16_f32 v43, v46, v47
	v_pk_mul_f32 v[46:47], v[122:123], v[60:61] op_sel_hi:[1,0]
	v_pk_mul_f32 v[44:45], v[120:121], v[60:61] op_sel_hi:[1,0]
	v_fmac_f32_e32 v131, v132, v62
	s_waitcnt lgkmcnt(10)
	v_mfma_f32_16x16x32_bf16 v[64:67], v[134:137], v[56:59], v[44:47]
	s_nop 2
	v_mul_f32_e64 v46, v126, v62
	v_mul_f32_e64 v47, v127, v62
	v_pk_mul_f32 v[44:45], v[124:125], v[62:63] op_sel_hi:[1,0]
	s_nop 1
	v_mfma_f32_16x16x32_bf16 v[68:71], v[134:137], v[40:43], v[44:47]
	s_nop 2
	v_mul_f32_e64 v46, v106, v60
	v_mul_f32_e64 v47, v107, v60
	v_pk_mul_f32 v[44:45], v[104:105], v[60:61] op_sel_hi:[1,0]
	s_waitcnt lgkmcnt(8)
	s_nop 0
	v_mfma_f32_16x16x32_bf16 v[104:107], v[138:141], v[56:59], v[44:47]
	s_nop 2
	v_mul_f32_e64 v46, v110, v62
	v_mul_f32_e64 v47, v111, v62
	v_pk_mul_f32 v[44:45], v[108:109], v[62:63] op_sel_hi:[1,0]
	s_nop 1
	v_mfma_f32_16x16x32_bf16 v[108:111], v[138:141], v[40:43], v[44:47]
	s_nop 2
	v_mul_f32_e64 v46, v114, v60
	v_mul_f32_e64 v47, v115, v60
	v_pk_mul_f32 v[44:45], v[112:113], v[60:61] op_sel_hi:[1,0]
	s_waitcnt lgkmcnt(6)
	s_nop 0
	v_mfma_f32_16x16x32_bf16 v[112:115], v[176:179], v[56:59], v[44:47]
	s_nop 2
	v_mul_f32_e64 v46, v118, v62
	v_mul_f32_e64 v47, v119, v62
	v_pk_mul_f32 v[44:45], v[116:117], v[62:63] op_sel_hi:[1,0]
	s_nop 1
	v_mfma_f32_16x16x32_bf16 v[116:119], v[176:179], v[40:43], v[44:47]
	s_nop 2
	v_mul_f32_e64 v46, v98, v60
	v_mul_f32_e64 v47, v99, v60
	v_pk_mul_f32 v[44:45], v[96:97], v[60:61] op_sel_hi:[1,0]
	s_waitcnt lgkmcnt(4)
	s_nop 0
	v_mfma_f32_16x16x32_bf16 v[120:123], v[188:191], v[56:59], v[44:47]
	v_or_b32_e32 v56, 0x50, v166
	v_add_u32_e32 v56, s76, v56
	s_nop 0
	v_pk_mul_f32 v[46:47], v[90:91], v[62:63] op_sel_hi:[1,0]
	v_pk_mul_f32 v[44:45], v[88:89], v[62:63] op_sel_hi:[1,0]
	s_nop 1
	v_mfma_f32_16x16x32_bf16 v[124:127], v[188:191], v[40:43], v[44:47]
	v_add_u32_e32 v40, 64, v155
	v_add_u32_e32 v40, s76, v40
	v_med3_i32 v40, v40, 0, s75
	v_lshl_add_u32 v40, v40, 9, v152
	global_load_dwordx4 v[72:75], v40, s[98:99]
	v_add_u32_e32 v40, 64, v172
	v_add_u32_e32 v40, s76, v40
	v_med3_i32 v40, v40, 0, s75
	v_lshl_add_u32 v40, v40, 9, v152
	global_load_dwordx4 v[80:83], v40, s[98:99]
	v_add_u32_e32 v40, 64, v173
	v_add_u32_e32 v40, s76, v40
	v_med3_i32 v40, v40, 0, s75
	v_lshl_add_u32 v40, v40, 9, v152
	global_load_dwordx4 v[88:91], v40, s[98:99]
	v_add_u32_e32 v40, 64, v182
	v_add_u32_e32 v40, s76, v40
	v_med3_i32 v40, v40, 0, s75
	v_lshl_add_u32 v40, v40, 9, v152
	global_load_dwordx4 v[96:99], v40, s[98:99]
	v_or_b32_e32 v40, 64, v166
	v_add_u32_e32 v40, s76, v40
	v_med3_i32 v40, v40, 0, s75
	v_med3_i32 v56, v56, 0, s75
	v_lshl_add_u32 v44, v40, 9, v158
	v_lshl_add_u32 v60, v56, 9, v158
	global_load_dwordx4 v[40:43], v44, s[100:101]
	s_nop 0
	global_load_dwordx4 v[44:47], v44, s[100:101] offset:64
	s_nop 0
	global_load_dwordx4 v[56:59], v60, s[100:101]
	s_nop 0
	global_load_dwordx4 v[60:63], v60, s[100:101] offset:64
	ds_read_b64_tr_b16 v[136:137], v169 offset:2304
	ds_read_b64_tr_b16 v[134:135], v169
	ds_read_b64_tr_b16 v[138:139], v169 offset:32
	ds_read_b64_tr_b16 v[140:141], v169 offset:2336
	ds_read_b64_tr_b16 v[176:177], v169 offset:64
	ds_read_b64_tr_b16 v[178:179], v169 offset:2368
	ds_read_b64_tr_b16 v[188:189], v169 offset:96
	ds_read_b64_tr_b16 v[190:191], v169 offset:2400
	s_waitcnt vmcnt(15)
	ds_write_b128 v241, v[76:79] offset:4608
	s_waitcnt vmcnt(14)
	ds_write_b128 v242, v[84:87] offset:4608
	s_waitcnt vmcnt(13)
	ds_write_b128 v243, v[92:95] offset:4608
	s_waitcnt vmcnt(12)
	ds_write_b128 v244, v[100:103] offset:4608
	v_mfma_f32_16x16x32_bf16 v[76:79], v[16:19], v[4:7], 0
	v_mfma_f32_16x16x32_bf16 v[16:19], v[16:19], v[12:15], 0
	v_mfma_f32_16x16x32_bf16 v[76:79], v[20:23], v[8:11], v[76:79]
	v_mfma_f32_16x16x32_bf16 v[84:87], v[24:27], v[4:7], 0
	v_mfma_f32_16x16x32_bf16 v[16:19], v[20:23], v[0:3], v[16:19]
	v_mfma_f32_16x16x32_bf16 v[20:23], v[24:27], v[12:15], 0
	v_sub_u32_e32 v24, v192, v147
	v_add_u32_e32 v27, 1, v24
	s_nop 2
	v_cmp_gt_u32_e64 s[0:1], v27, v146
	v_cmp_gt_u32_e32 vcc, v24, v146
	s_nop 0
	v_cndmask_b32_e64 v77, v77, v246, s[0:1]
	s_nop 0
	v_cndmask_b32_e32 v76, v76, v246, vcc
	v_max_f32_e32 v26, 0xf149f2ca, v76
	v_mfma_f32_16x16x32_bf16 v[84:87], v[28:31], v[8:11], v[84:87]
	v_max_f32_e32 v26, v26, v77
	v_add_u32_e32 v27, 2, v24
	v_cmp_gt_u32_e64 s[22:23], v27, v146
	v_mfma_f32_16x16x32_bf16 v[20:23], v[28:31], v[0:3], v[20:23]
	v_add_u32_e32 v28, 3, v24
	v_cmp_gt_u32_e64 s[24:25], v28, v146
	v_cndmask_b32_e64 v78, v78, v246, s[22:23]
	v_sub_u32_e32 v25, v192, v148
	v_cndmask_b32_e64 v79, v79, v246, s[24:25]
	v_max3_f32 v26, v26, v78, v79
	v_add_u32_e32 v27, 16, v24
	v_add_u32_e32 v28, 17, v24
	v_cmp_gt_u32_e64 s[26:27], v27, v146
	v_cmp_gt_u32_e64 s[28:29], v28, v146
	v_cmp_gt_u32_e64 s[38:39], v25, v145
	v_cndmask_b32_e64 v84, v84, v246, s[26:27]
	v_cndmask_b32_e64 v85, v85, v246, s[28:29]
	v_max3_f32 v26, v26, v84, v85
	v_add_u32_e32 v27, 18, v24
	v_add_u32_e32 v24, 19, v24
	v_cmp_gt_u32_e64 s[30:31], v27, v146
	v_cmp_gt_u32_e64 s[34:35], v24, v146
	v_add_u32_e32 v28, 3, v25
	v_cndmask_b32_e64 v86, v86, v246, s[30:31]
	v_cndmask_b32_e64 v87, v87, v246, s[34:35]
	v_max3_f32 v24, v26, v86, v87
	v_add_u32_e32 v27, 1, v25
	v_cmp_gt_u32_e64 s[40:41], v27, v145
	v_cndmask_b32_e64 v16, v16, v246, s[38:39]
	v_max_f32_e32 v26, 0xf149f2ca, v16
	v_cndmask_b32_e64 v17, v17, v246, s[40:41]
	v_max_f32_e32 v26, v26, v17
	v_add_u32_e32 v27, 2, v25
	v_cmp_gt_u32_e64 s[42:43], v27, v145
	v_cmp_gt_u32_e64 s[44:45], v28, v145
	s_nop 0
	v_cndmask_b32_e64 v18, v18, v246, s[42:43]
	v_cndmask_b32_e64 v19, v19, v246, s[44:45]
	v_max3_f32 v26, v26, v18, v19
	v_add_u32_e32 v27, 16, v25
	v_add_u32_e32 v28, 17, v25
	v_cmp_gt_u32_e64 s[46:47], v27, v145
	v_cmp_gt_u32_e64 s[48:49], v28, v145
	s_nop 0
	v_cndmask_b32_e64 v20, v20, v246, s[46:47]
	v_cndmask_b32_e64 v21, v21, v246, s[48:49]
	v_max3_f32 v26, v26, v20, v21
	v_add_u32_e32 v27, 18, v25
	v_add_u32_e32 v25, 19, v25
	v_cmp_gt_u32_e64 s[50:51], v27, v145
	v_cmp_gt_u32_e64 s[52:53], v25, v145
	s_nop 0
	v_cndmask_b32_e64 v22, v22, v246, s[50:51]
	v_cndmask_b32_e64 v23, v23, v246, s[52:53]
	v_max3_f32 v25, v26, v22, v23
	v_mov_b32_e32 v26, v24
	v_mov_b32_e32 v27, v24
	s_nop 1
	v_permlane32_swap_b32_e32 v26, v27
	v_max3_f32 v24, v24, v26, v27
	v_mov_b32_e32 v26, v25
	v_mov_b32_e32 v27, v25
	s_nop 1
	v_permlane32_swap_b32_e32 v26, v27
	v_max3_f32 v25, v25, v26, v27
	v_mov_b32_e32 v26, v24
	v_mov_b32_e32 v27, v24
	s_nop 1
	v_permlane16_swap_b32_e32 v26, v27
	v_max_f32_e32 v24, v24, v26
	v_mov_b32_e32 v26, v25
	v_mov_b32_e32 v28, v25
	v_max3_f32 v132, v128, v24, v27
	s_nop 0
	v_permlane16_swap_b32_e32 v26, v28
	v_sub_f32_e32 v24, v128, v132
	v_exp_f32_e32 v92, v24
	v_sub_f32_e32 v24, v76, v132
	v_max_f32_e32 v29, v25, v26
	v_exp_f32_e32 v24, v24
	v_sub_f32_e32 v26, v77, v132
	v_exp_f32_e32 v26, v26
	v_sub_f32_e32 v27, v78, v132
	v_exp_f32_e32 v27, v27
	v_sub_f32_e32 v30, v79, v132
	v_exp_f32_e32 v30, v30
	v_sub_f32_e32 v31, v84, v132
	v_exp_f32_e32 v31, v31
	v_sub_f32_e32 v76, v85, v132
	v_add_f32_e32 v25, 0, v24
	v_exp_f32_e32 v76, v76
	v_sub_f32_e32 v77, v86, v132
	v_add_f32_e32 v25, v26, v25
	v_exp_f32_e32 v77, v77
	v_sub_f32_e32 v78, v87, v132
	v_add_f32_e32 v25, v27, v25
	v_exp_f32_e32 v78, v78
	v_add_f32_e32 v25, v30, v25
	v_add_f32_e32 v25, v31, v25
	v_add_f32_e32 v25, v76, v25
	v_add_f32_e32 v25, v77, v25
	v_add_f32_e32 v128, v78, v25
	v_fmac_f32_e32 v128, v129, v92
	v_max3_f32 v129, v130, v29, v28
	v_sub_f32_e32 v16, v16, v129
	v_exp_f32_e32 v16, v16
	v_sub_f32_e32 v17, v17, v129
	v_exp_f32_e32 v17, v17
	v_sub_f32_e32 v18, v18, v129
	v_exp_f32_e32 v18, v18
	v_sub_f32_e32 v19, v19, v129
	v_exp_f32_e32 v19, v19
	v_sub_f32_e32 v20, v20, v129
	v_sub_f32_e32 v28, v130, v129
	v_exp_f32_e32 v20, v20
	v_sub_f32_e32 v21, v21, v129
	v_cvt_pk_bf16_f32 v24, v24, v26
	v_cvt_pk_bf16_f32 v26, v31, v76
	v_exp_f32_e32 v76, v28
	v_add_f32_e32 v28, 0, v16
	v_exp_f32_e32 v21, v21
	v_sub_f32_e32 v22, v22, v129
	v_add_f32_e32 v28, v17, v28
	v_exp_f32_e32 v22, v22
	v_sub_f32_e32 v23, v23, v129
	v_add_f32_e32 v28, v18, v28
	v_exp_f32_e32 v23, v23
	v_add_f32_e32 v28, v19, v28
	v_add_f32_e32 v28, v20, v28
	v_add_f32_e32 v28, v21, v28
	v_add_f32_e32 v28, v22, v28
	v_cvt_pk_bf16_f32 v25, v27, v30
	v_cvt_pk_bf16_f32 v27, v77, v78
	v_add_f32_e32 v130, v23, v28
	v_cvt_pk_bf16_f32 v28, v16, v17
	v_cvt_pk_bf16_f32 v29, v18, v19
	v_pk_mul_f32 v[18:19], v[66:67], v[92:93] op_sel_hi:[1,0]
	v_pk_mul_f32 v[16:17], v[64:65], v[92:93] op_sel_hi:[1,0]
	v_pk_mul_f32 v[66:67], v[106:107], v[92:93] op_sel_hi:[1,0]
	v_pk_mul_f32 v[64:65], v[104:105], v[92:93] op_sel_hi:[1,0]
	v_cvt_pk_bf16_f32 v30, v20, v21
	v_cvt_pk_bf16_f32 v31, v22, v23
	s_waitcnt lgkmcnt(8)
	v_mfma_f32_16x16x32_bf16 v[104:107], v[138:141], v[24:27], v[64:67]
	v_fmac_f32_e32 v130, v131, v76
	v_pk_mul_f32 v[22:23], v[70:71], v[76:77] op_sel_hi:[1,0]
	v_pk_mul_f32 v[20:21], v[68:69], v[76:77] op_sel_hi:[1,0]
	v_pk_mul_f32 v[66:67], v[110:111], v[76:77] op_sel_hi:[1,0]
	v_pk_mul_f32 v[64:65], v[108:109], v[76:77] op_sel_hi:[1,0]
	v_mfma_f32_16x16x32_bf16 v[16:19], v[134:137], v[24:27], v[16:19]
	s_nop 0
	v_mfma_f32_16x16x32_bf16 v[108:111], v[138:141], v[28:31], v[64:67]
	s_nop 2
	v_mul_f32_e64 v66, v114, v92
	v_mul_f32_e64 v67, v115, v92
	v_pk_mul_f32 v[64:65], v[112:113], v[92:93] op_sel_hi:[1,0]
	v_mfma_f32_16x16x32_bf16 v[20:23], v[134:137], v[28:31], v[20:23]
	s_waitcnt lgkmcnt(6)
	v_mfma_f32_16x16x32_bf16 v[112:115], v[176:179], v[24:27], v[64:67]
	s_nop 2
	v_mul_f32_e64 v66, v118, v76
	v_mul_f32_e64 v67, v119, v76
	v_pk_mul_f32 v[64:65], v[116:117], v[76:77] op_sel_hi:[1,0]
	s_nop 1
	v_mfma_f32_16x16x32_bf16 v[116:119], v[176:179], v[28:31], v[64:67]
	s_nop 2
	v_mul_f32_e64 v66, v122, v92
	v_mul_f32_e64 v67, v123, v92
	v_pk_mul_f32 v[64:65], v[120:121], v[92:93] op_sel_hi:[1,0]
	s_waitcnt lgkmcnt(4)
	s_nop 0
	v_mfma_f32_16x16x32_bf16 v[120:123], v[188:191], v[24:27], v[64:67]
	v_mul_f32_e64 v26, v126, v76
	v_mul_f32_e64 v27, v127, v76
	v_pk_mul_f32 v[24:25], v[124:125], v[76:77] op_sel_hi:[1,0]
	v_or_b32_e32 v64, 0x70, v166
	s_nop 0
	v_mfma_f32_16x16x32_bf16 v[124:127], v[188:191], v[28:31], v[24:27]
	v_add_u32_e32 v64, s76, v64
	s_nop 0
	s_nop 0
	v_add_u32_e32 v24, s76, v196
	v_med3_i32 v24, v24, 0, s75
	v_lshl_add_u32 v24, v24, 9, v152
	global_load_dwordx4 v[76:79], v24, s[98:99]
	v_add_u32_e32 v24, s76, v168
	v_med3_i32 v24, v24, 0, s75
	v_lshl_add_u32 v24, v24, 9, v152
	global_load_dwordx4 v[84:87], v24, s[98:99]
	v_add_u32_e32 v24, s76, v193
	v_med3_i32 v24, v24, 0, s75
	v_lshl_add_u32 v24, v24, 9, v152
	global_load_dwordx4 v[92:95], v24, s[98:99]
	v_add_u32_e32 v24, s76, v194
	v_med3_i32 v24, v24, 0, s75
	v_lshl_add_u32 v24, v24, 9, v152
	global_load_dwordx4 v[100:103], v24, s[98:99]
	v_or_b32_e32 v24, 0x60, v166
	v_add_u32_e32 v24, s76, v24
	v_med3_i32 v24, v24, 0, s75
	v_med3_i32 v64, v64, 0, s75
	v_lshl_add_u32 v28, v24, 9, v158
	v_lshl_add_u32 v68, v64, 9, v158
	global_load_dwordx4 v[24:27], v28, s[100:101]
	s_nop 0
	global_load_dwordx4 v[28:31], v28, s[100:101] offset:64
	s_nop 0
	global_load_dwordx4 v[64:67], v68, s[100:101]
	s_nop 0
	global_load_dwordx4 v[68:71], v68, s[100:101] offset:64
	ds_read_b64_tr_b16 v[136:137], v169 offset:6912
	ds_read_b64_tr_b16 v[134:135], v169 offset:4608
	ds_read_b64_tr_b16 v[138:139], v169 offset:4640
	ds_read_b64_tr_b16 v[140:141], v169 offset:6944
	ds_read_b64_tr_b16 v[176:177], v169 offset:4672
	ds_read_b64_tr_b16 v[178:179], v169 offset:6976
	ds_read_b64_tr_b16 v[188:189], v169 offset:4704
	ds_read_b64_tr_b16 v[190:191], v169 offset:7008
	s_waitcnt vmcnt(15)
	ds_write_b128 v241, v[72:75]
	s_waitcnt vmcnt(14)
	ds_write_b128 v242, v[80:83]
	s_waitcnt vmcnt(13)
	ds_write_b128 v243, v[88:91]
	s_waitcnt vmcnt(12)
	ds_write_b128 v244, v[96:99]
	v_mfma_f32_16x16x32_bf16 v[72:75], v[32:35], v[4:7], 0
	v_mfma_f32_16x16x32_bf16 v[32:35], v[32:35], v[12:15], 0
	v_mfma_f32_16x16x32_bf16 v[72:75], v[36:39], v[8:11], v[72:75]
	v_mfma_f32_16x16x32_bf16 v[80:83], v[48:51], v[4:7], 0
	v_mfma_f32_16x16x32_bf16 v[32:35], v[36:39], v[0:3], v[32:35]
	v_mfma_f32_16x16x32_bf16 v[36:39], v[48:51], v[12:15], 0
	v_sub_u32_e32 v48, v197, v147
	v_add_u32_e32 v51, 1, v48
	s_nop 2
	v_cmp_gt_u32_e64 s[0:1], v51, v146
	v_cmp_gt_u32_e32 vcc, v48, v146
	s_nop 0
	v_cndmask_b32_e64 v73, v73, v246, s[0:1]
	s_nop 0
	v_cndmask_b32_e32 v72, v72, v246, vcc
	v_max_f32_e32 v50, 0xf149f2ca, v72
	v_mfma_f32_16x16x32_bf16 v[80:83], v[52:55], v[8:11], v[80:83]
	v_max_f32_e32 v50, v50, v73
	v_add_u32_e32 v51, 2, v48
	v_cmp_gt_u32_e64 s[22:23], v51, v146
	v_mfma_f32_16x16x32_bf16 v[36:39], v[52:55], v[0:3], v[36:39]
	v_add_u32_e32 v52, 3, v48
	v_cmp_gt_u32_e64 s[24:25], v52, v146
	v_cndmask_b32_e64 v74, v74, v246, s[22:23]
	v_sub_u32_e32 v49, v197, v148
	v_cndmask_b32_e64 v75, v75, v246, s[24:25]
	v_max3_f32 v50, v50, v74, v75
	v_add_u32_e32 v51, 16, v48
	v_add_u32_e32 v52, 17, v48
	v_cmp_gt_u32_e64 s[26:27], v51, v146
	v_cmp_gt_u32_e64 s[28:29], v52, v146
	v_cmp_gt_u32_e64 s[38:39], v49, v145
	v_cndmask_b32_e64 v80, v80, v246, s[26:27]
	v_cndmask_b32_e64 v81, v81, v246, s[28:29]
	v_max3_f32 v50, v50, v80, v81
	v_add_u32_e32 v51, 18, v48
	v_add_u32_e32 v48, 19, v48
	v_cmp_gt_u32_e64 s[30:31], v51, v146
	v_cmp_gt_u32_e64 s[34:35], v48, v146
	v_add_u32_e32 v52, 3, v49
	v_cndmask_b32_e64 v82, v82, v246, s[30:31]
	v_cndmask_b32_e64 v83, v83, v246, s[34:35]
	v_max3_f32 v48, v50, v82, v83
	v_add_u32_e32 v51, 1, v49
	v_cmp_gt_u32_e64 s[40:41], v51, v145
	v_cndmask_b32_e64 v32, v32, v246, s[38:39]
	v_max_f32_e32 v50, 0xf149f2ca, v32
	v_cndmask_b32_e64 v33, v33, v246, s[40:41]
	v_max_f32_e32 v50, v50, v33
	v_add_u32_e32 v51, 2, v49
	v_cmp_gt_u32_e64 s[42:43], v51, v145
	v_cmp_gt_u32_e64 s[44:45], v52, v145
	s_nop 0
	v_cndmask_b32_e64 v34, v34, v246, s[42:43]
	v_cndmask_b32_e64 v35, v35, v246, s[44:45]
	v_max3_f32 v50, v50, v34, v35
	v_add_u32_e32 v51, 16, v49
	v_add_u32_e32 v52, 17, v49
	v_cmp_gt_u32_e64 s[46:47], v51, v145
	v_cmp_gt_u32_e64 s[48:49], v52, v145
	s_nop 0
	v_cndmask_b32_e64 v36, v36, v246, s[46:47]
	v_cndmask_b32_e64 v37, v37, v246, s[48:49]
	v_max3_f32 v50, v50, v36, v37
	v_add_u32_e32 v51, 18, v49
	v_add_u32_e32 v49, 19, v49
	v_cmp_gt_u32_e64 s[50:51], v51, v145
	v_cmp_gt_u32_e64 s[52:53], v49, v145
	s_nop 0
	v_cndmask_b32_e64 v38, v38, v246, s[50:51]
	v_cndmask_b32_e64 v39, v39, v246, s[52:53]
	v_max3_f32 v49, v50, v38, v39
	v_mov_b32_e32 v50, v48
	v_mov_b32_e32 v51, v48
	s_nop 1
	v_permlane32_swap_b32_e32 v50, v51
	v_max3_f32 v48, v48, v50, v51
	v_mov_b32_e32 v50, v49
	v_mov_b32_e32 v51, v49
	s_nop 1
	v_permlane32_swap_b32_e32 v50, v51
	v_max3_f32 v49, v49, v50, v51
	v_mov_b32_e32 v50, v48
	v_mov_b32_e32 v51, v48
	s_nop 1
	v_permlane16_swap_b32_e32 v50, v51
	v_max_f32_e32 v48, v48, v50
	v_mov_b32_e32 v50, v49
	v_mov_b32_e32 v53, v49
	v_max3_f32 v131, v132, v48, v51
	s_nop 0
	v_permlane16_swap_b32_e32 v50, v53
	v_sub_f32_e32 v48, v132, v131
	v_exp_f32_e32 v52, v48
	v_sub_f32_e32 v48, v72, v131
	v_max_f32_e32 v54, v49, v50
	v_exp_f32_e32 v48, v48
	v_sub_f32_e32 v50, v73, v131
	v_exp_f32_e32 v50, v50
	v_sub_f32_e32 v51, v74, v131
	v_exp_f32_e32 v51, v51
	v_sub_f32_e32 v55, v75, v131
	v_exp_f32_e32 v55, v55
	v_sub_f32_e32 v72, v80, v131
	v_exp_f32_e32 v72, v72
	v_sub_f32_e32 v73, v81, v131
	v_add_f32_e32 v49, 0, v48
	v_exp_f32_e32 v73, v73
	v_sub_f32_e32 v74, v82, v131
	v_add_f32_e32 v49, v50, v49
	v_exp_f32_e32 v74, v74
	v_sub_f32_e32 v75, v83, v131
	v_add_f32_e32 v49, v51, v49
	v_exp_f32_e32 v75, v75
	v_add_f32_e32 v49, v55, v49
	v_add_f32_e32 v49, v72, v49
	v_add_f32_e32 v49, v73, v49
	v_add_f32_e32 v49, v74, v49
	v_add_f32_e32 v132, v75, v49
	v_fmac_f32_e32 v132, v128, v52
	v_max3_f32 v128, v129, v54, v53
	v_sub_f32_e32 v32, v32, v128
	v_exp_f32_e32 v32, v32
	v_sub_f32_e32 v33, v33, v128
	v_exp_f32_e32 v33, v33
	v_sub_f32_e32 v34, v34, v128
	v_exp_f32_e32 v34, v34
	v_sub_f32_e32 v35, v35, v128
	v_exp_f32_e32 v35, v35
	v_sub_f32_e32 v36, v36, v128
	v_sub_f32_e32 v53, v129, v128
	v_exp_f32_e32 v36, v36
	v_sub_f32_e32 v37, v37, v128
	v_exp_f32_e32 v54, v53
	v_add_f32_e32 v53, 0, v32
	v_exp_f32_e32 v37, v37
	v_add_f32_e32 v53, v33, v53
	v_add_f32_e32 v53, v34, v53
	v_cvt_pk_bf16_f32 v49, v51, v55
	v_add_f32_e32 v53, v35, v53
	v_cndmask_b32_e64 v55, v36, 0, s[46:47]
	v_add_f32_e32 v36, v55, v53
	v_cndmask_b32_e64 v53, v37, 0, s[48:49]
	v_sub_f32_e32 v37, v38, v128
	v_exp_f32_e32 v37, v37
	v_cvt_pk_bf16_f32 v48, v48, v50
	v_cvt_pk_bf16_f32 v50, v72, v73
	v_add_f32_e32 v36, v53, v36
	v_cndmask_b32_e64 v72, v37, 0, s[50:51]
	v_sub_f32_e32 v37, v39, v128
	v_exp_f32_e32 v37, v37
	v_cvt_pk_bf16_f32 v51, v74, v75
	v_add_f32_e32 v36, v72, v36
	v_pk_mul_f32 v[18:19], v[18:19], v[52:53] op_sel_hi:[1,0]
	v_cndmask_b32_e64 v39, v37, 0, s[52:53]
	v_pk_mul_f32 v[16:17], v[16:17], v[52:53] op_sel_hi:[1,0]
	v_add_f32_e32 v129, v39, v36
	v_cvt_pk_bf16_f32 v36, v32, v33
	v_cvt_pk_bf16_f32 v37, v34, v35
	v_cvt_pk_bf16_f32 v38, v55, v53
	v_cvt_pk_bf16_f32 v39, v72, v39
	s_waitcnt lgkmcnt(10)
	v_mfma_f32_16x16x32_bf16 v[32:35], v[134:137], v[48:51], v[16:19]
	v_fmac_f32_e32 v129, v130, v54
	s_nop 1
	v_pk_mul_f32 v[18:19], v[22:23], v[54:55] op_sel_hi:[1,0]
	v_pk_mul_f32 v[16:17], v[20:21], v[54:55] op_sel_hi:[1,0]
	s_nop 1
	v_mfma_f32_16x16x32_bf16 v[96:99], v[134:137], v[36:39], v[16:19]
	s_nop 2
	v_mul_f32_e64 v18, v106, v52
	v_mul_f32_e64 v19, v107, v52
	v_pk_mul_f32 v[16:17], v[104:105], v[52:53] op_sel_hi:[1,0]
	s_waitcnt lgkmcnt(8)
	s_nop 0
	v_mfma_f32_16x16x32_bf16 v[104:107], v[138:141], v[48:51], v[16:19]
	s_nop 2
	v_mul_f32_e64 v18, v110, v54
	v_mul_f32_e64 v19, v111, v54
	v_pk_mul_f32 v[16:17], v[108:109], v[54:55] op_sel_hi:[1,0]
	s_nop 1
	v_mfma_f32_16x16x32_bf16 v[108:111], v[138:141], v[36:39], v[16:19]
	s_nop 2
	v_mul_f32_e64 v18, v114, v52
	v_mul_f32_e64 v19, v115, v52
	v_pk_mul_f32 v[16:17], v[112:113], v[52:53] op_sel_hi:[1,0]
	s_waitcnt lgkmcnt(6)
	s_nop 0
	v_mfma_f32_16x16x32_bf16 v[112:115], v[176:179], v[48:51], v[16:19]
	s_nop 2
	v_mul_f32_e64 v18, v118, v54
	v_mul_f32_e64 v19, v119, v54
	v_pk_mul_f32 v[16:17], v[116:117], v[54:55] op_sel_hi:[1,0]
	s_nop 1
	v_mfma_f32_16x16x32_bf16 v[116:119], v[176:179], v[36:39], v[16:19]
	s_nop 2
	v_mul_f32_e64 v18, v122, v52
	v_mul_f32_e64 v19, v123, v52
	v_pk_mul_f32 v[16:17], v[120:121], v[52:53] op_sel_hi:[1,0]
	s_waitcnt lgkmcnt(4)
	s_nop 0
	v_mfma_f32_16x16x32_bf16 v[120:123], v[188:191], v[48:51], v[16:19]
	v_or_b32_e32 v48, 0x90, v166
	v_add_u32_e32 v48, s76, v48
	s_nop 0
	v_pk_mul_f32 v[18:19], v[126:127], v[54:55] op_sel_hi:[1,0]
	v_pk_mul_f32 v[16:17], v[124:125], v[54:55] op_sel_hi:[1,0]
	s_nop 1
	v_mfma_f32_16x16x32_bf16 v[124:127], v[188:191], v[36:39], v[16:19]
	s_nop 2
	v_add_u32_e32 v16, 0x80, v149
	v_med3_i32 v16, v16, 0, s75
	v_lshl_add_u32 v16, v16, 9, v152
	global_load_dwordx4 v[36:39], v16, s[98:99]
	v_add_u32_e32 v16, 0x80, v150
	v_med3_i32 v16, v16, 0, s75
	v_lshl_add_u32 v16, v16, 9, v152
	global_load_dwordx4 v[72:75], v16, s[98:99]
	v_add_u32_e32 v16, 0x80, v151
	v_med3_i32 v16, v16, 0, s75
	v_lshl_add_u32 v16, v16, 9, v152
	global_load_dwordx4 v[80:83], v16, s[98:99]
	v_add_u32_e32 v16, 0x80, v252
	v_med3_i32 v16, v16, 0, s75
	v_lshl_add_u32 v16, v16, 9, v152
	global_load_dwordx4 v[88:91], v16, s[98:99]
	v_or_b32_e32 v16, 0x80, v166
	v_add_u32_e32 v16, s76, v16
	v_med3_i32 v16, v16, 0, s75
	v_med3_i32 v48, v48, 0, s75
	v_lshl_add_u32 v20, v16, 9, v158
	v_lshl_add_u32 v52, v48, 9, v158
	global_load_dwordx4 v[16:19], v20, s[100:101]
	s_nop 0
	global_load_dwordx4 v[20:23], v20, s[100:101] offset:64
	s_nop 0
	global_load_dwordx4 v[48:51], v52, s[100:101]
	s_nop 0
	global_load_dwordx4 v[52:55], v52, s[100:101] offset:64
	ds_read_b64_tr_b16 v[136:137], v169 offset:2304
	ds_read_b64_tr_b16 v[134:135], v169
	ds_read_b64_tr_b16 v[138:139], v169 offset:32
	ds_read_b64_tr_b16 v[140:141], v169 offset:2336
	ds_read_b64_tr_b16 v[188:189], v169 offset:64
	ds_read_b64_tr_b16 v[190:191], v169 offset:2368
	ds_read_b64_tr_b16 v[200:201], v169 offset:96
	ds_read_b64_tr_b16 v[202:203], v169 offset:2400
	s_waitcnt vmcnt(15)
	ds_write_b128 v241, v[76:79] offset:4608
	s_waitcnt vmcnt(14)
	ds_write_b128 v242, v[84:87] offset:4608
	s_waitcnt vmcnt(13)
	ds_write_b128 v243, v[92:95] offset:4608
	s_waitcnt vmcnt(12)
	ds_write_b128 v244, v[100:103] offset:4608
	v_mfma_f32_16x16x32_bf16 v[76:79], v[40:43], v[4:7], 0
	v_mfma_f32_16x16x32_bf16 v[40:43], v[40:43], v[12:15], 0
	v_mfma_f32_16x16x32_bf16 v[76:79], v[44:47], v[8:11], v[76:79]
	v_mfma_f32_16x16x32_bf16 v[84:87], v[56:59], v[4:7], 0
	v_mfma_f32_16x16x32_bf16 v[40:43], v[44:47], v[0:3], v[40:43]
	v_mfma_f32_16x16x32_bf16 v[44:47], v[56:59], v[12:15], 0
	v_sub_u32_e32 v56, v198, v147
	v_add_u32_e32 v59, 1, v56
	s_nop 2
	v_cmp_gt_u32_e64 s[0:1], v59, v146
	v_cmp_gt_u32_e32 vcc, v56, v146
	s_nop 0
	v_cndmask_b32_e64 v77, v77, v246, s[0:1]
	s_nop 0
	v_cndmask_b32_e32 v76, v76, v246, vcc
	v_max_f32_e32 v58, 0xf149f2ca, v76
	v_mfma_f32_16x16x32_bf16 v[84:87], v[60:63], v[8:11], v[84:87]
	v_max_f32_e32 v58, v58, v77
	v_add_u32_e32 v59, 2, v56
	v_cmp_gt_u32_e64 s[22:23], v59, v146
	v_mfma_f32_16x16x32_bf16 v[44:47], v[60:63], v[0:3], v[44:47]
	v_add_u32_e32 v60, 3, v56
	v_cmp_gt_u32_e64 s[24:25], v60, v146
	v_cndmask_b32_e64 v78, v78, v246, s[22:23]
	v_sub_u32_e32 v57, v198, v148
	v_cndmask_b32_e64 v79, v79, v246, s[24:25]
	v_max3_f32 v58, v58, v78, v79
	v_add_u32_e32 v59, 16, v56
	v_add_u32_e32 v60, 17, v56
	v_cmp_gt_u32_e64 s[26:27], v59, v146
	v_cmp_gt_u32_e64 s[28:29], v60, v146
	v_cmp_gt_u32_e64 s[38:39], v57, v145
	v_cndmask_b32_e64 v84, v84, v246, s[26:27]
	v_cndmask_b32_e64 v85, v85, v246, s[28:29]
	v_max3_f32 v58, v58, v84, v85
	v_add_u32_e32 v59, 18, v56
	v_add_u32_e32 v56, 19, v56
	v_cmp_gt_u32_e64 s[30:31], v59, v146
	v_cmp_gt_u32_e64 s[34:35], v56, v146
	v_add_u32_e32 v60, 3, v57
	v_cndmask_b32_e64 v86, v86, v246, s[30:31]
	v_cndmask_b32_e64 v87, v87, v246, s[34:35]
	v_max3_f32 v56, v58, v86, v87
	v_add_u32_e32 v59, 1, v57
	v_cmp_gt_u32_e64 s[40:41], v59, v145
	v_cndmask_b32_e64 v40, v40, v246, s[38:39]
	v_max_f32_e32 v58, 0xf149f2ca, v40
	v_cndmask_b32_e64 v41, v41, v246, s[40:41]
	v_max_f32_e32 v58, v58, v41
	v_add_u32_e32 v59, 2, v57
	v_cmp_gt_u32_e64 s[42:43], v59, v145
	v_cmp_gt_u32_e64 s[44:45], v60, v145
	s_nop 0
	v_cndmask_b32_e64 v42, v42, v246, s[42:43]
	v_cndmask_b32_e64 v43, v43, v246, s[44:45]
	v_max3_f32 v58, v58, v42, v43
	v_add_u32_e32 v59, 16, v57
	v_add_u32_e32 v60, 17, v57
	v_cmp_gt_u32_e64 s[46:47], v59, v145
	v_cmp_gt_u32_e64 s[48:49], v60, v145
	s_nop 0
	v_cndmask_b32_e64 v44, v44, v246, s[46:47]
	v_cndmask_b32_e64 v45, v45, v246, s[48:49]
	v_max3_f32 v58, v58, v44, v45
	v_add_u32_e32 v59, 18, v57
	v_add_u32_e32 v57, 19, v57
	v_cmp_gt_u32_e64 s[50:51], v59, v145
	v_cmp_gt_u32_e64 s[52:53], v57, v145
	s_nop 0
	v_cndmask_b32_e64 v46, v46, v246, s[50:51]
	v_cndmask_b32_e64 v47, v47, v246, s[52:53]
	v_max3_f32 v57, v58, v46, v47
	v_mov_b32_e32 v58, v56
	v_mov_b32_e32 v59, v56
	s_nop 1
	v_permlane32_swap_b32_e32 v58, v59
	v_max3_f32 v56, v56, v58, v59
	v_mov_b32_e32 v58, v57
	v_mov_b32_e32 v59, v57
	s_nop 1
	v_permlane32_swap_b32_e32 v58, v59
	v_max3_f32 v57, v57, v58, v59
	v_mov_b32_e32 v58, v56
	v_mov_b32_e32 v59, v56
	s_nop 1
	v_permlane16_swap_b32_e32 v58, v59
	v_max_f32_e32 v56, v56, v58
	v_mov_b32_e32 v58, v57
	v_mov_b32_e32 v61, v57
	s_nop 1
	v_permlane16_swap_b32_e32 v58, v61
	v_max_f32_e32 v62, v57, v58
	v_max3_f32 v175, v131, v56, v59
	v_sub_f32_e32 v56, v131, v175
	v_max3_f32 v177, v128, v62, v61
	v_exp_f32_e32 v60, v56
	v_sub_f32_e32 v56, v76, v175
	v_sub_f32_e32 v40, v40, v177
	v_exp_f32_e32 v56, v56
	v_sub_f32_e32 v58, v77, v175
	v_exp_f32_e32 v40, v40
	v_sub_f32_e32 v41, v41, v177
	v_exp_f32_e32 v58, v58
	v_sub_f32_e32 v59, v78, v175
	v_exp_f32_e32 v41, v41
	v_sub_f32_e32 v42, v42, v177
	v_exp_f32_e32 v59, v59
	v_sub_f32_e32 v63, v79, v175
	v_exp_f32_e32 v42, v42
	v_sub_f32_e32 v43, v43, v177
	v_exp_f32_e32 v63, v63
	v_sub_f32_e32 v76, v84, v175
	v_exp_f32_e32 v43, v43
	v_sub_f32_e32 v44, v44, v177
	v_exp_f32_e32 v76, v76
	v_sub_f32_e32 v77, v85, v175
	v_sub_f32_e32 v61, v128, v177
	v_exp_f32_e32 v44, v44
	v_sub_f32_e32 v45, v45, v177
	v_add_f32_e32 v57, 0, v56
	v_exp_f32_e32 v77, v77
	v_sub_f32_e32 v78, v86, v175
	v_exp_f32_e32 v62, v61
	v_add_f32_e32 v61, 0, v40
	v_exp_f32_e32 v45, v45
	v_sub_f32_e32 v46, v46, v177
	v_add_f32_e32 v57, v58, v57
	v_exp_f32_e32 v78, v78
	v_sub_f32_e32 v79, v87, v175
	v_add_f32_e32 v61, v41, v61
	v_exp_f32_e32 v46, v46
	v_add_f32_e32 v57, v59, v57
	v_exp_f32_e32 v79, v79
	v_add_f32_e32 v61, v42, v61
	v_sub_f32_e32 v47, v47, v177
	v_add_f32_e32 v57, v63, v57
	v_add_f32_e32 v61, v43, v61
	v_exp_f32_e32 v47, v47
	v_add_f32_e32 v57, v76, v57
	v_add_f32_e32 v61, v44, v61
	v_add_f32_e32 v57, v77, v57
	v_add_f32_e32 v61, v45, v61
	v_add_f32_e32 v57, v78, v57
	v_add_f32_e32 v61, v46, v61
	v_add_f32_e32 v176, v79, v57
	v_cvt_pk_bf16_f32 v56, v56, v58
	v_cvt_pk_bf16_f32 v57, v59, v63
	v_cvt_pk_bf16_f32 v58, v76, v77
	v_cvt_pk_bf16_f32 v59, v78, v79
	v_pk_mul_f32 v[34:35], v[34:35], v[60:61] op_sel_hi:[1,0]
	v_pk_mul_f32 v[32:33], v[32:33], v[60:61] op_sel_hi:[1,0]
	v_add_f32_e32 v178, v47, v61
	v_cvt_pk_bf16_f32 v40, v40, v41
	v_cvt_pk_bf16_f32 v41, v42, v43
	v_cvt_pk_bf16_f32 v42, v44, v45
	v_cvt_pk_bf16_f32 v43, v46, v47
	s_waitcnt lgkmcnt(10)
	v_mfma_f32_16x16x32_bf16 v[44:47], v[134:137], v[56:59], v[32:35]
	v_fmac_f32_e32 v176, v132, v60
	v_fmac_f32_e32 v178, v129, v62
	s_nop 0
	v_pk_mul_f32 v[34:35], v[98:99], v[62:63] op_sel_hi:[1,0]
	v_pk_mul_f32 v[32:33], v[96:97], v[62:63] op_sel_hi:[1,0]
	s_nop 1
	v_mfma_f32_16x16x32_bf16 v[100:103], v[134:137], v[40:43], v[32:35]
	s_nop 2
	v_mul_f32_e64 v34, v106, v60
	v_mul_f32_e64 v35, v107, v60
	v_pk_mul_f32 v[32:33], v[104:105], v[60:61] op_sel_hi:[1,0]
	s_waitcnt lgkmcnt(8)
	s_nop 0
	v_mfma_f32_16x16x32_bf16 v[104:107], v[138:141], v[56:59], v[32:35]
	s_nop 2
	v_mul_f32_e64 v34, v110, v62
	v_mul_f32_e64 v35, v111, v62
	v_pk_mul_f32 v[32:33], v[108:109], v[62:63] op_sel_hi:[1,0]
	s_nop 1
	v_mfma_f32_16x16x32_bf16 v[108:111], v[138:141], v[40:43], v[32:35]
	s_nop 2
	v_mul_f32_e64 v34, v114, v60
	v_mul_f32_e64 v35, v115, v60
	v_pk_mul_f32 v[32:33], v[112:113], v[60:61] op_sel_hi:[1,0]
	s_waitcnt lgkmcnt(6)
	s_nop 0
	v_mfma_f32_16x16x32_bf16 v[112:115], v[188:191], v[56:59], v[32:35]
	s_nop 2
	v_mul_f32_e64 v34, v118, v62
	v_mul_f32_e64 v35, v119, v62
	v_pk_mul_f32 v[32:33], v[116:117], v[62:63] op_sel_hi:[1,0]
	s_nop 1
	v_mfma_f32_16x16x32_bf16 v[116:119], v[188:191], v[40:43], v[32:35]
	v_add_u32_e32 v188, s76, v207
	s_nop 1
	v_pk_mul_f32 v[34:35], v[122:123], v[60:61] op_sel_hi:[1,0]
	v_pk_mul_f32 v[32:33], v[120:121], v[60:61] op_sel_hi:[1,0]
	s_waitcnt lgkmcnt(4)
	s_nop 0
	v_mfma_f32_16x16x32_bf16 v[120:123], v[200:203], v[56:59], v[32:35]
	v_or_b32_e32 v56, 0xb0, v166
	v_add_u32_e32 v56, s76, v56
	s_nop 0
	v_pk_mul_f32 v[34:35], v[126:127], v[62:63] op_sel_hi:[1,0]
	v_pk_mul_f32 v[32:33], v[124:125], v[62:63] op_sel_hi:[1,0]
	s_nop 1
	v_mfma_f32_16x16x32_bf16 v[124:127], v[200:203], v[40:43], v[32:35]
	s_nop 2
	v_add_u32_e32 v32, 0xa0, v149
	v_med3_i32 v32, v32, 0, s75
	v_lshl_add_u32 v32, v32, 9, v152
	global_load_dwordx4 v[76:79], v32, s[98:99]
	v_add_u32_e32 v32, 0xa0, v150
	v_med3_i32 v32, v32, 0, s75
	v_lshl_add_u32 v32, v32, 9, v152
	global_load_dwordx4 v[84:87], v32, s[98:99]
	v_add_u32_e32 v32, 0xa0, v151
	v_med3_i32 v32, v32, 0, s75
	v_lshl_add_u32 v32, v32, 9, v152
	global_load_dwordx4 v[92:95], v32, s[98:99]
	v_add_u32_e32 v32, 0xa0, v252
	v_med3_i32 v32, v32, 0, s75
	v_lshl_add_u32 v32, v32, 9, v152
	global_load_dwordx4 v[96:99], v32, s[98:99]
	v_or_b32_e32 v32, 0xa0, v166
	v_add_u32_e32 v32, s76, v32
	v_med3_i32 v32, v32, 0, s75
	v_med3_i32 v56, v56, 0, s75
	v_lshl_add_u32 v40, v32, 9, v158
	v_lshl_add_u32 v60, v56, 9, v158
	global_load_dwordx4 v[32:35], v40, s[100:101]
	s_nop 0
	global_load_dwordx4 v[40:43], v40, s[100:101] offset:64
	s_nop 0
	global_load_dwordx4 v[56:59], v60, s[100:101]
	s_nop 0
	global_load_dwordx4 v[60:63], v60, s[100:101] offset:64
	ds_read_b64_tr_b16 v[142:143], v169 offset:6912
	ds_read_b64_tr_b16 v[140:141], v169 offset:4608
	ds_read_b64_tr_b16 v[136:137], v169 offset:4640
	ds_read_b64_tr_b16 v[138:139], v169 offset:6944
	ds_read_b64_tr_b16 v[132:133], v169 offset:4672
	ds_read_b64_tr_b16 v[134:135], v169 offset:6976
	ds_read_b64_tr_b16 v[128:129], v169 offset:4704
	ds_read_b64_tr_b16 v[130:131], v169 offset:7008
	s_waitcnt vmcnt(15)
	ds_write_b128 v241, v[36:39]
	s_waitcnt vmcnt(14)
	ds_write_b128 v242, v[72:75]
	s_waitcnt vmcnt(13)
	ds_write_b128 v243, v[80:83]
	s_waitcnt vmcnt(12)
	ds_write_b128 v244, v[88:91]
	v_mfma_f32_16x16x32_bf16 v[36:39], v[24:27], v[4:7], 0
	v_mfma_f32_16x16x32_bf16 v[24:27], v[24:27], v[12:15], 0
	v_mfma_f32_16x16x32_bf16 v[36:39], v[28:31], v[8:11], v[36:39]
	v_mfma_f32_16x16x32_bf16 v[72:75], v[64:67], v[4:7], 0
	v_mfma_f32_16x16x32_bf16 v[24:27], v[28:31], v[0:3], v[24:27]
	v_mfma_f32_16x16x32_bf16 v[28:31], v[64:67], v[12:15], 0
	v_sub_u32_e32 v64, v199, v147
	v_add_u32_e32 v67, 1, v64
	s_nop 2
	v_cmp_gt_u32_e64 s[0:1], v67, v146
	v_cmp_gt_u32_e32 vcc, v64, v146
	s_nop 0
	v_cndmask_b32_e64 v37, v37, v246, s[0:1]
	s_nop 0
	v_cndmask_b32_e32 v36, v36, v246, vcc
	v_max_f32_e32 v66, 0xf149f2ca, v36
	v_mfma_f32_16x16x32_bf16 v[72:75], v[68:71], v[8:11], v[72:75]
	v_max_f32_e32 v66, v66, v37
	v_add_u32_e32 v67, 2, v64
	v_cmp_gt_u32_e64 s[22:23], v67, v146
	v_mfma_f32_16x16x32_bf16 v[28:31], v[68:71], v[0:3], v[28:31]
	v_add_u32_e32 v68, 3, v64
	v_cmp_gt_u32_e64 s[24:25], v68, v146
	v_cndmask_b32_e64 v38, v38, v246, s[22:23]
	v_sub_u32_e32 v65, v199, v148
	v_cndmask_b32_e64 v39, v39, v246, s[24:25]
	v_max3_f32 v66, v66, v38, v39
	v_add_u32_e32 v67, 16, v64
	v_add_u32_e32 v68, 17, v64
	v_cmp_gt_u32_e64 s[26:27], v67, v146
	v_cmp_gt_u32_e64 s[28:29], v68, v146
	v_cmp_gt_u32_e64 s[38:39], v65, v145
	v_cndmask_b32_e64 v72, v72, v246, s[26:27]
	v_cndmask_b32_e64 v73, v73, v246, s[28:29]
	v_max3_f32 v66, v66, v72, v73
	v_add_u32_e32 v67, 18, v64
	v_add_u32_e32 v64, 19, v64
	v_cmp_gt_u32_e64 s[30:31], v67, v146
	v_cmp_gt_u32_e64 s[34:35], v64, v146
	v_add_u32_e32 v68, 3, v65
	v_cndmask_b32_e64 v74, v74, v246, s[30:31]
	v_cndmask_b32_e64 v75, v75, v246, s[34:35]
	v_max3_f32 v64, v66, v74, v75
	v_add_u32_e32 v67, 1, v65
	v_cmp_gt_u32_e64 s[40:41], v67, v145
	v_cndmask_b32_e64 v24, v24, v246, s[38:39]
	v_max_f32_e32 v66, 0xf149f2ca, v24
	v_cndmask_b32_e64 v25, v25, v246, s[40:41]
	v_max_f32_e32 v66, v66, v25
	v_add_u32_e32 v67, 2, v65
	v_cmp_gt_u32_e64 s[42:43], v67, v145
	v_cmp_gt_u32_e64 s[44:45], v68, v145
	s_nop 0
	v_cndmask_b32_e64 v26, v26, v246, s[42:43]
	v_cndmask_b32_e64 v27, v27, v246, s[44:45]
	v_max3_f32 v66, v66, v26, v27
	v_add_u32_e32 v67, 16, v65
	v_add_u32_e32 v68, 17, v65
	v_cmp_gt_u32_e64 s[46:47], v67, v145
	v_cmp_gt_u32_e64 s[48:49], v68, v145
	s_nop 0
	v_cndmask_b32_e64 v28, v28, v246, s[46:47]
	v_cndmask_b32_e64 v29, v29, v246, s[48:49]
	v_max3_f32 v66, v66, v28, v29
	v_add_u32_e32 v67, 18, v65
	v_add_u32_e32 v65, 19, v65
	v_cmp_gt_u32_e64 s[50:51], v67, v145
	v_cmp_gt_u32_e64 s[52:53], v65, v145
	s_nop 0
	v_cndmask_b32_e64 v30, v30, v246, s[50:51]
	v_cndmask_b32_e64 v31, v31, v246, s[52:53]
	v_max3_f32 v65, v66, v30, v31
	v_mov_b32_e32 v66, v64
	v_mov_b32_e32 v67, v64
	s_nop 1
	v_permlane32_swap_b32_e32 v66, v67
	v_max3_f32 v64, v64, v66, v67
	v_mov_b32_e32 v66, v65
	v_mov_b32_e32 v67, v65
	s_nop 1
	v_permlane32_swap_b32_e32 v66, v67
	v_max3_f32 v65, v65, v66, v67
	v_mov_b32_e32 v66, v64
	v_mov_b32_e32 v67, v64
	s_nop 1
	v_permlane16_swap_b32_e32 v66, v67
	v_max_f32_e32 v64, v64, v66
	v_max3_f32 v179, v175, v64, v67
	v_sub_f32_e32 v36, v36, v179
	v_exp_f32_e32 v36, v36
	v_sub_f32_e32 v37, v37, v179
	v_mov_b32_e32 v66, v65
	v_mov_b32_e32 v68, v65
	v_exp_f32_e32 v37, v37
	v_sub_f32_e32 v38, v38, v179
	v_permlane16_swap_b32_e32 v66, v68
	v_exp_f32_e32 v38, v38
	v_sub_f32_e32 v39, v39, v179
	v_exp_f32_e32 v39, v39
	v_sub_f32_e32 v67, v72, v179
	v_max_f32_e32 v65, v65, v66
	v_exp_f32_e32 v67, v67
	v_sub_f32_e32 v69, v73, v179
	v_add_f32_e32 v66, 0, v36
	v_exp_f32_e32 v69, v69
	v_sub_f32_e32 v70, v74, v179
	v_max3_f32 v181, v177, v65, v68
	v_add_f32_e32 v66, v37, v66
	v_exp_f32_e32 v70, v70
	v_sub_f32_e32 v71, v75, v179
	v_sub_f32_e32 v24, v24, v181
	v_add_f32_e32 v66, v38, v66
	v_exp_f32_e32 v71, v71
	v_exp_f32_e32 v24, v24
	v_sub_f32_e32 v25, v25, v181
	v_add_f32_e32 v66, v39, v66
	v_exp_f32_e32 v25, v25
	v_sub_f32_e32 v26, v26, v181
	v_add_f32_e32 v66, v67, v66
	v_exp_f32_e32 v26, v26
	v_sub_f32_e32 v27, v27, v181
	v_add_f32_e32 v66, v69, v66
	v_exp_f32_e32 v27, v27
	v_sub_f32_e32 v28, v28, v181
	v_add_f32_e32 v66, v70, v66
	v_sub_f32_e32 v65, v177, v181
	v_exp_f32_e32 v28, v28
	v_sub_f32_e32 v29, v29, v181
	v_add_f32_e32 v180, v71, v66
	v_exp_f32_e32 v66, v65
	v_add_f32_e32 v65, 0, v24
	v_exp_f32_e32 v29, v29
	v_sub_f32_e32 v30, v30, v181
	v_add_f32_e32 v65, v25, v65
	v_exp_f32_e32 v30, v30
	v_sub_f32_e32 v31, v31, v181
	v_sub_f32_e32 v64, v175, v179
	v_add_f32_e32 v65, v26, v65
	v_exp_f32_e32 v31, v31
	v_exp_f32_e32 v64, v64
	v_add_f32_e32 v65, v27, v65
	v_add_f32_e32 v65, v28, v65
	v_add_f32_e32 v65, v29, v65
	v_add_f32_e32 v65, v30, v65
	v_cvt_pk_bf16_f32 v36, v36, v37
	v_cvt_pk_bf16_f32 v37, v38, v39
	v_cvt_pk_bf16_f32 v38, v67, v69
	v_cvt_pk_bf16_f32 v39, v70, v71
	v_add_f32_e32 v183, v31, v65
	v_cvt_pk_bf16_f32 v24, v24, v25
	v_cvt_pk_bf16_f32 v25, v26, v27
	v_cvt_pk_bf16_f32 v26, v28, v29
	v_cvt_pk_bf16_f32 v27, v30, v31
	v_pk_mul_f32 v[30:31], v[46:47], v[64:65] op_sel_hi:[1,0]
	v_pk_mul_f32 v[28:29], v[44:45], v[64:65] op_sel_hi:[1,0]
	v_fmac_f32_e32 v180, v176, v64
	v_fmac_f32_e32 v183, v178, v66
	s_waitcnt lgkmcnt(10)
	v_mfma_f32_16x16x32_bf16 v[68:71], v[140:143], v[36:39], v[28:31]
	s_nop 2
	v_mul_f32_e64 v30, v102, v66
	v_mul_f32_e64 v31, v103, v66
	v_pk_mul_f32 v[28:29], v[100:101], v[66:67] op_sel_hi:[1,0]
	s_nop 1
	v_mfma_f32_16x16x32_bf16 v[72:75], v[140:143], v[24:27], v[28:31]
	s_nop 2
	v_mul_f32_e64 v30, v106, v64
	v_mul_f32_e64 v31, v107, v64
	v_pk_mul_f32 v[28:29], v[104:105], v[64:65] op_sel_hi:[1,0]
	s_waitcnt lgkmcnt(8)
	s_nop 0
	v_mfma_f32_16x16x32_bf16 v[80:83], v[136:139], v[36:39], v[28:31]
	s_nop 2
	v_mul_f32_e64 v30, v110, v66
	v_mul_f32_e64 v31, v111, v66
	v_pk_mul_f32 v[28:29], v[108:109], v[66:67] op_sel_hi:[1,0]
	s_nop 1
	v_mfma_f32_16x16x32_bf16 v[108:111], v[136:139], v[24:27], v[28:31]
	s_nop 2
	v_mul_f32_e64 v30, v114, v64
	v_mul_f32_e64 v31, v115, v64
	v_pk_mul_f32 v[28:29], v[112:113], v[64:65] op_sel_hi:[1,0]
	s_waitcnt lgkmcnt(6)
	s_nop 0
	v_mfma_f32_16x16x32_bf16 v[112:115], v[132:135], v[36:39], v[28:31]
	s_nop 2
	v_mul_f32_e64 v30, v118, v66
	v_mul_f32_e64 v31, v119, v66
	v_pk_mul_f32 v[28:29], v[116:117], v[66:67] op_sel_hi:[1,0]
	s_nop 1
	v_mfma_f32_16x16x32_bf16 v[116:119], v[132:135], v[24:27], v[28:31]
	s_nop 2
	v_mul_f32_e64 v30, v122, v64
	v_mul_f32_e64 v31, v123, v64
	v_pk_mul_f32 v[28:29], v[120:121], v[64:65] op_sel_hi:[1,0]
	s_waitcnt lgkmcnt(4)
	s_nop 0
	v_mfma_f32_16x16x32_bf16 v[120:123], v[128:131], v[36:39], v[28:31]
	s_nop 2
	v_mul_f32_e64 v30, v126, v66
	v_mul_f32_e64 v31, v127, v66
	v_pk_mul_f32 v[28:29], v[124:125], v[66:67] op_sel_hi:[1,0]
	s_nop 1
	v_mfma_f32_16x16x32_bf16 v[124:127], v[128:131], v[24:27], v[28:31]
	v_add_u32_e32 v24, 0xc0, v149
	v_med3_i32 v24, v24, 0, s75
	v_lshl_add_u32 v24, v24, 9, v152
	global_load_dwordx4 v[64:67], v24, s[98:99]
	v_add_u32_e32 v24, 0xc0, v150
	v_med3_i32 v24, v24, 0, s75
	v_lshl_add_u32 v24, v24, 9, v152
	global_load_dwordx4 v[88:91], v24, s[98:99]
	v_add_u32_e32 v24, 0xc0, v151
	v_med3_i32 v24, v24, 0, s75
	v_lshl_add_u32 v24, v24, 9, v152
	global_load_dwordx4 v[100:103], v24, s[98:99]
	v_add_u32_e32 v24, 0xc0, v252
	v_med3_i32 v24, v24, 0, s75
	v_lshl_add_u32 v24, v24, 9, v152
	global_load_dwordx4 v[104:107], v24, s[98:99]
	v_or_b32_e32 v24, 0xc0, v166
	v_add_u32_e32 v24, s76, v24
	v_med3_i32 v24, v24, 0, s75
	v_lshl_add_u32 v24, v24, 9, v158
	global_load_dwordx4 v[36:39], v24, s[100:101]
	global_load_dwordx4 v[44:47], v24, s[100:101] offset:64
	v_or_b32_e32 v24, 0xd0, v166
	v_add_u32_e32 v24, s76, v24
	v_med3_i32 v24, v24, 0, s75
	v_lshl_add_u32 v28, v24, 9, v158
	global_load_dwordx4 v[24:27], v28, s[100:101]
	s_nop 0
	global_load_dwordx4 v[28:31], v28, s[100:101] offset:64
	ds_read_b64_tr_b16 v[142:143], v169 offset:2304
	ds_read_b64_tr_b16 v[140:141], v169
	ds_read_b64_tr_b16 v[136:137], v169 offset:32
	ds_read_b64_tr_b16 v[138:139], v169 offset:2336
	ds_read_b64_tr_b16 v[132:133], v169 offset:64
	ds_read_b64_tr_b16 v[134:135], v169 offset:2368
	ds_read_b64_tr_b16 v[128:129], v169 offset:96
	ds_read_b64_tr_b16 v[130:131], v169 offset:2400
	s_waitcnt vmcnt(15)
	ds_write_b128 v241, v[76:79] offset:4608
	s_waitcnt vmcnt(14)
	ds_write_b128 v242, v[84:87] offset:4608
	s_waitcnt vmcnt(13)
	ds_write_b128 v243, v[92:95] offset:4608
	s_waitcnt vmcnt(12)
	ds_write_b128 v244, v[96:99] offset:4608
	v_mfma_f32_16x16x32_bf16 v[76:79], v[16:19], v[4:7], 0
	v_mfma_f32_16x16x32_bf16 v[16:19], v[16:19], v[12:15], 0
	v_mfma_f32_16x16x32_bf16 v[76:79], v[20:23], v[8:11], v[76:79]
	v_mfma_f32_16x16x32_bf16 v[84:87], v[48:51], v[4:7], 0
	v_mfma_f32_16x16x32_bf16 v[16:19], v[20:23], v[0:3], v[16:19]
	v_mfma_f32_16x16x32_bf16 v[20:23], v[48:51], v[12:15], 0
	v_add_u32_e32 v49, 0xc0, v154
	v_sub_u32_e32 v48, v49, v147
	v_add_u32_e32 v51, 1, v48
	s_nop 1
	v_cmp_gt_u32_e64 s[0:1], v51, v146
	v_cmp_gt_u32_e32 vcc, v48, v146
	s_nop 0
	v_cndmask_b32_e64 v77, v77, v246, s[0:1]
	s_nop 0
	v_cndmask_b32_e32 v76, v76, v246, vcc
	v_max_f32_e32 v50, 0xf149f2ca, v76
	v_mfma_f32_16x16x32_bf16 v[84:87], v[52:55], v[8:11], v[84:87]
	v_max_f32_e32 v50, v50, v77
	v_add_u32_e32 v51, 2, v48
	v_cmp_gt_u32_e64 s[22:23], v51, v146
	v_mfma_f32_16x16x32_bf16 v[20:23], v[52:55], v[0:3], v[20:23]
	v_add_u32_e32 v52, 3, v48
	v_cmp_gt_u32_e64 s[24:25], v52, v146
	v_cndmask_b32_e64 v78, v78, v246, s[22:23]
	v_sub_u32_e32 v49, v49, v148
	v_cndmask_b32_e64 v79, v79, v246, s[24:25]
	v_max3_f32 v50, v50, v78, v79
	v_add_u32_e32 v51, 16, v48
	v_add_u32_e32 v52, 17, v48
	v_cmp_gt_u32_e64 s[26:27], v51, v146
	v_cmp_gt_u32_e64 s[28:29], v52, v146
	v_cmp_gt_u32_e64 s[38:39], v49, v145
	v_cndmask_b32_e64 v84, v84, v246, s[26:27]
	v_cndmask_b32_e64 v85, v85, v246, s[28:29]
	v_max3_f32 v50, v50, v84, v85
	v_add_u32_e32 v51, 18, v48
	v_add_u32_e32 v48, 19, v48
	v_cmp_gt_u32_e64 s[30:31], v51, v146
	v_cmp_gt_u32_e64 s[34:35], v48, v146
	v_add_u32_e32 v52, 3, v49
	v_cndmask_b32_e64 v86, v86, v246, s[30:31]
	v_cndmask_b32_e64 v87, v87, v246, s[34:35]
	v_max3_f32 v48, v50, v86, v87
	v_add_u32_e32 v51, 1, v49
	v_cmp_gt_u32_e64 s[40:41], v51, v145
	v_cndmask_b32_e64 v16, v16, v246, s[38:39]
	v_max_f32_e32 v50, 0xf149f2ca, v16
	v_cndmask_b32_e64 v17, v17, v246, s[40:41]
	v_max_f32_e32 v50, v50, v17
	v_add_u32_e32 v51, 2, v49
	v_cmp_gt_u32_e64 s[42:43], v51, v145
	v_cmp_gt_u32_e64 s[44:45], v52, v145
	s_nop 0
	v_cndmask_b32_e64 v18, v18, v246, s[42:43]
	v_cndmask_b32_e64 v19, v19, v246, s[44:45]
	v_max3_f32 v50, v50, v18, v19
	v_add_u32_e32 v51, 16, v49
	v_add_u32_e32 v52, 17, v49
	v_cmp_gt_u32_e64 s[46:47], v51, v145
	v_cmp_gt_u32_e64 s[48:49], v52, v145
	s_nop 0
	v_cndmask_b32_e64 v20, v20, v246, s[46:47]
	v_cndmask_b32_e64 v21, v21, v246, s[48:49]
	v_max3_f32 v50, v50, v20, v21
	v_add_u32_e32 v51, 18, v49
	v_add_u32_e32 v49, 19, v49
	v_cmp_gt_u32_e64 s[50:51], v51, v145
	v_cmp_gt_u32_e64 s[52:53], v49, v145
	s_nop 0
	v_cndmask_b32_e64 v22, v22, v246, s[50:51]
	v_cndmask_b32_e64 v23, v23, v246, s[52:53]
	v_max3_f32 v49, v50, v22, v23
	v_mov_b32_e32 v50, v48
	v_mov_b32_e32 v51, v48
	s_nop 1
	v_permlane32_swap_b32_e32 v50, v51
	v_max3_f32 v48, v48, v50, v51
	v_mov_b32_e32 v50, v49
	v_mov_b32_e32 v51, v49
	s_nop 1
	v_permlane32_swap_b32_e32 v50, v51
	v_max3_f32 v49, v49, v50, v51
	v_mov_b32_e32 v50, v48
	v_mov_b32_e32 v51, v48
	s_nop 1
	v_permlane16_swap_b32_e32 v50, v51
	v_max_f32_e32 v48, v48, v50
	v_mov_b32_e32 v50, v49
	v_mov_b32_e32 v53, v49
	s_nop 1
	v_permlane16_swap_b32_e32 v50, v53
	v_max_f32_e32 v54, v49, v50
	v_max3_f32 v175, v179, v48, v51
	v_sub_f32_e32 v48, v179, v175
	v_max3_f32 v177, v181, v54, v53
	v_exp_f32_e32 v52, v48
	v_sub_f32_e32 v48, v76, v175
	v_sub_f32_e32 v16, v16, v177
	v_exp_f32_e32 v48, v48
	v_sub_f32_e32 v50, v77, v175
	v_exp_f32_e32 v16, v16
	v_sub_f32_e32 v17, v17, v177
	v_exp_f32_e32 v50, v50
	v_sub_f32_e32 v51, v78, v175
	v_exp_f32_e32 v17, v17
	v_sub_f32_e32 v18, v18, v177
	v_exp_f32_e32 v51, v51
	v_sub_f32_e32 v55, v79, v175
	v_exp_f32_e32 v18, v18
	v_sub_f32_e32 v19, v19, v177
	v_exp_f32_e32 v55, v55
	v_sub_f32_e32 v76, v84, v175
	v_exp_f32_e32 v19, v19
	v_sub_f32_e32 v20, v20, v177
	v_exp_f32_e32 v76, v76
	v_sub_f32_e32 v77, v85, v175
	v_sub_f32_e32 v53, v181, v177
	v_exp_f32_e32 v20, v20
	v_sub_f32_e32 v21, v21, v177
	v_add_f32_e32 v49, 0, v48
	v_exp_f32_e32 v77, v77
	v_sub_f32_e32 v78, v86, v175
	v_exp_f32_e32 v54, v53
	v_add_f32_e32 v53, 0, v16
	v_exp_f32_e32 v21, v21
	v_sub_f32_e32 v22, v22, v177
	v_add_f32_e32 v49, v50, v49
	v_exp_f32_e32 v78, v78
	v_sub_f32_e32 v79, v87, v175
	v_add_f32_e32 v53, v17, v53
	v_exp_f32_e32 v22, v22
	v_sub_f32_e32 v23, v23, v177
	v_add_f32_e32 v49, v51, v49
	v_exp_f32_e32 v79, v79
	v_add_f32_e32 v53, v18, v53
	v_exp_f32_e32 v23, v23
	v_add_f32_e32 v49, v55, v49
	v_add_f32_e32 v53, v19, v53
	v_add_f32_e32 v49, v76, v49
	v_add_f32_e32 v53, v20, v53
	v_add_f32_e32 v49, v77, v49
	v_add_f32_e32 v53, v21, v53
	v_add_f32_e32 v49, v78, v49
	v_add_f32_e32 v53, v22, v53
	v_add_f32_e32 v176, v79, v49
	v_cvt_pk_bf16_f32 v48, v48, v50
	v_cvt_pk_bf16_f32 v49, v51, v55
	v_cvt_pk_bf16_f32 v50, v76, v77
	v_cvt_pk_bf16_f32 v51, v78, v79
	v_add_f32_e32 v178, v23, v53
	v_cvt_pk_bf16_f32 v16, v16, v17
	v_cvt_pk_bf16_f32 v17, v18, v19
	v_cvt_pk_bf16_f32 v18, v20, v21
	v_cvt_pk_bf16_f32 v19, v22, v23
	v_pk_mul_f32 v[22:23], v[70:71], v[52:53] op_sel_hi:[1,0]
	v_pk_mul_f32 v[20:21], v[68:69], v[52:53] op_sel_hi:[1,0]
	v_fmac_f32_e32 v176, v180, v52
	v_fmac_f32_e32 v178, v183, v54
	s_waitcnt lgkmcnt(10)
	v_mfma_f32_16x16x32_bf16 v[76:79], v[140:143], v[48:51], v[20:23]
	v_add_u32_e32 v180, 0x100, v149
	v_add_u32_e32 v179, 0x100, v150
	s_nop 0
	v_pk_mul_f32 v[22:23], v[74:75], v[54:55] op_sel_hi:[1,0]
	v_pk_mul_f32 v[20:21], v[72:73], v[54:55] op_sel_hi:[1,0]
	s_nop 1
	v_mfma_f32_16x16x32_bf16 v[92:95], v[140:143], v[16:19], v[20:23]
	s_nop 2
	v_mul_f32_e64 v22, v82, v52
	v_mul_f32_e64 v23, v83, v52
	v_pk_mul_f32 v[20:21], v[80:81], v[52:53] op_sel_hi:[1,0]
	s_waitcnt lgkmcnt(8)
	s_nop 0
	v_mfma_f32_16x16x32_bf16 v[96:99], v[136:139], v[48:51], v[20:23]
	s_nop 2
	v_mul_f32_e64 v22, v110, v54
	v_mul_f32_e64 v23, v111, v54
	v_pk_mul_f32 v[20:21], v[108:109], v[54:55] op_sel_hi:[1,0]
	s_nop 1
	v_mfma_f32_16x16x32_bf16 v[108:111], v[136:139], v[16:19], v[20:23]
	s_nop 2
	v_mul_f32_e64 v22, v114, v52
	v_mul_f32_e64 v23, v115, v52
	v_pk_mul_f32 v[20:21], v[112:113], v[52:53] op_sel_hi:[1,0]
	s_waitcnt lgkmcnt(6)
	s_nop 0
	v_mfma_f32_16x16x32_bf16 v[112:115], v[132:135], v[48:51], v[20:23]
	s_nop 2
	v_mul_f32_e64 v22, v118, v54
	v_mul_f32_e64 v23, v119, v54
	v_pk_mul_f32 v[20:21], v[116:117], v[54:55] op_sel_hi:[1,0]
	s_nop 1
	v_mfma_f32_16x16x32_bf16 v[116:119], v[132:135], v[16:19], v[20:23]
	s_nop 2
	v_mul_f32_e64 v22, v122, v52
	v_mul_f32_e64 v23, v123, v52
	v_pk_mul_f32 v[20:21], v[120:121], v[52:53] op_sel_hi:[1,0]
	s_waitcnt lgkmcnt(4)
	s_nop 0
	v_mfma_f32_16x16x32_bf16 v[120:123], v[128:131], v[48:51], v[20:23]
	s_nop 2
	v_mul_f32_e64 v22, v126, v54
	v_mul_f32_e64 v23, v127, v54
	v_pk_mul_f32 v[20:21], v[124:125], v[54:55] op_sel_hi:[1,0]
	s_nop 1
	v_mfma_f32_16x16x32_bf16 v[124:127], v[128:131], v[16:19], v[20:23]
	v_add_u32_e32 v16, 0xe0, v149
	v_med3_i32 v16, v16, 0, s75
	v_lshl_add_u32 v16, v16, 9, v152
	global_load_dwordx4 v[68:71], v16, s[98:99]
	v_add_u32_e32 v16, 0xe0, v150
	v_med3_i32 v16, v16, 0, s75
	v_lshl_add_u32 v16, v16, 9, v152
	global_load_dwordx4 v[72:75], v16, s[98:99]
	v_add_u32_e32 v16, 0xe0, v151
	v_med3_i32 v16, v16, 0, s75
	v_lshl_add_u32 v16, v16, 9, v152
	global_load_dwordx4 v[80:83], v16, s[98:99]
	v_add_u32_e32 v16, 0xe0, v252
	v_med3_i32 v16, v16, 0, s75
	v_lshl_add_u32 v16, v16, 9, v152
	global_load_dwordx4 v[84:87], v16, s[98:99]
	v_or_b32_e32 v16, 0xe0, v166
	v_add_u32_e32 v16, s76, v16
	v_med3_i32 v16, v16, 0, s75
	v_lshl_add_u32 v16, v16, 9, v158
	global_load_dwordx4 v[48:51], v16, s[100:101]
	global_load_dwordx4 v[52:55], v16, s[100:101] offset:64
	v_or_b32_e32 v16, 0xf0, v166
	v_add_u32_e32 v16, s76, v16
	v_med3_i32 v16, v16, 0, s75
	v_lshl_add_u32 v20, v16, 9, v158
	global_load_dwordx4 v[16:19], v20, s[100:101]
	s_nop 0
	global_load_dwordx4 v[20:23], v20, s[100:101] offset:64
	ds_read_b64_tr_b16 v[142:143], v169 offset:6912
	ds_read_b64_tr_b16 v[140:141], v169 offset:4608
	ds_read_b64_tr_b16 v[136:137], v169 offset:4640
	ds_read_b64_tr_b16 v[138:139], v169 offset:6944
	ds_read_b64_tr_b16 v[132:133], v169 offset:4672
	ds_read_b64_tr_b16 v[134:135], v169 offset:6976
	ds_read_b64_tr_b16 v[128:129], v169 offset:4704
	ds_read_b64_tr_b16 v[130:131], v169 offset:7008
	s_waitcnt vmcnt(15)
	ds_write_b128 v241, v[64:67]
	s_waitcnt vmcnt(14)
	ds_write_b128 v242, v[88:91]
	s_waitcnt vmcnt(13)
	ds_write_b128 v243, v[100:103]
	s_waitcnt vmcnt(12)
	ds_write_b128 v244, v[104:107]
	v_mfma_f32_16x16x32_bf16 v[64:67], v[32:35], v[4:7], 0
	v_mfma_f32_16x16x32_bf16 v[32:35], v[32:35], v[12:15], 0
	v_mfma_f32_16x16x32_bf16 v[64:67], v[40:43], v[8:11], v[64:67]
	v_mfma_f32_16x16x32_bf16 v[88:91], v[56:59], v[4:7], 0
	v_mfma_f32_16x16x32_bf16 v[32:35], v[40:43], v[0:3], v[32:35]
	v_mfma_f32_16x16x32_bf16 v[40:43], v[56:59], v[12:15], 0
	v_add_u32_e32 v57, 0xe0, v154
	v_sub_u32_e32 v56, v57, v147
	v_add_u32_e32 v59, 1, v56
	s_nop 1
	v_cmp_gt_u32_e64 s[0:1], v59, v146
	v_cmp_gt_u32_e32 vcc, v56, v146
	s_nop 0
	v_cndmask_b32_e64 v65, v65, v246, s[0:1]
	s_nop 0
	v_cndmask_b32_e32 v64, v64, v246, vcc
	v_max_f32_e32 v58, 0xf149f2ca, v64
	v_mfma_f32_16x16x32_bf16 v[88:91], v[60:63], v[8:11], v[88:91]
	v_max_f32_e32 v58, v58, v65
	v_add_u32_e32 v59, 2, v56
	v_cmp_gt_u32_e64 s[22:23], v59, v146
	v_mfma_f32_16x16x32_bf16 v[40:43], v[60:63], v[0:3], v[40:43]
	v_add_u32_e32 v60, 3, v56
	v_cmp_gt_u32_e64 s[24:25], v60, v146
	v_cndmask_b32_e64 v66, v66, v246, s[22:23]
	v_sub_u32_e32 v57, v57, v148
	v_cndmask_b32_e64 v67, v67, v246, s[24:25]
	v_max3_f32 v58, v58, v66, v67
	v_add_u32_e32 v59, 16, v56
	v_add_u32_e32 v60, 17, v56
	v_cmp_gt_u32_e64 s[26:27], v59, v146
	v_cmp_gt_u32_e64 s[28:29], v60, v146
	v_cmp_gt_u32_e64 s[38:39], v57, v145
	v_cndmask_b32_e64 v88, v88, v246, s[26:27]
	v_cndmask_b32_e64 v89, v89, v246, s[28:29]
	v_max3_f32 v58, v58, v88, v89
	v_add_u32_e32 v59, 18, v56
	v_add_u32_e32 v56, 19, v56
	v_cmp_gt_u32_e64 s[30:31], v59, v146
	v_cmp_gt_u32_e64 s[34:35], v56, v146
	v_add_u32_e32 v60, 3, v57
	v_cndmask_b32_e64 v90, v90, v246, s[30:31]
	v_cndmask_b32_e64 v91, v91, v246, s[34:35]
	v_max3_f32 v56, v58, v90, v91
	v_add_u32_e32 v59, 1, v57
	v_cmp_gt_u32_e64 s[40:41], v59, v145
	v_cndmask_b32_e64 v32, v32, v246, s[38:39]
	v_max_f32_e32 v58, 0xf149f2ca, v32
	v_cndmask_b32_e64 v33, v33, v246, s[40:41]
	v_max_f32_e32 v58, v58, v33
	v_add_u32_e32 v59, 2, v57
	v_cmp_gt_u32_e64 s[42:43], v59, v145
	v_cmp_gt_u32_e64 s[44:45], v60, v145
	s_nop 0
	v_cndmask_b32_e64 v34, v34, v246, s[42:43]
	v_cndmask_b32_e64 v35, v35, v246, s[44:45]
	v_max3_f32 v58, v58, v34, v35
	v_add_u32_e32 v59, 16, v57
	v_add_u32_e32 v60, 17, v57
	v_cmp_gt_u32_e64 s[46:47], v59, v145
	v_cmp_gt_u32_e64 s[48:49], v60, v145
	s_nop 0
	v_cndmask_b32_e64 v40, v40, v246, s[46:47]
	v_cndmask_b32_e64 v41, v41, v246, s[48:49]
	v_max3_f32 v58, v58, v40, v41
	v_add_u32_e32 v59, 18, v57
	v_add_u32_e32 v57, 19, v57
	v_cmp_gt_u32_e64 s[50:51], v59, v145
	v_cmp_gt_u32_e64 s[52:53], v57, v145
	s_nop 0
	v_cndmask_b32_e64 v42, v42, v246, s[50:51]
	v_cndmask_b32_e64 v43, v43, v246, s[52:53]
	v_max3_f32 v57, v58, v42, v43
	v_mov_b32_e32 v58, v56
	v_mov_b32_e32 v59, v56
	s_nop 1
	v_permlane32_swap_b32_e32 v58, v59
	v_max3_f32 v56, v56, v58, v59
	v_mov_b32_e32 v58, v57
	v_mov_b32_e32 v59, v57
	s_nop 1
	v_permlane32_swap_b32_e32 v58, v59
	v_max3_f32 v57, v57, v58, v59
	v_mov_b32_e32 v58, v56
	v_mov_b32_e32 v59, v56
	s_nop 1
	v_permlane16_swap_b32_e32 v58, v59
	v_max_f32_e32 v56, v56, v58
	v_mov_b32_e32 v58, v57
	v_mov_b32_e32 v61, v57
	s_nop 1
	v_permlane16_swap_b32_e32 v58, v61
	v_max_f32_e32 v62, v57, v58
	v_max3_f32 v181, v175, v56, v59
	v_sub_f32_e32 v56, v175, v181
	v_max3_f32 v184, v177, v62, v61
	v_exp_f32_e32 v60, v56
	v_sub_f32_e32 v56, v64, v181
	v_sub_f32_e32 v32, v32, v184
	v_exp_f32_e32 v56, v56
	v_sub_f32_e32 v58, v65, v181
	v_exp_f32_e32 v32, v32
	v_sub_f32_e32 v33, v33, v184
	v_exp_f32_e32 v58, v58
	v_sub_f32_e32 v59, v66, v181
	v_exp_f32_e32 v33, v33
	v_sub_f32_e32 v34, v34, v184
	v_exp_f32_e32 v59, v59
	v_sub_f32_e32 v63, v67, v181
	v_exp_f32_e32 v34, v34
	v_sub_f32_e32 v35, v35, v184
	v_exp_f32_e32 v63, v63
	v_sub_f32_e32 v64, v88, v181
	v_exp_f32_e32 v35, v35
	v_sub_f32_e32 v40, v40, v184
	v_exp_f32_e32 v64, v64
	v_sub_f32_e32 v65, v89, v181
	v_sub_f32_e32 v61, v177, v184
	v_exp_f32_e32 v40, v40
	v_sub_f32_e32 v41, v41, v184
	v_add_f32_e32 v57, 0, v56
	v_exp_f32_e32 v65, v65
	v_sub_f32_e32 v66, v90, v181
	v_exp_f32_e32 v62, v61
	v_add_f32_e32 v61, 0, v32
	v_exp_f32_e32 v41, v41
	v_sub_f32_e32 v42, v42, v184
	v_add_f32_e32 v57, v58, v57
	v_exp_f32_e32 v66, v66
	v_sub_f32_e32 v67, v91, v181
	v_add_f32_e32 v61, v33, v61
	v_exp_f32_e32 v42, v42
	v_sub_f32_e32 v43, v43, v184
	v_add_f32_e32 v57, v59, v57
	v_exp_f32_e32 v67, v67
	v_add_f32_e32 v61, v34, v61
	v_exp_f32_e32 v43, v43
	v_add_f32_e32 v57, v63, v57
	v_add_f32_e32 v61, v35, v61
	v_add_f32_e32 v57, v64, v57
	v_add_f32_e32 v61, v40, v61
	v_add_f32_e32 v57, v65, v57
	v_add_f32_e32 v61, v41, v61
	v_add_f32_e32 v57, v66, v57
	v_add_f32_e32 v61, v42, v61
	v_add_f32_e32 v183, v67, v57
	v_cvt_pk_bf16_f32 v56, v56, v58
	v_cvt_pk_bf16_f32 v57, v59, v63
	v_cvt_pk_bf16_f32 v58, v64, v65
	v_cvt_pk_bf16_f32 v59, v66, v67
	v_add_f32_e32 v185, v43, v61
	v_cvt_pk_bf16_f32 v32, v32, v33
	v_cvt_pk_bf16_f32 v33, v34, v35
	v_cvt_pk_bf16_f32 v34, v40, v41
	v_cvt_pk_bf16_f32 v35, v42, v43
	v_pk_mul_f32 v[42:43], v[78:79], v[60:61] op_sel_hi:[1,0]
	v_pk_mul_f32 v[40:41], v[76:77], v[60:61] op_sel_hi:[1,0]
	v_fmac_f32_e32 v185, v178, v62
	s_waitcnt lgkmcnt(10)
	v_mfma_f32_16x16x32_bf16 v[100:103], v[140:143], v[56:59], v[40:43]
	v_add_u32_e32 v178, 0x100, v151
	v_fmac_f32_e32 v183, v176, v60
	v_add_u32_e32 v177, 0x100, v252
	v_pk_mul_f32 v[42:43], v[94:95], v[62:63] op_sel_hi:[1,0]
	v_pk_mul_f32 v[40:41], v[92:93], v[62:63] op_sel_hi:[1,0]
	s_nop 1
	v_mfma_f32_16x16x32_bf16 v[92:95], v[140:143], v[32:35], v[40:43]
	s_nop 2
	v_mul_f32_e64 v42, v98, v60
	v_mul_f32_e64 v43, v99, v60
	v_pk_mul_f32 v[40:41], v[96:97], v[60:61] op_sel_hi:[1,0]
	s_waitcnt lgkmcnt(8)
	s_nop 0
	v_mfma_f32_16x16x32_bf16 v[104:107], v[136:139], v[56:59], v[40:43]
	s_nop 2
	v_mul_f32_e64 v42, v110, v62
	v_mul_f32_e64 v43, v111, v62
	v_pk_mul_f32 v[40:41], v[108:109], v[62:63] op_sel_hi:[1,0]
	s_nop 1
	v_mfma_f32_16x16x32_bf16 v[108:111], v[136:139], v[32:35], v[40:43]
	s_nop 2
	v_mul_f32_e64 v42, v114, v60
	v_mul_f32_e64 v43, v115, v60
	v_pk_mul_f32 v[40:41], v[112:113], v[60:61] op_sel_hi:[1,0]
	s_waitcnt lgkmcnt(6)
	s_nop 0
	v_mfma_f32_16x16x32_bf16 v[112:115], v[132:135], v[56:59], v[40:43]
	s_nop 2
	v_mul_f32_e64 v42, v118, v62
	v_mul_f32_e64 v43, v119, v62
	v_pk_mul_f32 v[40:41], v[116:117], v[62:63] op_sel_hi:[1,0]
	s_nop 1
	v_mfma_f32_16x16x32_bf16 v[116:119], v[132:135], v[32:35], v[40:43]
	s_nop 2
	v_mul_f32_e64 v42, v122, v60
	v_mul_f32_e64 v43, v123, v60
	v_pk_mul_f32 v[40:41], v[120:121], v[60:61] op_sel_hi:[1,0]
	s_waitcnt lgkmcnt(4)
	s_nop 0
	v_mfma_f32_16x16x32_bf16 v[120:123], v[128:131], v[56:59], v[40:43]
	s_nop 2
	v_mul_f32_e64 v42, v126, v62
	v_mul_f32_e64 v43, v127, v62
	v_pk_mul_f32 v[40:41], v[124:125], v[62:63] op_sel_hi:[1,0]
	s_nop 1
	v_mfma_f32_16x16x32_bf16 v[124:127], v[128:131], v[32:35], v[40:43]
	v_med3_i32 v32, v180, 0, s75
	v_lshl_add_u32 v32, v32, 9, v152
	global_load_dwordx4 v[56:59], v32, s[98:99]
	v_med3_i32 v32, v179, 0, s75
	v_lshl_add_u32 v32, v32, 9, v152
	global_load_dwordx4 v[60:63], v32, s[98:99]
	v_med3_i32 v32, v178, 0, s75
	v_lshl_add_u32 v32, v32, 9, v152
	global_load_dwordx4 v[88:91], v32, s[98:99]
	v_med3_i32 v32, v177, 0, s75
	v_lshl_add_u32 v32, v32, 9, v152
	global_load_dwordx4 v[96:99], v32, s[98:99]
	v_or_b32_e32 v32, 0x100, v166
	v_add_u32_e32 v32, s76, v32
	v_med3_i32 v32, v32, 0, s75
	v_lshl_add_u32 v32, v32, 9, v158
	global_load_dwordx4 v[76:79], v32, s[100:101]
	global_load_dwordx4 v[64:67], v32, s[100:101] offset:64
	v_or_b32_e32 v32, 0x110, v166
	v_add_u32_e32 v32, s76, v32
	v_med3_i32 v32, v32, 0, s75
	v_lshl_add_u32 v32, v32, 9, v158
	global_load_dwordx4 v[40:43], v32, s[100:101]
	s_nop 0
	global_load_dwordx4 v[32:35], v32, s[100:101] offset:64
	ds_read_b64_tr_b16 v[142:143], v169 offset:2304
	ds_read_b64_tr_b16 v[140:141], v169
	ds_read_b64_tr_b16 v[136:137], v169 offset:32
	ds_read_b64_tr_b16 v[138:139], v169 offset:2336
	ds_read_b64_tr_b16 v[132:133], v169 offset:64
	ds_read_b64_tr_b16 v[134:135], v169 offset:2368
	ds_read_b64_tr_b16 v[128:129], v169 offset:96
	ds_read_b64_tr_b16 v[130:131], v169 offset:2400
	s_waitcnt vmcnt(15)
	ds_write_b128 v241, v[68:71] offset:4608
	s_waitcnt vmcnt(14)
	ds_write_b128 v242, v[72:75] offset:4608
	s_waitcnt vmcnt(13)
	ds_write_b128 v243, v[80:83] offset:4608
	s_waitcnt vmcnt(12)
	ds_write_b128 v244, v[84:87] offset:4608
	v_mfma_f32_16x16x32_bf16 v[68:71], v[36:39], v[4:7], 0
	v_mfma_f32_16x16x32_bf16 v[72:75], v[24:27], v[4:7], 0
	v_mfma_f32_16x16x32_bf16 v[24:27], v[24:27], v[12:15], 0
	v_mfma_f32_16x16x32_bf16 v[68:71], v[44:47], v[8:11], v[68:71]
	v_mfma_f32_16x16x32_bf16 v[72:75], v[28:31], v[8:11], v[72:75]
	v_mfma_f32_16x16x32_bf16 v[24:27], v[28:31], v[0:3], v[24:27]
	v_add_u32_e32 v29, 0x100, v154
	v_sub_u32_e32 v28, v29, v147
	v_add_u32_e32 v31, 1, v28
	v_mfma_f32_16x16x32_bf16 v[36:39], v[36:39], v[12:15], 0
	s_nop 1
	v_cmp_gt_u32_e64 s[0:1], v31, v146
	v_cmp_gt_u32_e32 vcc, v28, v146
	s_nop 0
	v_cndmask_b32_e64 v69, v69, v246, s[0:1]
	s_nop 0
	v_cndmask_b32_e32 v68, v68, v246, vcc
	v_max_f32_e32 v30, 0xf149f2ca, v68
	v_mfma_f32_16x16x32_bf16 v[36:39], v[44:47], v[0:3], v[36:39]
	v_max_f32_e32 v30, v30, v69
	v_add_u32_e32 v31, 2, v28
	v_add_u32_e32 v44, 3, v28
	v_cmp_gt_u32_e64 s[22:23], v31, v146
	v_cmp_gt_u32_e64 s[24:25], v44, v146
	v_sub_u32_e32 v29, v29, v148
	v_cndmask_b32_e64 v70, v70, v246, s[22:23]
	v_cndmask_b32_e64 v71, v71, v246, s[24:25]
	v_max3_f32 v30, v30, v70, v71
	v_add_u32_e32 v31, 16, v28
	v_add_u32_e32 v44, 17, v28
	v_cmp_gt_u32_e64 s[26:27], v31, v146
	v_cmp_gt_u32_e64 s[28:29], v44, v146
	v_cmp_gt_u32_e64 s[38:39], v29, v145
	v_cndmask_b32_e64 v72, v72, v246, s[26:27]
	v_cndmask_b32_e64 v73, v73, v246, s[28:29]
	v_max3_f32 v30, v30, v72, v73
	v_add_u32_e32 v31, 18, v28
	v_add_u32_e32 v28, 19, v28
	v_cmp_gt_u32_e64 s[30:31], v31, v146
	v_cmp_gt_u32_e64 s[34:35], v28, v146
	v_add_u32_e32 v44, 3, v29
	v_cndmask_b32_e64 v74, v74, v246, s[30:31]
	v_cndmask_b32_e64 v75, v75, v246, s[34:35]
	v_max3_f32 v28, v30, v74, v75
	v_add_u32_e32 v31, 1, v29
	v_cmp_gt_u32_e64 s[40:41], v31, v145
	v_cndmask_b32_e64 v36, v36, v246, s[38:39]
	v_max_f32_e32 v30, 0xf149f2ca, v36
	v_cndmask_b32_e64 v37, v37, v246, s[40:41]
	v_max_f32_e32 v30, v30, v37
	v_add_u32_e32 v31, 2, v29
	v_cmp_gt_u32_e64 s[42:43], v31, v145
	v_cmp_gt_u32_e64 s[44:45], v44, v145
	s_nop 0
	v_cndmask_b32_e64 v38, v38, v246, s[42:43]
	v_cndmask_b32_e64 v39, v39, v246, s[44:45]
	v_max3_f32 v30, v30, v38, v39
	v_add_u32_e32 v31, 16, v29
	v_add_u32_e32 v44, 17, v29
	v_cmp_gt_u32_e64 s[46:47], v31, v145
	v_cmp_gt_u32_e64 s[48:49], v44, v145
	s_nop 0
	v_cndmask_b32_e64 v24, v24, v246, s[46:47]
	v_cndmask_b32_e64 v25, v25, v246, s[48:49]
	v_max3_f32 v30, v30, v24, v25
	v_add_u32_e32 v31, 18, v29
	v_add_u32_e32 v29, 19, v29
	v_cmp_gt_u32_e64 s[50:51], v31, v145
	v_cmp_gt_u32_e64 s[52:53], v29, v145
	s_nop 0
	v_cndmask_b32_e64 v26, v26, v246, s[50:51]
	v_cndmask_b32_e64 v27, v27, v246, s[52:53]
	v_max3_f32 v29, v30, v26, v27
	v_mov_b32_e32 v30, v28
	v_mov_b32_e32 v31, v28
	s_nop 1
	v_permlane32_swap_b32_e32 v30, v31
	v_max3_f32 v28, v28, v30, v31
	v_mov_b32_e32 v30, v29
	v_mov_b32_e32 v31, v29
	s_nop 1
	v_permlane32_swap_b32_e32 v30, v31
	v_max3_f32 v29, v29, v30, v31
	v_mov_b32_e32 v30, v28
	v_mov_b32_e32 v31, v28
	s_nop 1
	v_permlane16_swap_b32_e32 v30, v31
	v_max_f32_e32 v28, v28, v30
	v_mov_b32_e32 v30, v29
	v_mov_b32_e32 v45, v29
	v_max3_f32 v175, v181, v28, v31
	s_nop 0
	v_permlane16_swap_b32_e32 v30, v45
	v_sub_f32_e32 v28, v181, v175
	v_exp_f32_e32 v44, v28
	v_sub_f32_e32 v28, v68, v175
	v_max_f32_e32 v46, v29, v30
	v_exp_f32_e32 v28, v28
	v_sub_f32_e32 v30, v69, v175
	v_exp_f32_e32 v30, v30
	v_sub_f32_e32 v31, v70, v175
	v_exp_f32_e32 v31, v31
	v_sub_f32_e32 v47, v71, v175
	v_max3_f32 v181, v184, v46, v45
	v_exp_f32_e32 v47, v47
	v_sub_f32_e32 v68, v72, v175
	v_sub_f32_e32 v36, v36, v181
	v_exp_f32_e32 v68, v68
	v_sub_f32_e32 v69, v73, v175
	v_exp_f32_e32 v36, v36
	v_sub_f32_e32 v37, v37, v181
	v_add_f32_e32 v29, 0, v28
	v_exp_f32_e32 v69, v69
	v_sub_f32_e32 v70, v74, v175
	v_exp_f32_e32 v37, v37
	v_sub_f32_e32 v38, v38, v181
	v_add_f32_e32 v29, v30, v29
	v_exp_f32_e32 v70, v70
	v_sub_f32_e32 v71, v75, v175
	v_exp_f32_e32 v38, v38
	v_sub_f32_e32 v39, v39, v181
	v_add_f32_e32 v29, v31, v29
	v_exp_f32_e32 v71, v71
	v_exp_f32_e32 v39, v39
	v_sub_f32_e32 v24, v24, v181
	v_add_f32_e32 v29, v47, v29
	v_sub_f32_e32 v45, v184, v181
	v_exp_f32_e32 v24, v24
	v_sub_f32_e32 v25, v25, v181
	v_add_f32_e32 v29, v68, v29
	v_exp_f32_e32 v46, v45
	v_add_f32_e32 v45, 0, v36
	v_exp_f32_e32 v25, v25
	v_add_f32_e32 v29, v69, v29
	v_add_f32_e32 v45, v37, v45
	v_add_f32_e32 v29, v70, v29
	v_add_f32_e32 v45, v38, v45
	v_add_f32_e32 v176, v71, v29
	v_cvt_pk_bf16_f32 v29, v31, v47
	v_add_f32_e32 v45, v39, v45
	v_cndmask_b32_e64 v47, v24, 0, s[46:47]
	v_add_f32_e32 v24, v47, v45
	v_cndmask_b32_e64 v45, v25, 0, s[48:49]
	v_sub_f32_e32 v25, v26, v181
	v_exp_f32_e32 v25, v25
	v_cvt_pk_bf16_f32 v28, v28, v30
	v_cvt_pk_bf16_f32 v30, v68, v69
	v_add_f32_e32 v24, v45, v24
	v_cndmask_b32_e64 v68, v25, 0, s[50:51]
	v_sub_f32_e32 v25, v27, v181
	v_exp_f32_e32 v25, v25
	v_add_f32_e32 v24, v68, v24
	v_fmac_f32_e32 v176, v183, v44
	v_cvt_pk_bf16_f32 v31, v70, v71
	v_cndmask_b32_e64 v27, v25, 0, s[52:53]
	v_add_f32_e32 v183, v27, v24
	v_cvt_pk_bf16_f32 v24, v36, v37
	v_cvt_pk_bf16_f32 v25, v38, v39
	v_pk_mul_f32 v[38:39], v[102:103], v[44:45] op_sel_hi:[1,0]
	v_pk_mul_f32 v[36:37], v[100:101], v[44:45] op_sel_hi:[1,0]
	v_cvt_pk_bf16_f32 v26, v47, v45
	v_cvt_pk_bf16_f32 v27, v68, v27
	s_waitcnt lgkmcnt(10)
	v_mfma_f32_16x16x32_bf16 v[80:83], v[140:143], v[28:31], v[36:39]
	v_fmac_f32_e32 v183, v185, v46
	v_add_u32_e32 v184, s76, v204
	v_add_u32_e32 v185, s76, v205
	v_pk_mul_f32 v[38:39], v[94:95], v[46:47] op_sel_hi:[1,0]
	v_pk_mul_f32 v[36:37], v[92:93], v[46:47] op_sel_hi:[1,0]
	s_nop 1
	v_mfma_f32_16x16x32_bf16 v[84:87], v[140:143], v[24:27], v[36:39]
	s_nop 2
	v_mul_f32_e64 v38, v106, v44
	v_mul_f32_e64 v39, v107, v44
	v_pk_mul_f32 v[36:37], v[104:105], v[44:45] op_sel_hi:[1,0]
	s_waitcnt lgkmcnt(8)
	s_nop 0
	v_mfma_f32_16x16x32_bf16 v[104:107], v[136:139], v[28:31], v[36:39]
	s_nop 2
	v_mul_f32_e64 v38, v110, v46
	v_mul_f32_e64 v39, v111, v46
	v_pk_mul_f32 v[36:37], v[108:109], v[46:47] op_sel_hi:[1,0]
	s_nop 1
	v_mfma_f32_16x16x32_bf16 v[108:111], v[136:139], v[24:27], v[36:39]
	s_nop 2
	v_mul_f32_e64 v38, v114, v44
	v_mul_f32_e64 v39, v115, v44
	v_pk_mul_f32 v[36:37], v[112:113], v[44:45] op_sel_hi:[1,0]
	s_waitcnt lgkmcnt(6)
	s_nop 0
	v_mfma_f32_16x16x32_bf16 v[112:115], v[132:135], v[28:31], v[36:39]
	s_nop 2
	v_mul_f32_e64 v38, v118, v46
	v_mul_f32_e64 v39, v119, v46
	v_pk_mul_f32 v[36:37], v[116:117], v[46:47] op_sel_hi:[1,0]
	s_nop 1
	v_mfma_f32_16x16x32_bf16 v[116:119], v[132:135], v[24:27], v[36:39]
	s_nop 2
	v_mul_f32_e64 v38, v122, v44
	v_mul_f32_e64 v39, v123, v44
	v_pk_mul_f32 v[36:37], v[120:121], v[44:45] op_sel_hi:[1,0]
	s_waitcnt lgkmcnt(4)
	s_nop 0
	v_mfma_f32_16x16x32_bf16 v[120:123], v[128:131], v[28:31], v[36:39]
	v_mul_f32_e64 v30, v126, v46
	v_mul_f32_e64 v31, v127, v46
	v_pk_mul_f32 v[28:29], v[124:125], v[46:47] op_sel_hi:[1,0]
	s_nop 1
	v_mfma_f32_16x16x32_bf16 v[124:127], v[128:131], v[24:27], v[28:31]
	v_add_u32_e32 v24, 0x120, v149
	v_med3_i32 v24, v24, 0, s75
	v_lshl_add_u32 v24, v24, 9, v152
	global_load_dwordx4 v[28:31], v24, s[98:99]
	v_add_u32_e32 v24, 0x120, v150
	v_med3_i32 v24, v24, 0, s75
	v_lshl_add_u32 v24, v24, 9, v152
	global_load_dwordx4 v[44:47], v24, s[98:99]
	v_add_u32_e32 v24, 0x120, v151
	v_med3_i32 v24, v24, 0, s75
	v_lshl_add_u32 v24, v24, 9, v152
	global_load_dwordx4 v[92:95], v24, s[98:99]
	v_add_u32_e32 v24, 0x120, v252
	v_med3_i32 v24, v24, 0, s75
	v_lshl_add_u32 v24, v24, 9, v152
	global_load_dwordx4 v[100:103], v24, s[98:99]
	v_or_b32_e32 v24, 0x120, v166
	v_add_u32_e32 v24, s76, v24
	v_med3_i32 v24, v24, 0, s75
	v_lshl_add_u32 v24, v24, 9, v158
	global_load_dwordx4 v[72:75], v24, s[100:101]
	global_load_dwordx4 v[68:71], v24, s[100:101] offset:64
	v_or_b32_e32 v24, 0x130, v166
	v_add_u32_e32 v24, s76, v24
	v_med3_i32 v24, v24, 0, s75
	v_lshl_add_u32 v24, v24, 9, v158
	global_load_dwordx4 v[36:39], v24, s[100:101]
	s_nop 0
	global_load_dwordx4 v[24:27], v24, s[100:101] offset:64
	ds_read_b64_tr_b16 v[142:143], v169 offset:6912
	ds_read_b64_tr_b16 v[140:141], v169 offset:4608
	ds_read_b64_tr_b16 v[136:137], v169 offset:4640
	ds_read_b64_tr_b16 v[138:139], v169 offset:6944
	ds_read_b64_tr_b16 v[132:133], v169 offset:4672
	ds_read_b64_tr_b16 v[134:135], v169 offset:6976
	ds_read_b64_tr_b16 v[128:129], v169 offset:4704
	ds_read_b64_tr_b16 v[130:131], v169 offset:7008
	s_waitcnt vmcnt(15)
	ds_write_b128 v241, v[56:59]
	s_waitcnt vmcnt(14)
	ds_write_b128 v242, v[60:63]
	s_waitcnt vmcnt(13)
	ds_write_b128 v243, v[88:91]
	s_waitcnt vmcnt(12)
	ds_write_b128 v244, v[96:99]
	v_mfma_f32_16x16x32_bf16 v[56:59], v[48:51], v[4:7], 0
	v_mfma_f32_16x16x32_bf16 v[60:63], v[16:19], v[4:7], 0
	v_mfma_f32_16x16x32_bf16 v[16:19], v[16:19], v[12:15], 0
	v_mfma_f32_16x16x32_bf16 v[56:59], v[52:55], v[8:11], v[56:59]
	v_mfma_f32_16x16x32_bf16 v[60:63], v[20:23], v[8:11], v[60:63]
	v_mfma_f32_16x16x32_bf16 v[16:19], v[20:23], v[0:3], v[16:19]
	v_sub_u32_e32 v20, v195, v147
	v_add_u32_e32 v23, 1, v20
	s_nop 3
	v_mfma_f32_16x16x32_bf16 v[48:51], v[48:51], v[12:15], 0
	v_cmp_gt_u32_e64 s[0:1], v23, v146
	v_cmp_gt_u32_e32 vcc, v20, v146
	s_nop 0
	v_cndmask_b32_e64 v57, v57, v246, s[0:1]
	s_nop 0
	v_cndmask_b32_e32 v56, v56, v246, vcc
	v_max_f32_e32 v22, 0xf149f2ca, v56
	v_mfma_f32_16x16x32_bf16 v[48:51], v[52:55], v[0:3], v[48:51]
	v_max_f32_e32 v22, v22, v57
	v_add_u32_e32 v23, 2, v20
	v_add_u32_e32 v52, 3, v20
	v_cmp_gt_u32_e64 s[22:23], v23, v146
	v_cmp_gt_u32_e64 s[24:25], v52, v146
	v_sub_u32_e32 v21, v195, v148
	v_cndmask_b32_e64 v58, v58, v246, s[22:23]
	v_cndmask_b32_e64 v59, v59, v246, s[24:25]
	v_max3_f32 v22, v22, v58, v59
	v_add_u32_e32 v23, 16, v20
	v_add_u32_e32 v52, 17, v20
	v_cmp_gt_u32_e64 s[26:27], v23, v146
	v_cmp_gt_u32_e64 s[28:29], v52, v146
	v_cmp_gt_u32_e64 s[38:39], v21, v145
	v_cndmask_b32_e64 v60, v60, v246, s[26:27]
	v_cndmask_b32_e64 v61, v61, v246, s[28:29]
	v_max3_f32 v22, v22, v60, v61
	v_add_u32_e32 v23, 18, v20
	v_add_u32_e32 v20, 19, v20
	v_cmp_gt_u32_e64 s[30:31], v23, v146
	v_cmp_gt_u32_e64 s[34:35], v20, v146
	v_add_u32_e32 v52, 3, v21
	v_cndmask_b32_e64 v62, v62, v246, s[30:31]
	v_cndmask_b32_e64 v63, v63, v246, s[34:35]
	v_max3_f32 v20, v22, v62, v63
	v_add_u32_e32 v23, 1, v21
	v_cmp_gt_u32_e64 s[40:41], v23, v145
	v_cndmask_b32_e64 v48, v48, v246, s[38:39]
	v_max_f32_e32 v22, 0xf149f2ca, v48
	v_cndmask_b32_e64 v49, v49, v246, s[40:41]
	v_max_f32_e32 v22, v22, v49
	v_add_u32_e32 v23, 2, v21
	v_cmp_gt_u32_e64 s[42:43], v23, v145
	v_cmp_gt_u32_e64 s[44:45], v52, v145
	s_nop 0
	v_cndmask_b32_e64 v50, v50, v246, s[42:43]
	v_cndmask_b32_e64 v51, v51, v246, s[44:45]
	v_max3_f32 v22, v22, v50, v51
	v_add_u32_e32 v23, 16, v21
	v_add_u32_e32 v52, 17, v21
	v_cmp_gt_u32_e64 s[46:47], v23, v145
	v_cmp_gt_u32_e64 s[48:49], v52, v145
	s_nop 0
	v_cndmask_b32_e64 v16, v16, v246, s[46:47]
	v_cndmask_b32_e64 v17, v17, v246, s[48:49]
	v_max3_f32 v22, v22, v16, v17
	v_add_u32_e32 v23, 18, v21
	v_add_u32_e32 v21, 19, v21
	v_cmp_gt_u32_e64 s[50:51], v23, v145
	v_cmp_gt_u32_e64 s[52:53], v21, v145
	s_nop 0
	v_cndmask_b32_e64 v18, v18, v246, s[50:51]
	v_cndmask_b32_e64 v19, v19, v246, s[52:53]
	v_max3_f32 v21, v22, v18, v19
	v_mov_b32_e32 v22, v20
	v_mov_b32_e32 v23, v20
	s_nop 1
	v_permlane32_swap_b32_e32 v22, v23
	v_max3_f32 v20, v20, v22, v23
	v_mov_b32_e32 v22, v21
	v_mov_b32_e32 v23, v21
	s_nop 1
	v_permlane32_swap_b32_e32 v22, v23
	v_max3_f32 v21, v21, v22, v23
	v_mov_b32_e32 v22, v20
	v_mov_b32_e32 v23, v20
	s_nop 1
	v_permlane16_swap_b32_e32 v22, v23
	v_max_f32_e32 v20, v20, v22
	v_max3_f32 v149, v175, v20, v23
	v_sub_f32_e32 v20, v175, v149
	v_exp_f32_e32 v88, v20
	v_sub_f32_e32 v20, v56, v149
	v_sub_f32_e32 v56, v61, v149
	v_exp_f32_e32 v56, v56
	v_exp_f32_e32 v20, v20
	v_sub_f32_e32 v23, v57, v149
	v_exp_f32_e32 v23, v23
	v_sub_f32_e32 v53, v58, v149
	v_cndmask_b32_e64 v58, v56, 0, s[28:29]
	v_sub_f32_e32 v56, v62, v149
	v_mov_b32_e32 v22, v21
	v_mov_b32_e32 v52, v21
	v_exp_f32_e32 v53, v53
	v_sub_f32_e32 v54, v59, v149
	v_exp_f32_e32 v56, v56
	v_permlane16_swap_b32_e32 v22, v52
	v_exp_f32_e32 v54, v54
	v_sub_f32_e32 v55, v60, v149
	v_exp_f32_e32 v55, v55
	v_max_f32_e32 v21, v21, v22
	v_add_f32_e32 v22, 0, v20
	v_add_f32_e32 v22, v23, v22
	v_cndmask_b32_e64 v59, v56, 0, s[30:31]
	v_sub_f32_e32 v56, v63, v149
	v_add_f32_e32 v22, v53, v22
	v_exp_f32_e32 v56, v56
	v_add_f32_e32 v22, v54, v22
	v_add_f32_e32 v22, v55, v22
	v_add_f32_e32 v22, v58, v22
	v_max3_f32 v151, v181, v21, v52
	v_add_f32_e32 v22, v59, v22
	v_cndmask_b32_e64 v60, v56, 0, s[34:35]
	v_cvt_pk_bf16_f32 v56, v20, v23
	v_sub_f32_e32 v20, v181, v151
	v_add_f32_e32 v150, v60, v22
	v_cvt_pk_bf16_f32 v59, v59, v60
	v_exp_f32_e32 v60, v20
	v_sub_f32_e32 v20, v48, v151
	v_exp_f32_e32 v20, v20
	v_sub_f32_e32 v22, v49, v151
	v_exp_f32_e32 v22, v22
	v_sub_f32_e32 v23, v50, v151
	v_exp_f32_e32 v23, v23
	v_sub_f32_e32 v48, v51, v151
	v_exp_f32_e32 v48, v48
	v_sub_f32_e32 v16, v16, v151
	v_exp_f32_e32 v16, v16
	v_sub_f32_e32 v17, v17, v151
	v_add_f32_e32 v21, 0, v20
	v_exp_f32_e32 v17, v17
	v_add_f32_e32 v21, v22, v21
	v_add_f32_e32 v21, v23, v21
	v_add_f32_e32 v21, v48, v21
	v_cndmask_b32_e64 v49, v16, 0, s[46:47]
	v_add_f32_e32 v16, v49, v21
	v_cndmask_b32_e64 v21, v17, 0, s[48:49]
	v_sub_f32_e32 v17, v18, v151
	v_exp_f32_e32 v17, v17
	v_add_f32_e32 v16, v21, v16
	v_cvt_pk_bf16_f32 v18, v49, v21
	v_cvt_pk_bf16_f32 v57, v53, v54
	v_cndmask_b32_e64 v50, v17, 0, s[50:51]
	v_sub_f32_e32 v17, v19, v151
	v_exp_f32_e32 v17, v17
	v_add_f32_e32 v16, v50, v16
	v_cvt_pk_bf16_f32 v58, v55, v58
	v_fmac_f32_e32 v150, v176, v88
	v_cndmask_b32_e64 v19, v17, 0, s[52:53]
	v_add_f32_e32 v175, v19, v16
	v_cvt_pk_bf16_f32 v16, v20, v22
	v_cvt_pk_bf16_f32 v17, v23, v48
	v_cvt_pk_bf16_f32 v19, v50, v19
	v_pk_mul_f32 v[50:51], v[86:87], v[60:61] op_sel_hi:[1,0]
	v_pk_mul_f32 v[48:49], v[84:85], v[60:61] op_sel_hi:[1,0]
	v_pk_mul_f32 v[22:23], v[82:83], v[88:89] op_sel_hi:[1,0]
	v_pk_mul_f32 v[20:21], v[80:81], v[88:89] op_sel_hi:[1,0]
	s_waitcnt lgkmcnt(10)
	v_mfma_f32_16x16x32_bf16 v[52:55], v[140:143], v[16:19], v[48:51]
	v_fmac_f32_e32 v175, v183, v60
	s_nop 1
	v_pk_mul_f32 v[50:51], v[106:107], v[88:89] op_sel_hi:[1,0]
	v_pk_mul_f32 v[48:49], v[104:105], v[88:89] op_sel_hi:[1,0]
	v_mfma_f32_16x16x32_bf16 v[20:23], v[140:143], v[56:59], v[20:23]
	s_waitcnt lgkmcnt(8)
	v_mfma_f32_16x16x32_bf16 v[104:107], v[136:139], v[56:59], v[48:51]
	s_nop 2
	v_mul_f32_e64 v50, v110, v60
	v_mul_f32_e64 v51, v111, v60
	v_pk_mul_f32 v[48:49], v[108:109], v[60:61] op_sel_hi:[1,0]
	s_nop 1
	v_mfma_f32_16x16x32_bf16 v[108:111], v[136:139], v[16:19], v[48:51]
	s_nop 2
	v_mul_f32_e64 v50, v114, v88
	v_mul_f32_e64 v51, v115, v88
	v_pk_mul_f32 v[48:49], v[112:113], v[88:89] op_sel_hi:[1,0]
	s_waitcnt lgkmcnt(6)
	s_nop 0
	v_mfma_f32_16x16x32_bf16 v[112:115], v[132:135], v[56:59], v[48:51]
	s_nop 2
	v_mul_f32_e64 v50, v118, v60
	v_mul_f32_e64 v51, v119, v60
	v_pk_mul_f32 v[48:49], v[116:117], v[60:61] op_sel_hi:[1,0]
	s_nop 1
	v_mfma_f32_16x16x32_bf16 v[116:119], v[132:135], v[16:19], v[48:51]
	s_nop 2
	v_mul_f32_e64 v50, v122, v88
	v_mul_f32_e64 v51, v123, v88
	v_pk_mul_f32 v[48:49], v[120:121], v[88:89] op_sel_hi:[1,0]
	s_waitcnt lgkmcnt(4)
	s_nop 0
	v_mfma_f32_16x16x32_bf16 v[120:123], v[128:131], v[56:59], v[48:51]
	v_add_u32_e32 v56, 0xffffff00, v206
	v_add_u32_e32 v56, s76, v56
	s_nop 0
	v_pk_mul_f32 v[50:51], v[126:127], v[60:61] op_sel_hi:[1,0]
	v_pk_mul_f32 v[48:49], v[124:125], v[60:61] op_sel_hi:[1,0]
	s_nop 1
	v_mfma_f32_16x16x32_bf16 v[124:127], v[128:131], v[16:19], v[48:51]
	v_add_u32_e32 v16, 0xffffff00, v204
	v_add_u32_e32 v16, s76, v16
	s_nop 0
	v_add_u32_e32 v48, 0xffffff00, v205
	v_add_u32_e32 v48, s76, v48
	v_med3_i32 v16, v16, 0, s75
	v_med3_i32 v48, v48, 0, s75
	v_med3_i32 v56, v56, 0, s75
	v_lshl_add_u32 v56, v56, 9, v152
	global_load_dwordx4 v[88:91], v56, s[98:99]
	v_add_u32_e32 v56, 0xffffff00, v207
	v_add_u32_e32 v56, s76, v56
	v_med3_i32 v56, v56, 0, s75
	v_lshl_add_u32 v56, v56, 9, v152
	global_load_dwordx4 v[96:99], v56, s[98:99]
	v_add_u32_e32 v56, s76, v208
	v_lshl_add_u32 v16, v16, 9, v152
	v_lshl_add_u32 v48, v48, 9, v152
	v_med3_i32 v56, v56, 0, s75
	v_lshl_add_u32 v56, v56, 9, v158
	global_load_dwordx4 v[16:19], v16, s[98:99]
	s_nop 0
	global_load_dwordx4 v[48:51], v48, s[98:99]
	s_nop 0
	global_load_dwordx4 v[84:87], v56, s[100:101]
	global_load_dwordx4 v[80:83], v56, s[100:101] offset:64
	v_or_b32_e32 v56, 0xffffff40, v209
	v_add_u32_e32 v56, s76, v56
	v_med3_i32 v56, v56, 0, s75
	v_lshl_add_u32 v56, v56, 9, v158
	global_load_dwordx4 v[60:63], v56, s[100:101]
	s_nop 0
	global_load_dwordx4 v[56:59], v56, s[100:101] offset:64
	ds_read_b64_tr_b16 v[142:143], v169 offset:2304
	ds_read_b64_tr_b16 v[140:141], v169
	ds_read_b64_tr_b16 v[136:137], v169 offset:32
	ds_read_b64_tr_b16 v[138:139], v169 offset:2336
	ds_read_b64_tr_b16 v[132:133], v169 offset:64
	ds_read_b64_tr_b16 v[134:135], v169 offset:2368
	ds_read_b64_tr_b16 v[128:129], v169 offset:96
	ds_read_b64_tr_b16 v[130:131], v169 offset:2400
	s_waitcnt vmcnt(15)
	ds_write_b128 v241, v[28:31] offset:4608
	s_waitcnt vmcnt(14)
	ds_write_b128 v242, v[44:47] offset:4608
	s_waitcnt vmcnt(13)
	ds_write_b128 v243, v[92:95] offset:4608
	s_waitcnt vmcnt(12)
	ds_write_b128 v244, v[100:103] offset:4608
	v_mfma_f32_16x16x32_bf16 v[28:31], v[76:79], v[4:7], 0
	v_mfma_f32_16x16x32_bf16 v[44:47], v[40:43], v[4:7], 0
	v_mfma_f32_16x16x32_bf16 v[40:43], v[40:43], v[12:15], 0
	v_mfma_f32_16x16x32_bf16 v[28:31], v[64:67], v[8:11], v[28:31]
	v_mfma_f32_16x16x32_bf16 v[44:47], v[32:35], v[8:11], v[44:47]
	v_mfma_f32_16x16x32_bf16 v[32:35], v[32:35], v[0:3], v[40:43]
	s_nop 4
	v_sub_u32_e32 v40, v210, v147
	v_mfma_f32_16x16x32_bf16 v[76:79], v[76:79], v[12:15], 0
	v_add_u32_e32 v43, 1, v40
	v_cmp_gt_u32_e64 s[0:1], v43, v146
	v_cmp_gt_u32_e32 vcc, v40, v146
	s_nop 0
	v_cndmask_b32_e64 v29, v29, v246, s[0:1]
	s_nop 0
	v_cndmask_b32_e32 v28, v28, v246, vcc
	v_max_f32_e32 v42, 0xf149f2ca, v28
	v_mfma_f32_16x16x32_bf16 v[64:67], v[64:67], v[0:3], v[76:79]
	v_max_f32_e32 v42, v42, v29
	v_add_u32_e32 v43, 2, v40
	v_cmp_gt_u32_e64 s[22:23], v43, v146
	v_add_u32_e32 v76, 3, v40
	v_cmp_gt_u32_e64 s[24:25], v76, v146
	v_cndmask_b32_e64 v30, v30, v246, s[22:23]
	v_sub_u32_e32 v41, v210, v148
	v_cndmask_b32_e64 v31, v31, v246, s[24:25]
	v_max3_f32 v42, v42, v30, v31
	v_add_u32_e32 v43, 16, v40
	v_add_u32_e32 v76, 17, v40
	v_cmp_gt_u32_e64 s[26:27], v43, v146
	v_cmp_gt_u32_e64 s[28:29], v76, v146
	v_cmp_gt_u32_e64 s[38:39], v41, v145
	v_cndmask_b32_e64 v44, v44, v246, s[26:27]
	v_cndmask_b32_e64 v45, v45, v246, s[28:29]
	v_max3_f32 v42, v42, v44, v45
	v_add_u32_e32 v43, 18, v40
	v_add_u32_e32 v40, 19, v40
	v_cmp_gt_u32_e64 s[30:31], v43, v146
	v_cmp_gt_u32_e64 s[34:35], v40, v146
	v_add_u32_e32 v76, 3, v41
	v_cndmask_b32_e64 v46, v46, v246, s[30:31]
	v_cndmask_b32_e64 v47, v47, v246, s[34:35]
	v_max3_f32 v40, v42, v46, v47
	v_add_u32_e32 v43, 1, v41
	v_cmp_gt_u32_e64 s[40:41], v43, v145
	v_cndmask_b32_e64 v64, v64, v246, s[38:39]
	v_max_f32_e32 v42, 0xf149f2ca, v64
	v_cndmask_b32_e64 v65, v65, v246, s[40:41]
	v_max_f32_e32 v42, v42, v65
	v_add_u32_e32 v43, 2, v41
	v_cmp_gt_u32_e64 s[42:43], v43, v145
	v_cmp_gt_u32_e64 s[44:45], v76, v145
	s_nop 0
	v_cndmask_b32_e64 v66, v66, v246, s[42:43]
	v_cndmask_b32_e64 v67, v67, v246, s[44:45]
	v_max3_f32 v42, v42, v66, v67
	v_add_u32_e32 v43, 16, v41
	v_add_u32_e32 v76, 17, v41
	v_cmp_gt_u32_e64 s[46:47], v43, v145
	v_cmp_gt_u32_e64 s[48:49], v76, v145
	s_nop 0
	v_cndmask_b32_e64 v32, v32, v246, s[46:47]
	v_cndmask_b32_e64 v33, v33, v246, s[48:49]
	v_max3_f32 v42, v42, v32, v33
	v_add_u32_e32 v43, 18, v41
	v_add_u32_e32 v41, 19, v41
	v_cmp_gt_u32_e64 s[50:51], v43, v145
	v_cmp_gt_u32_e64 s[52:53], v41, v145
	s_nop 0
	v_cndmask_b32_e64 v34, v34, v246, s[50:51]
	v_cndmask_b32_e64 v35, v35, v246, s[52:53]
	v_max3_f32 v41, v42, v34, v35
	v_mov_b32_e32 v42, v40
	v_mov_b32_e32 v43, v40
	s_nop 1
	v_permlane32_swap_b32_e32 v42, v43
	v_max3_f32 v40, v40, v42, v43
	v_mov_b32_e32 v42, v41
	v_mov_b32_e32 v43, v41
	s_nop 1
	v_permlane32_swap_b32_e32 v42, v43
	v_max3_f32 v41, v41, v42, v43
	v_mov_b32_e32 v42, v40
	v_mov_b32_e32 v43, v40
	s_nop 1
	v_permlane16_swap_b32_e32 v42, v43
	v_max_f32_e32 v40, v40, v42
	v_max3_f32 v176, v149, v40, v43
	v_sub_f32_e32 v28, v28, v176
	v_mov_b32_e32 v42, v41
	v_mov_b32_e32 v77, v41
	v_exp_f32_e32 v28, v28
	v_sub_f32_e32 v29, v29, v176
	v_permlane16_swap_b32_e32 v42, v77
	v_exp_f32_e32 v29, v29
	v_sub_f32_e32 v30, v30, v176
	v_exp_f32_e32 v30, v30
	v_sub_f32_e32 v31, v31, v176
	v_max_f32_e32 v41, v41, v42
	v_exp_f32_e32 v31, v31
	v_sub_f32_e32 v42, v44, v176
	v_sub_f32_e32 v40, v149, v176
	v_exp_f32_e32 v42, v42
	v_sub_f32_e32 v43, v45, v176
	v_exp_f32_e32 v76, v40
	v_add_f32_e32 v40, 0, v28
	v_exp_f32_e32 v43, v43
	v_sub_f32_e32 v44, v46, v176
	v_add_f32_e32 v40, v29, v40
	v_exp_f32_e32 v44, v44
	v_sub_f32_e32 v45, v47, v176
	v_add_f32_e32 v40, v30, v40
	v_exp_f32_e32 v45, v45
	v_add_f32_e32 v40, v31, v40
	v_add_f32_e32 v40, v42, v40
	v_add_f32_e32 v40, v43, v40
	v_add_f32_e32 v40, v44, v40
	v_add_f32_e32 v149, v45, v40
	v_fmac_f32_e32 v149, v150, v76
	v_max3_f32 v150, v151, v41, v77
	v_sub_f32_e32 v40, v151, v150
	v_cvt_pk_bf16_f32 v28, v28, v29
	v_cvt_pk_bf16_f32 v29, v30, v31
	v_cvt_pk_bf16_f32 v31, v44, v45
	v_exp_f32_e32 v44, v40
	v_sub_f32_e32 v40, v64, v150
	v_cvt_pk_bf16_f32 v30, v42, v43
	v_exp_f32_e32 v40, v40
	v_sub_f32_e32 v42, v65, v150
	v_exp_f32_e32 v42, v42
	v_sub_f32_e32 v43, v66, v150
	v_exp_f32_e32 v43, v43
	v_sub_f32_e32 v45, v67, v150
	v_exp_f32_e32 v45, v45
	v_sub_f32_e32 v32, v32, v150
	v_exp_f32_e32 v32, v32
	v_sub_f32_e32 v33, v33, v150
	v_add_f32_e32 v41, 0, v40
	v_exp_f32_e32 v33, v33
	v_add_f32_e32 v41, v42, v41
	v_add_f32_e32 v41, v43, v41
	v_add_f32_e32 v41, v45, v41
	v_cndmask_b32_e64 v46, v32, 0, s[46:47]
	v_add_f32_e32 v32, v46, v41
	v_cndmask_b32_e64 v41, v33, 0, s[48:49]
	v_sub_f32_e32 v33, v34, v150
	v_exp_f32_e32 v33, v33
	v_add_f32_e32 v32, v41, v32
	v_pk_mul_f32 v[22:23], v[22:23], v[76:77] op_sel_hi:[1,0]
	v_pk_mul_f32 v[20:21], v[20:21], v[76:77] op_sel_hi:[1,0]
	v_cndmask_b32_e64 v47, v33, 0, s[50:51]
	v_sub_f32_e32 v33, v35, v150
	v_exp_f32_e32 v33, v33
	v_add_f32_e32 v32, v47, v32
	v_cvt_pk_bf16_f32 v34, v46, v41
	v_cndmask_b32_e64 v35, v33, 0, s[52:53]
	v_add_f32_e32 v151, v35, v32
	v_cvt_pk_bf16_f32 v32, v40, v42
	v_cvt_pk_bf16_f32 v33, v43, v45
	v_cvt_pk_bf16_f32 v35, v47, v35
	s_waitcnt lgkmcnt(10)
	v_mfma_f32_16x16x32_bf16 v[40:43], v[140:143], v[28:31], v[20:23]
	v_fmac_f32_e32 v151, v175, v44
	s_nop 1
	v_pk_mul_f32 v[22:23], v[54:55], v[44:45] op_sel_hi:[1,0]
	v_pk_mul_f32 v[20:21], v[52:53], v[44:45] op_sel_hi:[1,0]
	s_nop 1
	v_mfma_f32_16x16x32_bf16 v[92:95], v[140:143], v[32:35], v[20:23]
	s_nop 2
	v_mul_f32_e64 v22, v106, v76
	v_mul_f32_e64 v23, v107, v76
	v_pk_mul_f32 v[20:21], v[104:105], v[76:77] op_sel_hi:[1,0]
	s_waitcnt lgkmcnt(8)
	s_nop 0
	v_mfma_f32_16x16x32_bf16 v[104:107], v[136:139], v[28:31], v[20:23]
	s_nop 2
	v_mul_f32_e64 v22, v110, v44
	v_mul_f32_e64 v23, v111, v44
	v_pk_mul_f32 v[20:21], v[108:109], v[44:45] op_sel_hi:[1,0]
	s_nop 1
	v_mfma_f32_16x16x32_bf16 v[108:111], v[136:139], v[32:35], v[20:23]
	s_nop 2
	v_mul_f32_e64 v22, v114, v76
	v_mul_f32_e64 v23, v115, v76
	v_pk_mul_f32 v[20:21], v[112:113], v[76:77] op_sel_hi:[1,0]
	s_waitcnt lgkmcnt(6)
	s_nop 0
	v_mfma_f32_16x16x32_bf16 v[112:115], v[132:135], v[28:31], v[20:23]
	s_nop 2
	v_mul_f32_e64 v22, v118, v44
	v_mul_f32_e64 v23, v119, v44
	v_pk_mul_f32 v[20:21], v[116:117], v[44:45] op_sel_hi:[1,0]
	s_nop 1
	v_mfma_f32_16x16x32_bf16 v[116:119], v[132:135], v[32:35], v[20:23]
	s_nop 2
	v_mul_f32_e64 v22, v122, v76
	v_mul_f32_e64 v23, v123, v76
	v_pk_mul_f32 v[20:21], v[120:121], v[76:77] op_sel_hi:[1,0]
	s_waitcnt lgkmcnt(4)
	s_nop 0
	v_mfma_f32_16x16x32_bf16 v[120:123], v[128:131], v[28:31], v[20:23]
	s_nop 2
	v_mul_f32_e64 v22, v126, v44
	v_mul_f32_e64 v23, v127, v44
	v_pk_mul_f32 v[20:21], v[124:125], v[44:45] op_sel_hi:[1,0]
	s_nop 1
	v_mfma_f32_16x16x32_bf16 v[124:127], v[128:131], v[32:35], v[20:23]
	s_nop 2
	v_add_u32_e32 v20, 0xffffff80, v204
	v_add_u32_e32 v20, s76, v20
	v_med3_i32 v20, v20, 0, s75
	v_lshl_add_u32 v20, v20, 9, v152
	global_load_dwordx4 v[32:35], v20, s[98:99]
	v_add_u32_e32 v20, 0xffffff80, v205
	v_add_u32_e32 v20, s76, v20
	v_med3_i32 v20, v20, 0, s75
	v_lshl_add_u32 v20, v20, 9, v152
	global_load_dwordx4 v[64:67], v20, s[98:99]
	v_add_u32_e32 v20, 0xffffff80, v206
	v_add_u32_e32 v20, s76, v20
	v_med3_i32 v20, v20, 0, s75
	v_lshl_add_u32 v20, v20, 9, v152
	global_load_dwordx4 v[76:79], v20, s[98:99]
	v_add_u32_e32 v20, 0xffffff80, v207
	v_add_u32_e32 v20, s76, v20
	v_med3_i32 v20, v20, 0, s75
	v_lshl_add_u32 v20, v20, 9, v152
	global_load_dwordx4 v[100:103], v20, s[98:99]
	v_or_b32_e32 v20, 0xffffff80, v209
	v_add_u32_e32 v20, s76, v20
	v_med3_i32 v20, v20, 0, s75
	v_lshl_add_u32 v20, v20, 9, v158
	global_load_dwordx4 v[52:55], v20, s[100:101]
	global_load_dwordx4 v[44:47], v20, s[100:101] offset:64
	v_add_u32_e32 v20, s76, v211
	v_med3_i32 v20, v20, 0, s75
	v_lshl_add_u32 v20, v20, 9, v158
	global_load_dwordx4 v[28:31], v20, s[100:101]
	s_nop 0
	global_load_dwordx4 v[20:23], v20, s[100:101] offset:64
	ds_read_b64_tr_b16 v[142:143], v169 offset:6912
	ds_read_b64_tr_b16 v[140:141], v169 offset:4608
	ds_read_b64_tr_b16 v[136:137], v169 offset:4640
	ds_read_b64_tr_b16 v[138:139], v169 offset:6944
	ds_read_b64_tr_b16 v[132:133], v169 offset:4672
	ds_read_b64_tr_b16 v[134:135], v169 offset:6976
	ds_read_b64_tr_b16 v[128:129], v169 offset:4704
	ds_read_b64_tr_b16 v[130:131], v169 offset:7008
	s_waitcnt vmcnt(13)
	ds_write_b128 v241, v[16:19]
	s_waitcnt vmcnt(12)
	ds_write_b128 v242, v[48:51]
	ds_write_b128 v243, v[88:91]
	ds_write_b128 v244, v[96:99]
	v_mfma_f32_16x16x32_bf16 v[16:19], v[72:75], v[4:7], 0
	v_mfma_f32_16x16x32_bf16 v[48:51], v[36:39], v[4:7], 0
	v_mfma_f32_16x16x32_bf16 v[36:39], v[36:39], v[12:15], 0
	v_mfma_f32_16x16x32_bf16 v[16:19], v[68:71], v[8:11], v[16:19]
	v_mfma_f32_16x16x32_bf16 v[48:51], v[24:27], v[8:11], v[48:51]
	v_mfma_f32_16x16x32_bf16 v[24:27], v[24:27], v[0:3], v[36:39]
	s_nop 4
	v_sub_u32_e32 v36, v212, v147
	v_mfma_f32_16x16x32_bf16 v[72:75], v[72:75], v[12:15], 0
	v_add_u32_e32 v39, 1, v36
	v_cmp_gt_u32_e64 s[0:1], v39, v146
	v_cmp_gt_u32_e32 vcc, v36, v146
	s_nop 0
	v_cndmask_b32_e64 v17, v17, v246, s[0:1]
	s_nop 0
	v_cndmask_b32_e32 v16, v16, v246, vcc
	v_max_f32_e32 v38, 0xf149f2ca, v16
	v_mfma_f32_16x16x32_bf16 v[68:71], v[68:71], v[0:3], v[72:75]
	v_max_f32_e32 v38, v38, v17
	v_add_u32_e32 v39, 2, v36
	v_cmp_gt_u32_e64 s[22:23], v39, v146
	v_add_u32_e32 v72, 3, v36
	v_cmp_gt_u32_e64 s[24:25], v72, v146
	v_cndmask_b32_e64 v18, v18, v246, s[22:23]
	v_sub_u32_e32 v37, v212, v148
	v_cndmask_b32_e64 v19, v19, v246, s[24:25]
	v_max3_f32 v38, v38, v18, v19
	v_add_u32_e32 v39, 16, v36
	v_add_u32_e32 v72, 17, v36
	v_cmp_gt_u32_e64 s[26:27], v39, v146
	v_cmp_gt_u32_e64 s[28:29], v72, v146
	v_cmp_gt_u32_e64 s[38:39], v37, v145
	v_cndmask_b32_e64 v48, v48, v246, s[26:27]
	v_cndmask_b32_e64 v49, v49, v246, s[28:29]
	v_max3_f32 v38, v38, v48, v49
	v_add_u32_e32 v39, 18, v36
	v_add_u32_e32 v36, 19, v36
	v_cmp_gt_u32_e64 s[30:31], v39, v146
	v_cmp_gt_u32_e64 s[34:35], v36, v146
	v_add_u32_e32 v72, 3, v37
	v_cndmask_b32_e64 v50, v50, v246, s[30:31]
	v_cndmask_b32_e64 v51, v51, v246, s[34:35]
	v_max3_f32 v36, v38, v50, v51
	v_add_u32_e32 v39, 1, v37
	v_cmp_gt_u32_e64 s[40:41], v39, v145
	v_cndmask_b32_e64 v68, v68, v246, s[38:39]
	v_max_f32_e32 v38, 0xf149f2ca, v68
	v_cndmask_b32_e64 v69, v69, v246, s[40:41]
	v_max_f32_e32 v38, v38, v69
	v_add_u32_e32 v39, 2, v37
	v_cmp_gt_u32_e64 s[42:43], v39, v145
	v_cmp_gt_u32_e64 s[44:45], v72, v145
	s_nop 0
	v_cndmask_b32_e64 v70, v70, v246, s[42:43]
	v_cndmask_b32_e64 v71, v71, v246, s[44:45]
	v_max3_f32 v38, v38, v70, v71
	v_add_u32_e32 v39, 16, v37
	v_add_u32_e32 v72, 17, v37
	v_cmp_gt_u32_e64 s[46:47], v39, v145
	v_cmp_gt_u32_e64 s[48:49], v72, v145
	s_nop 0
	v_cndmask_b32_e64 v24, v24, v246, s[46:47]
	v_cndmask_b32_e64 v25, v25, v246, s[48:49]
	v_max3_f32 v38, v38, v24, v25
	v_add_u32_e32 v39, 18, v37
	v_add_u32_e32 v37, 19, v37
	v_cmp_gt_u32_e64 s[50:51], v39, v145
	v_cmp_gt_u32_e64 s[52:53], v37, v145
	s_nop 0
	v_cndmask_b32_e64 v26, v26, v246, s[50:51]
	v_cndmask_b32_e64 v27, v27, v246, s[52:53]
	v_max3_f32 v37, v38, v26, v27
	v_mov_b32_e32 v38, v36
	v_mov_b32_e32 v39, v36
	s_nop 1
	v_permlane32_swap_b32_e32 v38, v39
	v_max3_f32 v36, v36, v38, v39
	v_mov_b32_e32 v38, v37
	v_mov_b32_e32 v39, v37
	s_nop 1
	v_permlane32_swap_b32_e32 v38, v39
	v_max3_f32 v37, v37, v38, v39
	v_mov_b32_e32 v38, v36
	v_mov_b32_e32 v39, v36
	s_nop 1
	v_permlane16_swap_b32_e32 v38, v39
	v_max_f32_e32 v36, v36, v38
	v_max3_f32 v145, v176, v36, v39
	v_sub_f32_e32 v16, v16, v145
	v_mov_b32_e32 v38, v37
	v_mov_b32_e32 v72, v37
	v_exp_f32_e32 v16, v16
	v_sub_f32_e32 v17, v17, v145
	v_permlane16_swap_b32_e32 v38, v72
	v_exp_f32_e32 v17, v17
	v_sub_f32_e32 v18, v18, v145
	v_exp_f32_e32 v18, v18
	v_sub_f32_e32 v19, v19, v145
	v_max_f32_e32 v37, v37, v38
	v_exp_f32_e32 v19, v19
	v_sub_f32_e32 v38, v48, v145
	v_sub_f32_e32 v36, v176, v145
	v_exp_f32_e32 v38, v38
	v_sub_f32_e32 v39, v49, v145
	v_exp_f32_e32 v88, v36
	v_add_f32_e32 v36, 0, v16
	v_exp_f32_e32 v39, v39
	v_sub_f32_e32 v48, v50, v145
	v_add_f32_e32 v36, v17, v36
	v_exp_f32_e32 v48, v48
	v_sub_f32_e32 v49, v51, v145
	v_add_f32_e32 v36, v18, v36
	v_exp_f32_e32 v49, v49
	v_add_f32_e32 v36, v19, v36
	v_add_f32_e32 v36, v38, v36
	v_add_f32_e32 v36, v39, v36
	v_add_f32_e32 v36, v48, v36
	v_max3_f32 v147, v150, v37, v72
	v_add_f32_e32 v146, v49, v36
	v_sub_f32_e32 v36, v150, v147
	v_cvt_pk_bf16_f32 v16, v16, v17
	v_cvt_pk_bf16_f32 v17, v18, v19
	v_cvt_pk_bf16_f32 v19, v48, v49
	v_exp_f32_e32 v48, v36
	v_sub_f32_e32 v36, v68, v147
	v_cvt_pk_bf16_f32 v18, v38, v39
	v_exp_f32_e32 v36, v36
	v_sub_f32_e32 v38, v69, v147
	v_exp_f32_e32 v38, v38
	v_sub_f32_e32 v39, v70, v147
	v_exp_f32_e32 v39, v39
	v_sub_f32_e32 v49, v71, v147
	v_exp_f32_e32 v49, v49
	v_sub_f32_e32 v24, v24, v147
	v_exp_f32_e32 v24, v24
	v_sub_f32_e32 v25, v25, v147
	v_add_f32_e32 v37, 0, v36
	v_exp_f32_e32 v25, v25
	v_add_f32_e32 v37, v38, v37
	v_add_f32_e32 v37, v39, v37
	v_add_f32_e32 v37, v49, v37
	v_cndmask_b32_e64 v50, v24, 0, s[46:47]
	v_add_f32_e32 v24, v50, v37
	v_cndmask_b32_e64 v37, v25, 0, s[48:49]
	v_sub_f32_e32 v25, v26, v147
	v_exp_f32_e32 v25, v25
	v_add_f32_e32 v24, v37, v24
	v_cvt_pk_bf16_f32 v26, v50, v37
	v_cmp_lt_i32_e32 vcc, -1, v184
	v_cndmask_b32_e64 v51, v25, 0, s[50:51]
	v_sub_f32_e32 v25, v27, v147
	v_exp_f32_e32 v25, v25
	v_add_f32_e32 v24, v51, v24
	v_fmac_f32_e32 v146, v149, v88
	s_add_i32 s0, s76, 0xffffff00
	v_cndmask_b32_e64 v27, v25, 0, s[52:53]
	v_add_f32_e32 v183, v27, v24
	v_cvt_pk_bf16_f32 v24, v36, v38
	v_cvt_pk_bf16_f32 v25, v39, v49
	v_cvt_pk_bf16_f32 v27, v51, v27
	v_pk_mul_f32 v[38:39], v[42:43], v[88:89] op_sel_hi:[1,0]
	v_pk_mul_f32 v[36:37], v[40:41], v[88:89] op_sel_hi:[1,0]
	v_pk_mul_f32 v[42:43], v[94:95], v[48:49] op_sel_hi:[1,0]
	v_pk_mul_f32 v[40:41], v[92:93], v[48:49] op_sel_hi:[1,0]
	s_waitcnt lgkmcnt(10)
	v_mfma_f32_16x16x32_bf16 v[36:39], v[140:143], v[16:19], v[36:39]
	v_fmac_f32_e32 v183, v151, v48
	s_min_i32 s1, s0, 0
	s_sub_i32 s1, 3, s1
	v_mfma_f32_16x16x32_bf16 v[68:71], v[140:143], v[24:27], v[40:43]
	s_ashr_i32 s1, s1, 2
	s_sub_i32 s22, 0x200, s76
	s_sub_i32 s0, s75, s0
	v_pk_mul_f32 v[42:43], v[106:107], v[88:89] op_sel_hi:[1,0]
	v_pk_mul_f32 v[40:41], v[104:105], v[88:89] op_sel_hi:[1,0]
	s_ashr_i32 s0, s0, 2
	s_cmp_lt_i32 s76, 0
	s_waitcnt lgkmcnt(8)
	v_mfma_f32_16x16x32_bf16 v[72:75], v[136:139], v[16:19], v[40:43]
	s_nop 2
	v_mul_f32_e64 v42, v110, v48
	v_mul_f32_e64 v43, v111, v48
	v_pk_mul_f32 v[40:41], v[108:109], v[48:49] op_sel_hi:[1,0]
	s_nop 1
	v_mfma_f32_16x16x32_bf16 v[104:107], v[136:139], v[24:27], v[40:43]
	s_nop 2
	v_mul_f32_e64 v42, v114, v88
	v_mul_f32_e64 v43, v115, v88
	v_pk_mul_f32 v[40:41], v[112:113], v[88:89] op_sel_hi:[1,0]
	s_waitcnt lgkmcnt(6)
	s_nop 0
	v_mfma_f32_16x16x32_bf16 v[108:111], v[132:135], v[16:19], v[40:43]
	s_nop 2
	v_mul_f32_e64 v42, v118, v48
	v_mul_f32_e64 v43, v119, v48
	v_pk_mul_f32 v[40:41], v[116:117], v[48:49] op_sel_hi:[1,0]
	s_nop 1
	v_mfma_f32_16x16x32_bf16 v[112:115], v[132:135], v[24:27], v[40:43]
	s_nop 2
	v_mul_f32_e64 v42, v122, v88
	v_mul_f32_e64 v43, v123, v88
	v_pk_mul_f32 v[40:41], v[120:121], v[88:89] op_sel_hi:[1,0]
	s_waitcnt lgkmcnt(4)
	s_nop 0
	v_mfma_f32_16x16x32_bf16 v[116:119], v[128:131], v[16:19], v[40:43]
	v_mul_f32_e64 v18, v126, v48
	v_mul_f32_e64 v19, v127, v48
	v_pk_mul_f32 v[16:17], v[124:125], v[48:49] op_sel_hi:[1,0]
	s_nop 1
	v_mfma_f32_16x16x32_bf16 v[128:131], v[128:131], v[24:27], v[16:19]
	s_nop 2
	v_min_i32_e32 v16, s75, v184
	v_cndmask_b32_e32 v16, 0, v16, vcc
	v_lshl_add_u32 v16, v16, 9, v152
	global_load_dwordx4 v[88:91], v16, s[98:99]
	v_med3_i32 v16, v185, 0, s75
	v_lshl_add_u32 v16, v16, 9, v152
	global_load_dwordx4 v[92:95], v16, s[98:99]
	v_med3_i32 v16, v186, 0, s75
	v_lshl_add_u32 v16, v16, 9, v152
	global_load_dwordx4 v[120:123], v16, s[98:99]
	v_med3_i32 v16, v188, 0, s75
	v_lshl_add_u32 v16, v16, 9, v152
	global_load_dwordx4 v[124:127], v16, s[98:99]
	v_add_u32_e32 v16, s76, v209
	v_med3_i32 v16, v16, 0, s75
	v_lshl_add_u32 v16, v16, 9, v158
	global_load_dwordx4 v[48:51], v16, s[100:101]
	global_load_dwordx4 v[40:43], v16, s[100:101] offset:64
	v_or_b32_e32 v16, 64, v209
	v_add_u32_e32 v16, s76, v16
	v_med3_i32 v16, v16, 0, s75
	v_lshl_add_u32 v16, v16, 9, v158
	global_load_dwordx4 v[24:27], v16, s[100:101]
	s_nop 0
	global_load_dwordx4 v[16:19], v16, s[100:101] offset:64
	ds_read_b64_tr_b16 v[98:99], v169 offset:2304
	ds_read_b64_tr_b16 v[96:97], v169
	ds_read_b64_tr_b16 v[140:141], v169 offset:32
	ds_read_b64_tr_b16 v[142:143], v169 offset:2336
	ds_read_b64_tr_b16 v[136:137], v169 offset:64
	ds_read_b64_tr_b16 v[138:139], v169 offset:2368
	ds_read_b64_tr_b16 v[132:133], v169 offset:96
	ds_read_b64_tr_b16 v[134:135], v169 offset:2400
	s_waitcnt vmcnt(15)
	ds_write_b128 v241, v[32:35] offset:4608
	s_waitcnt vmcnt(14)
	ds_write_b128 v242, v[64:67] offset:4608
	s_waitcnt vmcnt(13)
	ds_write_b128 v243, v[76:79] offset:4608
	s_waitcnt vmcnt(12)
	ds_write_b128 v244, v[100:103] offset:4608
	v_mfma_f32_16x16x32_bf16 v[64:67], v[60:63], v[4:7], 0
	v_mfma_f32_16x16x32_bf16 v[60:63], v[60:63], v[12:15], 0
	v_mfma_f32_16x16x32_bf16 v[32:35], v[84:87], v[4:7], 0
	v_mfma_f32_16x16x32_bf16 v[64:67], v[56:59], v[8:11], v[64:67]
	v_mfma_f32_16x16x32_bf16 v[56:59], v[56:59], v[0:3], v[60:63]
	s_nop 4
	v_ashrrev_i32_e32 v60, 2, v250
	v_max_i32_e32 v176, s1, v60
	v_add_u32_e32 v60, s22, v251
	v_ashrrev_i32_e32 v60, 2, v60
	v_min3_i32 v60, v60, s0, v247
	v_mfma_f32_16x16x32_bf16 v[32:35], v[80:83], v[8:11], v[32:35]
	v_sub_u32_e32 v175, v60, v176
	v_ashrrev_i32_e32 v60, 2, v249
	v_max_i32_e32 v181, s1, v60
	v_add_u32_e32 v60, s22, v144
	v_sub_u32_e32 v61, v154, v176
	v_ashrrev_i32_e32 v60, 2, v60
	v_mfma_f32_16x16x32_bf16 v[76:79], v[84:87], v[12:15], 0
	v_min3_i32 v60, v60, s0, v247
	v_add_u32_e32 v63, 1, v61
	v_sub_u32_e32 v252, v60, v181
	v_cmp_gt_u32_e64 s[0:1], v63, v175
	v_cmp_gt_u32_e32 vcc, v61, v175
	s_nop 0
	v_cndmask_b32_e64 v33, v33, v246, s[0:1]
	s_nop 0
	v_cndmask_b32_e32 v32, v32, v246, vcc
	v_max_f32_e32 v60, 0xf149f2ca, v32
	v_mfma_f32_16x16x32_bf16 v[76:79], v[80:83], v[0:3], v[76:79]
	v_max_f32_e32 v60, v60, v33
	v_add_u32_e32 v63, 2, v61
	v_add_u32_e32 v80, 3, v61
	v_cmp_gt_u32_e64 s[22:23], v63, v175
	v_cmp_gt_u32_e64 s[24:25], v80, v175
	v_sub_u32_e32 v62, v154, v181
	v_cndmask_b32_e64 v34, v34, v246, s[22:23]
	v_cndmask_b32_e64 v35, v35, v246, s[24:25]
	v_max3_f32 v60, v60, v34, v35
	v_add_u32_e32 v63, 16, v61
	v_add_u32_e32 v80, 17, v61
	v_cmp_gt_u32_e64 s[26:27], v63, v175
	v_cmp_gt_u32_e64 s[28:29], v80, v175
	v_cmp_gt_u32_e64 s[38:39], v62, v252
	v_cndmask_b32_e64 v64, v64, v246, s[26:27]
	v_cndmask_b32_e64 v65, v65, v246, s[28:29]
	v_max3_f32 v60, v60, v64, v65
	v_add_u32_e32 v63, 18, v61
	v_add_u32_e32 v61, 19, v61
	v_cmp_gt_u32_e64 s[30:31], v63, v175
	v_cmp_gt_u32_e64 s[34:35], v61, v175
	v_add_u32_e32 v80, 3, v62
	v_cndmask_b32_e64 v66, v66, v246, s[30:31]
	v_cndmask_b32_e64 v67, v67, v246, s[34:35]
	v_max3_f32 v60, v60, v66, v67
	v_add_u32_e32 v63, 1, v62
	v_cmp_gt_u32_e64 s[40:41], v63, v252
	v_cndmask_b32_e64 v76, v76, v246, s[38:39]
	v_max_f32_e32 v61, 0xf149f2ca, v76
	v_cndmask_b32_e64 v77, v77, v246, s[40:41]
	v_max_f32_e32 v61, v61, v77
	v_add_u32_e32 v63, 2, v62
	v_cmp_gt_u32_e64 s[42:43], v63, v252
	v_cmp_gt_u32_e64 s[44:45], v80, v252
	s_nop 0
	v_cndmask_b32_e64 v78, v78, v246, s[42:43]
	v_cndmask_b32_e64 v79, v79, v246, s[44:45]
	v_max3_f32 v61, v61, v78, v79
	v_add_u32_e32 v63, 16, v62
	v_add_u32_e32 v80, 17, v62
	v_cmp_gt_u32_e64 s[46:47], v63, v252
	v_cmp_gt_u32_e64 s[48:49], v80, v252
	s_nop 0
	v_cndmask_b32_e64 v56, v56, v246, s[46:47]
	v_cndmask_b32_e64 v57, v57, v246, s[48:49]
	v_max3_f32 v61, v61, v56, v57
	v_add_u32_e32 v63, 18, v62
	v_add_u32_e32 v62, 19, v62
	v_cmp_gt_u32_e64 s[50:51], v63, v252
	v_cmp_gt_u32_e64 s[52:53], v62, v252
	s_nop 0
	v_cndmask_b32_e64 v58, v58, v246, s[50:51]
	v_cndmask_b32_e64 v59, v59, v246, s[52:53]
	v_max3_f32 v61, v61, v58, v59
	v_mov_b32_e32 v62, v60
	v_mov_b32_e32 v63, v60
	s_nop 1
	v_permlane32_swap_b32_e32 v62, v63
	v_max3_f32 v60, v60, v62, v63
	v_mov_b32_e32 v62, v61
	v_mov_b32_e32 v63, v61
	s_nop 1
	v_permlane32_swap_b32_e32 v62, v63
	v_max3_f32 v61, v61, v62, v63
	v_mov_b32_e32 v62, v60
	v_mov_b32_e32 v63, v60
	s_nop 1
	v_permlane16_swap_b32_e32 v62, v63
	v_max_f32_e32 v60, v60, v62
	v_max3_f32 v148, v145, v60, v63
	v_sub_f32_e32 v32, v32, v148
	v_exp_f32_e32 v32, v32
	v_sub_f32_e32 v33, v33, v148
	v_exp_f32_e32 v33, v33
	v_sub_f32_e32 v34, v34, v148
	v_mov_b32_e32 v62, v61
	v_mov_b32_e32 v80, v61
	v_exp_f32_e32 v34, v34
	v_sub_f32_e32 v35, v35, v148
	v_permlane16_swap_b32_e32 v62, v80
	v_exp_f32_e32 v35, v35
	v_sub_f32_e32 v63, v64, v148
	v_exp_f32_e32 v63, v63
	v_sub_f32_e32 v64, v65, v148
	v_max_f32_e32 v61, v61, v62
	v_add_f32_e32 v62, 0, v32
	v_exp_f32_e32 v64, v64
	v_sub_f32_e32 v65, v66, v148
	v_add_f32_e32 v62, v33, v62
	v_exp_f32_e32 v65, v65
	v_sub_f32_e32 v66, v67, v148
	v_add_f32_e32 v62, v34, v62
	v_exp_f32_e32 v66, v66
	v_add_f32_e32 v62, v35, v62
	v_add_f32_e32 v62, v63, v62
	v_add_f32_e32 v62, v64, v62
	v_max3_f32 v150, v147, v61, v80
	v_add_f32_e32 v62, v65, v62
	v_sub_f32_e32 v61, v147, v150
	v_add_f32_e32 v149, v66, v62
	v_exp_f32_e32 v62, v61
	v_sub_f32_e32 v61, v76, v150
	v_cvt_pk_bf16_f32 v32, v32, v33
	v_cvt_pk_bf16_f32 v33, v34, v35
	v_cvt_pk_bf16_f32 v34, v63, v64
	v_exp_f32_e32 v61, v61
	v_sub_f32_e32 v64, v77, v150
	v_cvt_pk_bf16_f32 v35, v65, v66
	v_exp_f32_e32 v64, v64
	v_sub_f32_e32 v65, v78, v150
	v_exp_f32_e32 v65, v65
	v_sub_f32_e32 v66, v79, v150
	v_exp_f32_e32 v66, v66
	v_sub_f32_e32 v56, v56, v150
	v_exp_f32_e32 v56, v56
	v_sub_f32_e32 v57, v57, v150
	v_add_f32_e32 v63, 0, v61
	v_exp_f32_e32 v57, v57
	v_add_f32_e32 v63, v64, v63
	v_add_f32_e32 v63, v65, v63
	v_add_f32_e32 v63, v66, v63
	v_cndmask_b32_e64 v67, v56, 0, s[46:47]
	v_add_f32_e32 v56, v67, v63
	v_cndmask_b32_e64 v63, v57, 0, s[48:49]
	v_sub_f32_e32 v57, v58, v150
	v_exp_f32_e32 v57, v57
	v_sub_f32_e32 v60, v145, v148
	v_exp_f32_e32 v60, v60
	v_add_f32_e32 v56, v63, v56
	v_cndmask_b32_e64 v76, v57, 0, s[50:51]
	v_sub_f32_e32 v57, v59, v150
	v_exp_f32_e32 v57, v57
	v_add_f32_e32 v56, v76, v56
	v_pk_mul_f32 v[38:39], v[38:39], v[60:61] op_sel_hi:[1,0]
	v_pk_mul_f32 v[36:37], v[36:37], v[60:61] op_sel_hi:[1,0]
	v_cndmask_b32_e64 v59, v57, 0, s[52:53]
	v_add_f32_e32 v151, v59, v56
	v_cvt_pk_bf16_f32 v56, v61, v64
	v_cvt_pk_bf16_f32 v57, v65, v66
	v_cvt_pk_bf16_f32 v58, v67, v63
	v_cvt_pk_bf16_f32 v59, v76, v59
	s_waitcnt lgkmcnt(10)
	v_mfma_f32_16x16x32_bf16 v[80:83], v[96:99], v[32:35], v[36:39]
	v_fmac_f32_e32 v149, v146, v60
	v_fmac_f32_e32 v151, v183, v62
	s_nop 0
	v_pk_mul_f32 v[38:39], v[70:71], v[62:63] op_sel_hi:[1,0]
	v_pk_mul_f32 v[36:37], v[68:69], v[62:63] op_sel_hi:[1,0]
	s_nop 1
	v_mfma_f32_16x16x32_bf16 v[84:87], v[96:99], v[56:59], v[36:39]
	s_nop 2
	v_mul_f32_e64 v38, v74, v60
	v_mul_f32_e64 v39, v75, v60
	v_pk_mul_f32 v[36:37], v[72:73], v[60:61] op_sel_hi:[1,0]
	s_waitcnt lgkmcnt(8)
	s_nop 0
	v_mfma_f32_16x16x32_bf16 v[96:99], v[140:143], v[32:35], v[36:39]
	s_nop 2
	v_mul_f32_e64 v38, v106, v62
	v_mul_f32_e64 v39, v107, v62
	v_pk_mul_f32 v[36:37], v[104:105], v[62:63] op_sel_hi:[1,0]
	s_nop 1
	v_mfma_f32_16x16x32_bf16 v[100:103], v[140:143], v[56:59], v[36:39]
	s_nop 2
	v_mul_f32_e64 v38, v110, v60
	v_mul_f32_e64 v39, v111, v60
	v_pk_mul_f32 v[36:37], v[108:109], v[60:61] op_sel_hi:[1,0]
	s_waitcnt lgkmcnt(6)
	s_nop 0
	v_mfma_f32_16x16x32_bf16 v[104:107], v[136:139], v[32:35], v[36:39]
	s_nop 2
	v_mul_f32_e64 v38, v114, v62
	v_mul_f32_e64 v39, v115, v62
	v_pk_mul_f32 v[36:37], v[112:113], v[62:63] op_sel_hi:[1,0]
	s_nop 1
	v_mfma_f32_16x16x32_bf16 v[108:111], v[136:139], v[56:59], v[36:39]
	s_nop 2
	v_mul_f32_e64 v38, v118, v60
	v_mul_f32_e64 v39, v119, v60
	v_pk_mul_f32 v[36:37], v[116:117], v[60:61] op_sel_hi:[1,0]
	s_waitcnt lgkmcnt(4)
	s_nop 0
	v_mfma_f32_16x16x32_bf16 v[112:115], v[132:135], v[32:35], v[36:39]
	v_mul_f32_e64 v34, v130, v62
	v_mul_f32_e64 v35, v131, v62
	v_pk_mul_f32 v[32:33], v[128:129], v[62:63] op_sel_hi:[1,0]
	s_nop 1
	v_mfma_f32_16x16x32_bf16 v[116:119], v[132:135], v[56:59], v[32:35]
	s_nop 2
	v_add_u32_e32 v32, 0x80, v184
	v_med3_i32 v32, v32, 0, s75
	v_lshl_add_u32 v32, v32, 9, v152
	global_load_dwordx4 v[64:67], v32, s[98:99]
	v_add_u32_e32 v32, 0x80, v185
	v_med3_i32 v32, v32, 0, s75
	v_lshl_add_u32 v32, v32, 9, v152
	global_load_dwordx4 v[68:71], v32, s[98:99]
	v_add_u32_e32 v32, 0x80, v186
	v_med3_i32 v32, v32, 0, s75
	v_lshl_add_u32 v32, v32, 9, v152
	global_load_dwordx4 v[72:75], v32, s[98:99]
	v_add_u32_e32 v32, 0x80, v188
	v_med3_i32 v32, v32, 0, s75
	v_lshl_add_u32 v32, v32, 9, v152
	global_load_dwordx4 v[76:79], v32, s[98:99]
	v_or_b32_e32 v32, 0x80, v209
	v_add_u32_e32 v32, s76, v32
	v_med3_i32 v32, v32, 0, s75
	v_lshl_add_u32 v32, v32, 9, v158
	global_load_dwordx4 v[60:63], v32, s[100:101]
	global_load_dwordx4 v[56:59], v32, s[100:101] offset:64
	v_or_b32_e32 v32, 0xc0, v209
	v_add_u32_e32 v32, s76, v32
	v_med3_i32 v32, v32, 0, s75
	v_lshl_add_u32 v32, v32, 9, v158
	global_load_dwordx4 v[36:39], v32, s[100:101]
	s_nop 0
	global_load_dwordx4 v[32:35], v32, s[100:101] offset:64
	ds_read_b64_tr_b16 v[134:135], v169 offset:6912
	ds_read_b64_tr_b16 v[132:133], v169 offset:4608
	ds_read_b64_tr_b16 v[128:129], v169 offset:4640
	ds_read_b64_tr_b16 v[130:131], v169 offset:6944
	ds_read_b64_tr_b16 v[136:137], v169 offset:4672
	ds_read_b64_tr_b16 v[138:139], v169 offset:6976
	ds_read_b64_tr_b16 v[144:145], v169 offset:4704
	ds_read_b64_tr_b16 v[146:147], v169 offset:7008
	s_waitcnt vmcnt(15)
	ds_write_b128 v241, v[88:91]
	s_waitcnt vmcnt(14)
	ds_write_b128 v242, v[92:95]
	s_waitcnt vmcnt(13)
	ds_write_b128 v243, v[120:123]
	s_waitcnt vmcnt(12)
	ds_write_b128 v244, v[124:127]
	v_mfma_f32_16x16x32_bf16 v[88:91], v[52:55], v[4:7], 0
	v_mfma_f32_16x16x32_bf16 v[92:95], v[28:31], v[4:7], 0
	v_mfma_f32_16x16x32_bf16 v[28:31], v[28:31], v[12:15], 0
	v_mfma_f32_16x16x32_bf16 v[88:91], v[44:47], v[8:11], v[88:91]
	v_mfma_f32_16x16x32_bf16 v[92:95], v[20:23], v[8:11], v[92:95]
	v_mfma_f32_16x16x32_bf16 v[20:23], v[20:23], v[0:3], v[28:31]
	s_nop 4
	v_sub_u32_e32 v28, v187, v176
	v_mfma_f32_16x16x32_bf16 v[52:55], v[52:55], v[12:15], 0
	v_add_u32_e32 v31, 1, v28
	v_cmp_gt_u32_e64 s[0:1], v31, v175
	v_cmp_gt_u32_e32 vcc, v28, v175
	s_nop 0
	v_cndmask_b32_e64 v89, v89, v246, s[0:1]
	s_nop 0
	v_cndmask_b32_e32 v88, v88, v246, vcc
	v_max_f32_e32 v30, 0xf149f2ca, v88
	v_mfma_f32_16x16x32_bf16 v[44:47], v[44:47], v[0:3], v[52:55]
	v_max_f32_e32 v30, v30, v89
	v_add_u32_e32 v31, 2, v28
	v_cmp_gt_u32_e64 s[22:23], v31, v175
	v_add_u32_e32 v52, 3, v28
	v_cmp_gt_u32_e64 s[24:25], v52, v175
	v_cndmask_b32_e64 v90, v90, v246, s[22:23]
	v_sub_u32_e32 v29, v187, v181
	v_cndmask_b32_e64 v91, v91, v246, s[24:25]
	v_max3_f32 v30, v30, v90, v91
	v_add_u32_e32 v31, 16, v28
	v_add_u32_e32 v52, 17, v28
	v_cmp_gt_u32_e64 s[26:27], v31, v175
	v_cmp_gt_u32_e64 s[28:29], v52, v175
	v_cmp_gt_u32_e64 s[38:39], v29, v252
	v_cndmask_b32_e64 v92, v92, v246, s[26:27]
	v_cndmask_b32_e64 v93, v93, v246, s[28:29]
	v_max3_f32 v30, v30, v92, v93
	v_add_u32_e32 v31, 18, v28
	v_add_u32_e32 v28, 19, v28
	v_cmp_gt_u32_e64 s[30:31], v31, v175
	v_cmp_gt_u32_e64 s[34:35], v28, v175
	v_add_u32_e32 v52, 3, v29
	v_cndmask_b32_e64 v94, v94, v246, s[30:31]
	v_cndmask_b32_e64 v95, v95, v246, s[34:35]
	v_max3_f32 v28, v30, v94, v95
	v_add_u32_e32 v31, 1, v29
	v_cmp_gt_u32_e64 s[40:41], v31, v252
	v_cndmask_b32_e64 v44, v44, v246, s[38:39]
	v_max_f32_e32 v30, 0xf149f2ca, v44
	v_cndmask_b32_e64 v45, v45, v246, s[40:41]
	v_max_f32_e32 v30, v30, v45
	v_add_u32_e32 v31, 2, v29
	v_cmp_gt_u32_e64 s[42:43], v31, v252
	v_cmp_gt_u32_e64 s[44:45], v52, v252
	s_nop 0
	v_cndmask_b32_e64 v46, v46, v246, s[42:43]
	v_cndmask_b32_e64 v47, v47, v246, s[44:45]
	v_max3_f32 v30, v30, v46, v47
	v_add_u32_e32 v31, 16, v29
	v_add_u32_e32 v52, 17, v29
	v_cmp_gt_u32_e64 s[46:47], v31, v252
	v_cmp_gt_u32_e64 s[48:49], v52, v252
	s_nop 0
	v_cndmask_b32_e64 v20, v20, v246, s[46:47]
	v_cndmask_b32_e64 v21, v21, v246, s[48:49]
	v_max3_f32 v30, v30, v20, v21
	v_add_u32_e32 v31, 18, v29
	v_add_u32_e32 v29, 19, v29
	v_cmp_gt_u32_e64 s[50:51], v31, v252
	v_cmp_gt_u32_e64 s[52:53], v29, v252
	s_nop 0
	v_cndmask_b32_e64 v22, v22, v246, s[50:51]
	v_cndmask_b32_e64 v23, v23, v246, s[52:53]
	v_max3_f32 v29, v30, v22, v23
	v_mov_b32_e32 v30, v28
	v_mov_b32_e32 v31, v28
	s_nop 1
	v_permlane32_swap_b32_e32 v30, v31
	v_max3_f32 v28, v28, v30, v31
	v_mov_b32_e32 v30, v29
	v_mov_b32_e32 v31, v29
	s_nop 1
	v_permlane32_swap_b32_e32 v30, v31
	v_max3_f32 v29, v29, v30, v31
	v_mov_b32_e32 v30, v28
	v_mov_b32_e32 v31, v28
	s_nop 1
	v_permlane16_swap_b32_e32 v30, v31
	v_max_f32_e32 v28, v28, v30
	v_mov_b32_e32 v30, v29
	v_mov_b32_e32 v53, v29
	v_max3_f32 v183, v148, v28, v31
	s_nop 0
	v_permlane16_swap_b32_e32 v30, v53
	v_sub_f32_e32 v28, v148, v183
	v_exp_f32_e32 v52, v28
	v_sub_f32_e32 v28, v88, v183
	v_max_f32_e32 v54, v29, v30
	v_exp_f32_e32 v28, v28
	v_sub_f32_e32 v30, v89, v183
	v_exp_f32_e32 v30, v30
	v_sub_f32_e32 v31, v90, v183
	v_exp_f32_e32 v31, v31
	v_sub_f32_e32 v55, v91, v183
	v_max3_f32 v185, v150, v54, v53
	v_exp_f32_e32 v55, v55
	v_sub_f32_e32 v88, v92, v183
	v_sub_f32_e32 v44, v44, v185
	v_exp_f32_e32 v88, v88
	v_sub_f32_e32 v89, v93, v183
	v_exp_f32_e32 v44, v44
	v_sub_f32_e32 v45, v45, v185
	v_add_f32_e32 v29, 0, v28
	v_exp_f32_e32 v89, v89
	v_sub_f32_e32 v90, v94, v183
	v_exp_f32_e32 v45, v45
	v_sub_f32_e32 v46, v46, v185
	v_add_f32_e32 v29, v30, v29
	v_exp_f32_e32 v90, v90
	v_sub_f32_e32 v91, v95, v183
	v_exp_f32_e32 v46, v46
	v_sub_f32_e32 v47, v47, v185
	v_add_f32_e32 v29, v31, v29
	v_exp_f32_e32 v91, v91
	v_exp_f32_e32 v47, v47
	v_sub_f32_e32 v20, v20, v185
	v_add_f32_e32 v29, v55, v29
	v_sub_f32_e32 v53, v150, v185
	v_exp_f32_e32 v20, v20
	v_sub_f32_e32 v21, v21, v185
	v_add_f32_e32 v29, v88, v29
	v_exp_f32_e32 v54, v53
	v_add_f32_e32 v53, 0, v44
	v_exp_f32_e32 v21, v21
	v_add_f32_e32 v29, v89, v29
	v_add_f32_e32 v53, v45, v53
	v_add_f32_e32 v29, v90, v29
	v_add_f32_e32 v53, v46, v53
	v_add_f32_e32 v184, v91, v29
	v_cvt_pk_bf16_f32 v29, v31, v55
	v_add_f32_e32 v53, v47, v53
	v_cndmask_b32_e64 v55, v20, 0, s[46:47]
	v_add_f32_e32 v20, v55, v53
	v_cndmask_b32_e64 v53, v21, 0, s[48:49]
	v_sub_f32_e32 v21, v22, v185
	v_exp_f32_e32 v21, v21
	v_cvt_pk_bf16_f32 v28, v28, v30
	v_cvt_pk_bf16_f32 v30, v88, v89
	v_add_f32_e32 v20, v53, v20
	v_cndmask_b32_e64 v88, v21, 0, s[50:51]
	v_sub_f32_e32 v21, v23, v185
	v_exp_f32_e32 v21, v21
	v_add_f32_e32 v20, v88, v20
	v_cvt_pk_bf16_f32 v31, v90, v91
	v_cvt_pk_bf16_f32 v22, v55, v53
	v_cndmask_b32_e64 v23, v21, 0, s[52:53]
	v_add_f32_e32 v186, v23, v20
	v_cvt_pk_bf16_f32 v20, v44, v45
	v_cvt_pk_bf16_f32 v21, v46, v47
	v_pk_mul_f32 v[46:47], v[82:83], v[52:53] op_sel_hi:[1,0]
	v_pk_mul_f32 v[44:45], v[80:81], v[52:53] op_sel_hi:[1,0]
	v_cvt_pk_bf16_f32 v23, v88, v23
	v_fmac_f32_e32 v184, v149, v52
	s_waitcnt lgkmcnt(10)
	v_mfma_f32_16x16x32_bf16 v[120:123], v[132:135], v[28:31], v[44:47]
	v_fmac_f32_e32 v186, v151, v54
	s_nop 1
	v_pk_mul_f32 v[46:47], v[86:87], v[54:55] op_sel_hi:[1,0]
	v_pk_mul_f32 v[44:45], v[84:85], v[54:55] op_sel_hi:[1,0]
	s_nop 1
	v_mfma_f32_16x16x32_bf16 v[124:127], v[132:135], v[20:23], v[44:47]
	s_nop 2
	v_mul_f32_e64 v46, v98, v52
	v_mul_f32_e64 v47, v99, v52
	v_pk_mul_f32 v[44:45], v[96:97], v[52:53] op_sel_hi:[1,0]
	s_waitcnt lgkmcnt(8)
	s_nop 0
	v_mfma_f32_16x16x32_bf16 v[96:99], v[128:131], v[28:31], v[44:47]
	s_nop 2
	v_mul_f32_e64 v46, v102, v54
	v_mul_f32_e64 v47, v103, v54
	v_pk_mul_f32 v[44:45], v[100:101], v[54:55] op_sel_hi:[1,0]
	s_nop 1
	v_mfma_f32_16x16x32_bf16 v[128:131], v[128:131], v[20:23], v[44:47]
	s_nop 2
	v_mul_f32_e64 v46, v106, v52
	v_mul_f32_e64 v47, v107, v52
	v_pk_mul_f32 v[44:45], v[104:105], v[52:53] op_sel_hi:[1,0]
	s_waitcnt lgkmcnt(6)
	s_nop 0
	v_mfma_f32_16x16x32_bf16 v[132:135], v[136:139], v[28:31], v[44:47]
	s_nop 2
	v_mul_f32_e64 v46, v110, v54
	v_mul_f32_e64 v47, v111, v54
	v_pk_mul_f32 v[44:45], v[108:109], v[54:55] op_sel_hi:[1,0]
	s_nop 1
	v_mfma_f32_16x16x32_bf16 v[136:139], v[136:139], v[20:23], v[44:47]
	s_nop 2
	v_mul_f32_e64 v46, v114, v52
	v_mul_f32_e64 v47, v115, v52
	v_pk_mul_f32 v[44:45], v[112:113], v[52:53] op_sel_hi:[1,0]
	s_waitcnt lgkmcnt(4)
	s_nop 0
	v_mfma_f32_16x16x32_bf16 v[140:143], v[144:147], v[28:31], v[44:47]
	v_mul_f32_e64 v30, v118, v54
	v_mul_f32_e64 v31, v119, v54
	v_pk_mul_f32 v[28:29], v[116:117], v[54:55] op_sel_hi:[1,0]
	s_nop 1
	v_mfma_f32_16x16x32_bf16 v[144:147], v[144:147], v[20:23], v[28:31]
	v_lshl_add_u32 v20, v155, 1, v155
	v_add_u32_e32 v20, v180, v20
	v_med3_i32 v20, v20, 0, s75
	v_lshl_add_u32 v20, v20, 9, v152
	global_load_dwordx4 v[80:83], v20, s[98:99]
	v_lshl_add_u32 v20, v172, 1, v172
	v_add_u32_e32 v20, v179, v20
	v_med3_i32 v20, v20, 0, s75
	v_lshl_add_u32 v20, v20, 9, v152
	global_load_dwordx4 v[84:87], v20, s[98:99]
	v_lshl_add_u32 v20, v173, 1, v173
	v_add_u32_e32 v20, v178, v20
	v_med3_i32 v20, v20, 0, s75
	v_lshl_add_u32 v20, v20, 9, v152
	global_load_dwordx4 v[88:91], v20, s[98:99]
	v_lshl_add_u32 v20, v182, 1, v182
	v_add_u32_e32 v20, v177, v20
	v_med3_i32 v20, v20, 0, s75
	v_lshl_add_u32 v20, v20, 9, v152
	global_load_dwordx4 v[92:95], v20, s[98:99]
	v_or_b32_e32 v20, 0x100, v209
	v_add_u32_e32 v20, s76, v20
	v_med3_i32 v20, v20, 0, s75
	v_lshl_add_u32 v20, v20, 9, v158
	global_load_dwordx4 v[52:55], v20, s[100:101]
	global_load_dwordx4 v[44:47], v20, s[100:101] offset:64
	v_or_b32_e32 v20, 0x140, v209
	v_add_u32_e32 v20, s76, v20
	v_med3_i32 v20, v20, 0, s75
	v_lshl_add_u32 v20, v20, 9, v158
	global_load_dwordx4 v[28:31], v20, s[100:101]
	s_nop 0
	global_load_dwordx4 v[20:23], v20, s[100:101] offset:64
	ds_read_b64_tr_b16 v[102:103], v169 offset:2304
	ds_read_b64_tr_b16 v[100:101], v169
	ds_read_b64_tr_b16 v[108:109], v169 offset:32
	ds_read_b64_tr_b16 v[110:111], v169 offset:2336
	ds_read_b64_tr_b16 v[116:117], v169 offset:64
	ds_read_b64_tr_b16 v[118:119], v169 offset:2368
	ds_read_b64_tr_b16 v[148:149], v169 offset:96
	ds_read_b64_tr_b16 v[150:151], v169 offset:2400
	s_waitcnt vmcnt(15)
	ds_write_b128 v241, v[64:67] offset:4608
	s_waitcnt vmcnt(14)
	ds_write_b128 v242, v[68:71] offset:4608
	s_waitcnt vmcnt(13)
	ds_write_b128 v243, v[72:75] offset:4608
	s_waitcnt vmcnt(12)
	ds_write_b128 v244, v[76:79] offset:4608
	v_mfma_f32_16x16x32_bf16 v[64:67], v[48:51], v[4:7], 0
	v_mfma_f32_16x16x32_bf16 v[68:71], v[24:27], v[4:7], 0
	v_mfma_f32_16x16x32_bf16 v[24:27], v[24:27], v[12:15], 0
	v_mfma_f32_16x16x32_bf16 v[64:67], v[40:43], v[8:11], v[64:67]
	v_mfma_f32_16x16x32_bf16 v[68:71], v[16:19], v[8:11], v[68:71]
	v_mfma_f32_16x16x32_bf16 v[16:19], v[16:19], v[0:3], v[24:27]
	s_nop 4
	v_sub_u32_e32 v24, v192, v176
	v_mfma_f32_16x16x32_bf16 v[48:51], v[48:51], v[12:15], 0
	v_add_u32_e32 v27, 1, v24
	v_cmp_gt_u32_e64 s[0:1], v27, v175
	v_cmp_gt_u32_e32 vcc, v24, v175
	s_nop 0
	v_cndmask_b32_e64 v65, v65, v246, s[0:1]
	s_nop 0
	v_cndmask_b32_e32 v64, v64, v246, vcc
	v_max_f32_e32 v26, 0xf149f2ca, v64
	v_mfma_f32_16x16x32_bf16 v[40:43], v[40:43], v[0:3], v[48:51]
	v_max_f32_e32 v26, v26, v65
	v_add_u32_e32 v27, 2, v24
	v_cmp_gt_u32_e64 s[22:23], v27, v175
	v_add_u32_e32 v48, 3, v24
	v_cmp_gt_u32_e64 s[24:25], v48, v175
	v_cndmask_b32_e64 v66, v66, v246, s[22:23]
	v_sub_u32_e32 v25, v192, v181
	v_cndmask_b32_e64 v67, v67, v246, s[24:25]
	v_max3_f32 v26, v26, v66, v67
	v_add_u32_e32 v27, 16, v24
	v_add_u32_e32 v48, 17, v24
	v_cmp_gt_u32_e64 s[26:27], v27, v175
	v_cmp_gt_u32_e64 s[28:29], v48, v175
	v_cmp_gt_u32_e64 s[38:39], v25, v252
	v_cndmask_b32_e64 v68, v68, v246, s[26:27]
	v_cndmask_b32_e64 v69, v69, v246, s[28:29]
	v_max3_f32 v26, v26, v68, v69
	v_add_u32_e32 v27, 18, v24
	v_add_u32_e32 v24, 19, v24
	v_cmp_gt_u32_e64 s[30:31], v27, v175
	v_cmp_gt_u32_e64 s[34:35], v24, v175
	v_add_u32_e32 v48, 3, v25
	v_cndmask_b32_e64 v70, v70, v246, s[30:31]
	v_cndmask_b32_e64 v71, v71, v246, s[34:35]
	v_max3_f32 v24, v26, v70, v71
	v_add_u32_e32 v27, 1, v25
	v_cmp_gt_u32_e64 s[40:41], v27, v252
	v_cndmask_b32_e64 v40, v40, v246, s[38:39]
	v_max_f32_e32 v26, 0xf149f2ca, v40
	v_cndmask_b32_e64 v41, v41, v246, s[40:41]
	v_max_f32_e32 v26, v26, v41
	v_add_u32_e32 v27, 2, v25
	v_cmp_gt_u32_e64 s[42:43], v27, v252
	v_cmp_gt_u32_e64 s[44:45], v48, v252
	s_nop 0
	v_cndmask_b32_e64 v42, v42, v246, s[42:43]
	v_cndmask_b32_e64 v43, v43, v246, s[44:45]
	v_max3_f32 v26, v26, v42, v43
	v_add_u32_e32 v27, 16, v25
	v_add_u32_e32 v48, 17, v25
	v_cmp_gt_u32_e64 s[46:47], v27, v252
	v_cmp_gt_u32_e64 s[48:49], v48, v252
	s_nop 0
	v_cndmask_b32_e64 v16, v16, v246, s[46:47]
	v_cndmask_b32_e64 v17, v17, v246, s[48:49]
	v_max3_f32 v26, v26, v16, v17
	v_add_u32_e32 v27, 18, v25
	v_add_u32_e32 v25, 19, v25
	v_cmp_gt_u32_e64 s[50:51], v27, v252
	v_cmp_gt_u32_e64 s[52:53], v25, v252
	s_nop 0
	v_cndmask_b32_e64 v18, v18, v246, s[50:51]
	v_cndmask_b32_e64 v19, v19, v246, s[52:53]
	v_max3_f32 v25, v26, v18, v19
	v_mov_b32_e32 v26, v24
	v_mov_b32_e32 v27, v24
	s_nop 1
	v_permlane32_swap_b32_e32 v26, v27
	v_max3_f32 v24, v24, v26, v27
	v_mov_b32_e32 v26, v25
	v_mov_b32_e32 v27, v25
	s_nop 1
	v_permlane32_swap_b32_e32 v26, v27
	v_max3_f32 v25, v25, v26, v27
	v_mov_b32_e32 v26, v24
	v_mov_b32_e32 v27, v24
	s_nop 1
	v_permlane16_swap_b32_e32 v26, v27
	v_max_f32_e32 v24, v24, v26
	v_max3_f32 v177, v183, v24, v27
	v_sub_f32_e32 v48, v66, v177
	v_exp_f32_e32 v48, v48
	v_sub_f32_e32 v24, v183, v177
	v_exp_f32_e32 v72, v24
	v_sub_f32_e32 v24, v64, v177
	v_cndmask_b32_e64 v49, v48, 0, s[22:23]
	v_sub_f32_e32 v48, v67, v177
	v_exp_f32_e32 v48, v48
	v_exp_f32_e32 v24, v24
	v_sub_f32_e32 v27, v65, v177
	v_exp_f32_e32 v27, v27
	v_cndmask_b32_e64 v50, v48, 0, s[24:25]
	v_sub_f32_e32 v48, v68, v177
	v_exp_f32_e32 v48, v48
	v_mov_b32_e32 v26, v25
	v_mov_b32_e32 v73, v25
	s_nop 1
	v_permlane16_swap_b32_e32 v26, v73
	v_cndmask_b32_e64 v51, v48, 0, s[26:27]
	v_sub_f32_e32 v48, v69, v177
	v_exp_f32_e32 v48, v48
	v_max_f32_e32 v25, v25, v26
	v_cndmask_b32_e64 v64, v48, 0, s[28:29]
	v_sub_f32_e32 v48, v70, v177
	v_exp_f32_e32 v48, v48
	v_add_f32_e32 v26, 0, v24
	v_add_f32_e32 v26, v27, v26
	v_cndmask_b32_e64 v65, v48, 0, s[30:31]
	v_sub_f32_e32 v48, v71, v177
	v_exp_f32_e32 v48, v48
	v_add_f32_e32 v26, v49, v26
	v_add_f32_e32 v26, v50, v26
	v_add_f32_e32 v26, v51, v26
	v_max3_f32 v179, v185, v25, v73
	v_add_f32_e32 v26, v64, v26
	v_cndmask_b32_e64 v66, v48, 0, s[34:35]
	v_cvt_pk_bf16_f32 v48, v24, v27
	v_sub_f32_e32 v24, v185, v179
	v_add_f32_e32 v26, v65, v26
	v_cvt_pk_bf16_f32 v49, v49, v50
	v_cvt_pk_bf16_f32 v50, v51, v64
	v_exp_f32_e32 v64, v24
	v_sub_f32_e32 v24, v40, v179
	v_add_f32_e32 v178, v66, v26
	v_exp_f32_e32 v24, v24
	v_sub_f32_e32 v26, v41, v179
	v_exp_f32_e32 v26, v26
	v_sub_f32_e32 v27, v42, v179
	v_exp_f32_e32 v27, v27
	v_sub_f32_e32 v40, v43, v179
	v_exp_f32_e32 v40, v40
	v_sub_f32_e32 v16, v16, v179
	v_exp_f32_e32 v16, v16
	v_sub_f32_e32 v17, v17, v179
	v_add_f32_e32 v25, 0, v24
	v_exp_f32_e32 v17, v17
	v_add_f32_e32 v25, v26, v25
	v_add_f32_e32 v25, v27, v25
	v_add_f32_e32 v25, v40, v25
	v_cndmask_b32_e64 v41, v16, 0, s[46:47]
	v_add_f32_e32 v16, v41, v25
	v_cndmask_b32_e64 v25, v17, 0, s[48:49]
	v_sub_f32_e32 v17, v18, v179
	v_exp_f32_e32 v17, v17
	v_add_f32_e32 v16, v25, v16
	v_cvt_pk_bf16_f32 v51, v65, v66
	v_cvt_pk_bf16_f32 v18, v41, v25
	v_cndmask_b32_e64 v42, v17, 0, s[50:51]
	v_sub_f32_e32 v17, v19, v179
	v_exp_f32_e32 v17, v17
	v_add_f32_e32 v16, v42, v16
	v_fmac_f32_e32 v178, v184, v72
	v_cndmask_b32_e64 v19, v17, 0, s[52:53]
	v_add_f32_e32 v180, v19, v16
	v_cvt_pk_bf16_f32 v16, v24, v26
	v_cvt_pk_bf16_f32 v17, v27, v40
	v_cvt_pk_bf16_f32 v19, v42, v19
	v_pk_mul_f32 v[26:27], v[122:123], v[72:73] op_sel_hi:[1,0]
	v_pk_mul_f32 v[24:25], v[120:121], v[72:73] op_sel_hi:[1,0]
	v_pk_mul_f32 v[42:43], v[126:127], v[64:65] op_sel_hi:[1,0]
	v_pk_mul_f32 v[40:41], v[124:125], v[64:65] op_sel_hi:[1,0]
	s_waitcnt lgkmcnt(10)
	v_mfma_f32_16x16x32_bf16 v[24:27], v[100:103], v[48:51], v[24:27]
	v_fmac_f32_e32 v180, v186, v64
	v_mfma_f32_16x16x32_bf16 v[100:103], v[100:103], v[16:19], v[40:43]
	s_nop 2
	v_mul_f32_e64 v42, v98, v72
	v_mul_f32_e64 v43, v99, v72
	v_pk_mul_f32 v[40:41], v[96:97], v[72:73] op_sel_hi:[1,0]
	s_waitcnt lgkmcnt(8)
	s_nop 0
	v_mfma_f32_16x16x32_bf16 v[104:107], v[108:111], v[48:51], v[40:43]
	s_nop 2
	v_mul_f32_e64 v42, v130, v64
	v_mul_f32_e64 v43, v131, v64
	v_pk_mul_f32 v[40:41], v[128:129], v[64:65] op_sel_hi:[1,0]
	s_nop 1
	v_mfma_f32_16x16x32_bf16 v[108:111], v[108:111], v[16:19], v[40:43]
	s_nop 2
	v_mul_f32_e64 v42, v134, v72
	v_mul_f32_e64 v43, v135, v72
	v_pk_mul_f32 v[40:41], v[132:133], v[72:73] op_sel_hi:[1,0]
	s_waitcnt lgkmcnt(6)
	s_nop 0
	v_mfma_f32_16x16x32_bf16 v[112:115], v[116:119], v[48:51], v[40:43]
	s_nop 2
	v_mul_f32_e64 v42, v138, v64
	v_mul_f32_e64 v43, v139, v64
	v_pk_mul_f32 v[40:41], v[136:137], v[64:65] op_sel_hi:[1,0]
	s_nop 1
	v_mfma_f32_16x16x32_bf16 v[116:119], v[116:119], v[16:19], v[40:43]
	s_nop 2
	v_mul_f32_e64 v42, v142, v72
	v_mul_f32_e64 v43, v143, v72
	v_pk_mul_f32 v[40:41], v[140:141], v[72:73] op_sel_hi:[1,0]
	s_waitcnt lgkmcnt(4)
	s_nop 0
	v_mfma_f32_16x16x32_bf16 v[120:123], v[148:151], v[48:51], v[40:43]
	s_nop 2
	v_mul_f32_e64 v42, v146, v64
	v_mul_f32_e64 v43, v147, v64
	v_pk_mul_f32 v[40:41], v[144:145], v[64:65] op_sel_hi:[1,0]
	s_nop 1
	v_mfma_f32_16x16x32_bf16 v[124:127], v[148:151], v[16:19], v[40:43]
	v_lshlrev_b32_e32 v16, 2, v196
	v_add_u32_e32 v16, s76, v16
	v_med3_i32 v16, v16, 0, s75
	v_lshl_add_u32 v16, v16, 9, v152
	global_load_dwordx4 v[68:71], v16, s[98:99]
	v_lshlrev_b32_e32 v16, 2, v168
	v_add_u32_e32 v16, s76, v16
	v_med3_i32 v16, v16, 0, s75
	v_lshl_add_u32 v16, v16, 9, v152
	global_load_dwordx4 v[72:75], v16, s[98:99]
	v_lshlrev_b32_e32 v16, 2, v193
	v_add_u32_e32 v16, s76, v16
	v_med3_i32 v16, v16, 0, s75
	v_lshl_add_u32 v16, v16, 9, v152
	global_load_dwordx4 v[76:79], v16, s[98:99]
	v_lshlrev_b32_e32 v16, 2, v194
	v_add_u32_e32 v16, s76, v16
	v_med3_i32 v16, v16, 0, s75
	v_lshl_add_u32 v16, v16, 9, v152
	global_load_dwordx4 v[96:99], v16, s[98:99]
	v_or_b32_e32 v16, 0x180, v209
	v_add_u32_e32 v16, s76, v16
	v_med3_i32 v16, v16, 0, s75
	v_lshl_add_u32 v16, v16, 9, v158
	global_load_dwordx4 v[64:67], v16, s[100:101]
	global_load_dwordx4 v[48:51], v16, s[100:101] offset:64
	v_or_b32_e32 v16, 0x1c0, v209
	v_add_u32_e32 v16, s76, v16
	v_med3_i32 v16, v16, 0, s75
	v_lshl_add_u32 v16, v16, 9, v158
	global_load_dwordx4 v[40:43], v16, s[100:101]
	s_nop 0
	global_load_dwordx4 v[16:19], v16, s[100:101] offset:64
	ds_read_b64_tr_b16 v[142:143], v169 offset:6912
	ds_read_b64_tr_b16 v[140:141], v169 offset:4608
	ds_read_b64_tr_b16 v[136:137], v169 offset:4640
	ds_read_b64_tr_b16 v[138:139], v169 offset:6944
	ds_read_b64_tr_b16 v[132:133], v169 offset:4672
	ds_read_b64_tr_b16 v[134:135], v169 offset:6976
	ds_read_b64_tr_b16 v[128:129], v169 offset:4704
	ds_read_b64_tr_b16 v[130:131], v169 offset:7008
	s_waitcnt vmcnt(15)
	ds_write_b128 v241, v[80:83]
	s_waitcnt vmcnt(14)
	ds_write_b128 v242, v[84:87]
	s_waitcnt vmcnt(13)
	ds_write_b128 v243, v[88:91]
	s_waitcnt vmcnt(12)
	ds_write_b128 v244, v[92:95]
	v_mfma_f32_16x16x32_bf16 v[80:83], v[60:63], v[4:7], 0
	v_mfma_f32_16x16x32_bf16 v[84:87], v[36:39], v[4:7], 0
	v_mfma_f32_16x16x32_bf16 v[36:39], v[36:39], v[12:15], 0
	v_mfma_f32_16x16x32_bf16 v[80:83], v[56:59], v[8:11], v[80:83]
	v_mfma_f32_16x16x32_bf16 v[84:87], v[32:35], v[8:11], v[84:87]
	v_mfma_f32_16x16x32_bf16 v[32:35], v[32:35], v[0:3], v[36:39]
	s_nop 4
	v_sub_u32_e32 v36, v197, v176
	v_mfma_f32_16x16x32_bf16 v[60:63], v[60:63], v[12:15], 0
	v_add_u32_e32 v39, 1, v36
	v_cmp_gt_u32_e64 s[0:1], v39, v175
	v_cmp_gt_u32_e32 vcc, v36, v175
	s_nop 0
	v_cndmask_b32_e64 v81, v81, v246, s[0:1]
	s_nop 0
	v_cndmask_b32_e32 v80, v80, v246, vcc
	v_max_f32_e32 v38, 0xf149f2ca, v80
	v_mfma_f32_16x16x32_bf16 v[56:59], v[56:59], v[0:3], v[60:63]
	v_max_f32_e32 v38, v38, v81
	v_add_u32_e32 v39, 2, v36
	v_cmp_gt_u32_e64 s[22:23], v39, v175
	v_add_u32_e32 v60, 3, v36
	v_cmp_gt_u32_e64 s[24:25], v60, v175
	v_cndmask_b32_e64 v82, v82, v246, s[22:23]
	v_sub_u32_e32 v37, v197, v181
	v_cndmask_b32_e64 v83, v83, v246, s[24:25]
	v_max3_f32 v38, v38, v82, v83
	v_add_u32_e32 v39, 16, v36
	v_add_u32_e32 v60, 17, v36
	v_cmp_gt_u32_e64 s[26:27], v39, v175
	v_cmp_gt_u32_e64 s[28:29], v60, v175
	v_cmp_gt_u32_e64 s[38:39], v37, v252
	v_cndmask_b32_e64 v84, v84, v246, s[26:27]
	v_cndmask_b32_e64 v85, v85, v246, s[28:29]
	v_max3_f32 v38, v38, v84, v85
	v_add_u32_e32 v39, 18, v36
	v_add_u32_e32 v36, 19, v36
	v_cmp_gt_u32_e64 s[30:31], v39, v175
	v_cmp_gt_u32_e64 s[34:35], v36, v175
	v_add_u32_e32 v60, 3, v37
	v_cndmask_b32_e64 v86, v86, v246, s[30:31]
	v_cndmask_b32_e64 v87, v87, v246, s[34:35]
	v_max3_f32 v36, v38, v86, v87
	v_add_u32_e32 v39, 1, v37
	v_cmp_gt_u32_e64 s[40:41], v39, v252
	v_cndmask_b32_e64 v56, v56, v246, s[38:39]
	v_max_f32_e32 v38, 0xf149f2ca, v56
	v_cndmask_b32_e64 v57, v57, v246, s[40:41]
	v_max_f32_e32 v38, v38, v57
	v_add_u32_e32 v39, 2, v37
	v_cmp_gt_u32_e64 s[42:43], v39, v252
	v_cmp_gt_u32_e64 s[44:45], v60, v252
	s_nop 0
	v_cndmask_b32_e64 v58, v58, v246, s[42:43]
	v_cndmask_b32_e64 v59, v59, v246, s[44:45]
	v_max3_f32 v38, v38, v58, v59
	v_add_u32_e32 v39, 16, v37
	v_add_u32_e32 v60, 17, v37
	v_cmp_gt_u32_e64 s[46:47], v39, v252
	v_cmp_gt_u32_e64 s[48:49], v60, v252
	s_nop 0
	v_cndmask_b32_e64 v32, v32, v246, s[46:47]
	v_cndmask_b32_e64 v33, v33, v246, s[48:49]
	v_max3_f32 v38, v38, v32, v33
	v_add_u32_e32 v39, 18, v37
	v_add_u32_e32 v37, 19, v37
	v_cmp_gt_u32_e64 s[50:51], v39, v252
	v_cmp_gt_u32_e64 s[52:53], v37, v252
	s_nop 0
	v_cndmask_b32_e64 v34, v34, v246, s[50:51]
	v_cndmask_b32_e64 v35, v35, v246, s[52:53]
	v_max3_f32 v37, v38, v34, v35
	v_mov_b32_e32 v38, v36
	v_mov_b32_e32 v39, v36
	s_nop 1
	v_permlane32_swap_b32_e32 v38, v39
	v_max3_f32 v36, v36, v38, v39
	v_mov_b32_e32 v38, v37
	v_mov_b32_e32 v39, v37
	s_nop 1
	v_permlane32_swap_b32_e32 v38, v39
	v_max3_f32 v37, v37, v38, v39
	v_mov_b32_e32 v38, v36
	v_mov_b32_e32 v39, v36
	s_nop 1
	v_permlane16_swap_b32_e32 v38, v39
	v_max_f32_e32 v36, v36, v38
	v_mov_b32_e32 v38, v37
	v_mov_b32_e32 v61, v37
	v_max3_f32 v144, v177, v36, v39
	s_nop 0
	v_permlane16_swap_b32_e32 v38, v61
	v_sub_f32_e32 v36, v177, v144
	v_exp_f32_e32 v60, v36
	v_sub_f32_e32 v36, v80, v144
	v_max_f32_e32 v62, v37, v38
	v_exp_f32_e32 v36, v36
	v_sub_f32_e32 v38, v81, v144
	v_exp_f32_e32 v38, v38
	v_sub_f32_e32 v39, v82, v144
	v_exp_f32_e32 v39, v39
	v_sub_f32_e32 v63, v83, v144
	v_max3_f32 v146, v179, v62, v61
	v_exp_f32_e32 v63, v63
	v_sub_f32_e32 v80, v84, v144
	v_sub_f32_e32 v56, v56, v146
	v_exp_f32_e32 v80, v80
	v_sub_f32_e32 v81, v85, v144
	v_exp_f32_e32 v56, v56
	v_sub_f32_e32 v57, v57, v146
	v_add_f32_e32 v37, 0, v36
	v_exp_f32_e32 v81, v81
	v_sub_f32_e32 v82, v86, v144
	v_exp_f32_e32 v57, v57
	v_sub_f32_e32 v58, v58, v146
	v_add_f32_e32 v37, v38, v37
	v_exp_f32_e32 v82, v82
	v_sub_f32_e32 v83, v87, v144
	v_exp_f32_e32 v58, v58
	v_sub_f32_e32 v59, v59, v146
	v_add_f32_e32 v37, v39, v37
	v_exp_f32_e32 v83, v83
	v_exp_f32_e32 v59, v59
	v_sub_f32_e32 v32, v32, v146
	v_add_f32_e32 v37, v63, v37
	v_sub_f32_e32 v61, v179, v146
	v_exp_f32_e32 v32, v32
	v_sub_f32_e32 v33, v33, v146
	v_add_f32_e32 v37, v80, v37
	v_exp_f32_e32 v62, v61
	v_add_f32_e32 v61, 0, v56
	v_exp_f32_e32 v33, v33
	v_add_f32_e32 v37, v81, v37
	v_add_f32_e32 v61, v57, v61
	v_add_f32_e32 v37, v82, v37
	v_add_f32_e32 v61, v58, v61
	v_add_f32_e32 v145, v83, v37
	v_cvt_pk_bf16_f32 v37, v39, v63
	v_add_f32_e32 v61, v59, v61
	v_cndmask_b32_e64 v63, v32, 0, s[46:47]
	v_add_f32_e32 v32, v63, v61
	v_cndmask_b32_e64 v61, v33, 0, s[48:49]
	v_sub_f32_e32 v33, v34, v146
	v_exp_f32_e32 v33, v33
	v_cvt_pk_bf16_f32 v36, v36, v38
	v_cvt_pk_bf16_f32 v38, v80, v81
	v_add_f32_e32 v32, v61, v32
	v_cndmask_b32_e64 v80, v33, 0, s[50:51]
	v_sub_f32_e32 v33, v35, v146
	v_exp_f32_e32 v33, v33
	v_cvt_pk_bf16_f32 v39, v82, v83
	v_add_f32_e32 v32, v80, v32
	v_pk_mul_f32 v[26:27], v[26:27], v[60:61] op_sel_hi:[1,0]
	v_cndmask_b32_e64 v35, v33, 0, s[52:53]
	v_pk_mul_f32 v[24:25], v[24:25], v[60:61] op_sel_hi:[1,0]
	v_add_f32_e32 v147, v35, v32
	v_cvt_pk_bf16_f32 v32, v56, v57
	v_cvt_pk_bf16_f32 v33, v58, v59
	v_cvt_pk_bf16_f32 v34, v63, v61
	v_cvt_pk_bf16_f32 v35, v80, v35
	s_waitcnt lgkmcnt(10)
	v_mfma_f32_16x16x32_bf16 v[92:95], v[140:143], v[36:39], v[24:27]
	v_fmac_f32_e32 v145, v178, v60
	v_fmac_f32_e32 v147, v180, v62
	s_nop 0
	v_pk_mul_f32 v[26:27], v[102:103], v[62:63] op_sel_hi:[1,0]
	v_pk_mul_f32 v[24:25], v[100:101], v[62:63] op_sel_hi:[1,0]
	s_nop 1
	v_mfma_f32_16x16x32_bf16 v[100:103], v[140:143], v[32:35], v[24:27]
	s_nop 2
	v_mul_f32_e64 v26, v106, v60
	v_mul_f32_e64 v27, v107, v60
	v_pk_mul_f32 v[24:25], v[104:105], v[60:61] op_sel_hi:[1,0]
	s_waitcnt lgkmcnt(8)
	s_nop 0
	v_mfma_f32_16x16x32_bf16 v[104:107], v[136:139], v[36:39], v[24:27]
	s_nop 2
	v_mul_f32_e64 v26, v110, v62
	v_mul_f32_e64 v27, v111, v62
	v_pk_mul_f32 v[24:25], v[108:109], v[62:63] op_sel_hi:[1,0]
	s_nop 1
	v_mfma_f32_16x16x32_bf16 v[108:111], v[136:139], v[32:35], v[24:27]
	s_nop 2
	v_mul_f32_e64 v26, v114, v60
	v_mul_f32_e64 v27, v115, v60
	v_pk_mul_f32 v[24:25], v[112:113], v[60:61] op_sel_hi:[1,0]
	s_waitcnt lgkmcnt(6)
	s_nop 0
	v_mfma_f32_16x16x32_bf16 v[112:115], v[132:135], v[36:39], v[24:27]
	s_nop 2
	v_mul_f32_e64 v26, v118, v62
	v_mul_f32_e64 v27, v119, v62
	v_pk_mul_f32 v[24:25], v[116:117], v[62:63] op_sel_hi:[1,0]
	s_nop 1
	v_mfma_f32_16x16x32_bf16 v[116:119], v[132:135], v[32:35], v[24:27]
	s_nop 2
	v_mul_f32_e64 v26, v122, v60
	v_mul_f32_e64 v27, v123, v60
	v_pk_mul_f32 v[24:25], v[120:121], v[60:61] op_sel_hi:[1,0]
	s_waitcnt lgkmcnt(4)
	s_nop 0
	v_mfma_f32_16x16x32_bf16 v[120:123], v[128:131], v[36:39], v[24:27]
	s_nop 2
	v_mul_f32_e64 v26, v126, v62
	v_mul_f32_e64 v27, v127, v62
	v_pk_mul_f32 v[24:25], v[124:125], v[62:63] op_sel_hi:[1,0]
	s_nop 1
	v_mfma_f32_16x16x32_bf16 v[124:127], v[128:131], v[32:35], v[24:27]
	s_nop 2
	v_add_u32_e32 v24, s76, v214
	v_med3_i32 v24, v24, 0, s75
	v_lshl_add_u32 v24, v24, 9, v152
	global_load_dwordx4 v[60:63], v24, s[98:99]
	v_add_u32_e32 v24, s76, v216
	v_med3_i32 v24, v24, 0, s75
	v_lshl_add_u32 v24, v24, 9, v152
	global_load_dwordx4 v[80:83], v24, s[98:99]
	v_add_u32_e32 v24, s76, v218
	v_med3_i32 v24, v24, 0, s75
	v_lshl_add_u32 v24, v24, 9, v152
	global_load_dwordx4 v[84:87], v24, s[98:99]
	v_add_u32_e32 v24, s76, v220
	v_med3_i32 v24, v24, 0, s75
	v_lshl_add_u32 v24, v24, 9, v152
	global_load_dwordx4 v[88:91], v24, s[98:99]
	v_add_u32_e32 v24, s76, v221
	v_med3_i32 v24, v24, 0, s75
	v_lshl_add_u32 v24, v24, 9, v158
	global_load_dwordx4 v[56:59], v24, s[100:101]
	global_load_dwordx4 v[36:39], v24, s[100:101] offset:64
	v_or_b32_e32 v24, 0x100, v221
	v_add_u32_e32 v24, s76, v24
	v_med3_i32 v24, v24, 0, s75
	v_lshl_add_u32 v24, v24, 9, v158
	global_load_dwordx4 v[32:35], v24, s[100:101]
	s_nop 0
	global_load_dwordx4 v[24:27], v24, s[100:101] offset:64
	ds_read_b64_tr_b16 v[142:143], v169 offset:2304
	ds_read_b64_tr_b16 v[140:141], v169
	ds_read_b64_tr_b16 v[136:137], v169 offset:32
	ds_read_b64_tr_b16 v[138:139], v169 offset:2336
	ds_read_b64_tr_b16 v[132:133], v169 offset:64
	ds_read_b64_tr_b16 v[134:135], v169 offset:2368
	ds_read_b64_tr_b16 v[128:129], v169 offset:96
	ds_read_b64_tr_b16 v[130:131], v169 offset:2400
	s_waitcnt vmcnt(15)
	ds_write_b128 v241, v[68:71] offset:4608
	s_waitcnt vmcnt(14)
	ds_write_b128 v242, v[72:75] offset:4608
	s_waitcnt vmcnt(13)
	ds_write_b128 v243, v[76:79] offset:4608
	s_waitcnt vmcnt(12)
	ds_write_b128 v244, v[96:99] offset:4608
	v_mfma_f32_16x16x32_bf16 v[68:71], v[52:55], v[4:7], 0
	v_mfma_f32_16x16x32_bf16 v[72:75], v[28:31], v[4:7], 0
	v_mfma_f32_16x16x32_bf16 v[28:31], v[28:31], v[12:15], 0
	v_mfma_f32_16x16x32_bf16 v[68:71], v[44:47], v[8:11], v[68:71]
	v_mfma_f32_16x16x32_bf16 v[72:75], v[20:23], v[8:11], v[72:75]
	v_mfma_f32_16x16x32_bf16 v[20:23], v[20:23], v[0:3], v[28:31]
	s_nop 4
	v_sub_u32_e32 v28, v198, v176
	v_mfma_f32_16x16x32_bf16 v[52:55], v[52:55], v[12:15], 0
	v_add_u32_e32 v31, 1, v28
	v_cmp_gt_u32_e64 s[0:1], v31, v175
	v_cmp_gt_u32_e32 vcc, v28, v175
	s_nop 0
	v_cndmask_b32_e64 v69, v69, v246, s[0:1]
	s_nop 0
	v_cndmask_b32_e32 v68, v68, v246, vcc
	v_max_f32_e32 v30, 0xf149f2ca, v68
	v_mfma_f32_16x16x32_bf16 v[44:47], v[44:47], v[0:3], v[52:55]
	v_max_f32_e32 v30, v30, v69
	v_add_u32_e32 v31, 2, v28
	v_cmp_gt_u32_e64 s[22:23], v31, v175
	v_add_u32_e32 v52, 3, v28
	v_cmp_gt_u32_e64 s[24:25], v52, v175
	v_cndmask_b32_e64 v70, v70, v246, s[22:23]
	v_sub_u32_e32 v29, v198, v181
	v_cndmask_b32_e64 v71, v71, v246, s[24:25]
	v_max3_f32 v30, v30, v70, v71
	v_add_u32_e32 v31, 16, v28
	v_add_u32_e32 v52, 17, v28
	v_cmp_gt_u32_e64 s[26:27], v31, v175
	v_cmp_gt_u32_e64 s[28:29], v52, v175
	v_cmp_gt_u32_e64 s[38:39], v29, v252
	v_cndmask_b32_e64 v72, v72, v246, s[26:27]
	v_cndmask_b32_e64 v73, v73, v246, s[28:29]
	v_max3_f32 v30, v30, v72, v73
	v_add_u32_e32 v31, 18, v28
	v_add_u32_e32 v28, 19, v28
	v_cmp_gt_u32_e64 s[30:31], v31, v175
	v_cmp_gt_u32_e64 s[34:35], v28, v175
	v_add_u32_e32 v52, 3, v29
	v_cndmask_b32_e64 v74, v74, v246, s[30:31]
	v_cndmask_b32_e64 v75, v75, v246, s[34:35]
	v_max3_f32 v28, v30, v74, v75
	v_add_u32_e32 v31, 1, v29
	v_cmp_gt_u32_e64 s[40:41], v31, v252
	v_cndmask_b32_e64 v44, v44, v246, s[38:39]
	v_max_f32_e32 v30, 0xf149f2ca, v44
	v_cndmask_b32_e64 v45, v45, v246, s[40:41]
	v_max_f32_e32 v30, v30, v45
	v_add_u32_e32 v31, 2, v29
	v_cmp_gt_u32_e64 s[42:43], v31, v252
	v_cmp_gt_u32_e64 s[44:45], v52, v252
	s_nop 0
	v_cndmask_b32_e64 v46, v46, v246, s[42:43]
	v_cndmask_b32_e64 v47, v47, v246, s[44:45]
	v_max3_f32 v30, v30, v46, v47
	v_add_u32_e32 v31, 16, v29
	v_add_u32_e32 v52, 17, v29
	v_cmp_gt_u32_e64 s[46:47], v31, v252
	v_cmp_gt_u32_e64 s[48:49], v52, v252
	s_nop 0
	v_cndmask_b32_e64 v20, v20, v246, s[46:47]
	v_cndmask_b32_e64 v21, v21, v246, s[48:49]
	v_max3_f32 v30, v30, v20, v21
	v_add_u32_e32 v31, 18, v29
	v_add_u32_e32 v29, 19, v29
	v_cmp_gt_u32_e64 s[50:51], v31, v252
	v_cmp_gt_u32_e64 s[52:53], v29, v252
	s_nop 0
	v_cndmask_b32_e64 v22, v22, v246, s[50:51]
	v_cndmask_b32_e64 v23, v23, v246, s[52:53]
	v_max3_f32 v29, v30, v22, v23
	v_mov_b32_e32 v30, v28
	v_mov_b32_e32 v31, v28
	s_nop 1
	v_permlane32_swap_b32_e32 v30, v31
	v_max3_f32 v28, v28, v30, v31
	v_mov_b32_e32 v30, v29
	v_mov_b32_e32 v31, v29
	s_nop 1
	v_permlane32_swap_b32_e32 v30, v31
	v_max3_f32 v29, v29, v30, v31
	v_mov_b32_e32 v30, v28
	v_mov_b32_e32 v31, v28
	s_nop 1
	v_permlane16_swap_b32_e32 v30, v31
	v_max_f32_e32 v28, v28, v30
	v_mov_b32_e32 v30, v29
	v_mov_b32_e32 v53, v29
	v_max3_f32 v148, v144, v28, v31
	s_nop 0
	v_permlane16_swap_b32_e32 v30, v53
	v_sub_f32_e32 v28, v144, v148
	v_exp_f32_e32 v52, v28
	v_sub_f32_e32 v28, v68, v148
	v_max_f32_e32 v54, v29, v30
	v_exp_f32_e32 v28, v28
	v_sub_f32_e32 v30, v69, v148
	v_exp_f32_e32 v30, v30
	v_sub_f32_e32 v31, v70, v148
	v_exp_f32_e32 v31, v31
	v_sub_f32_e32 v55, v71, v148
	v_max3_f32 v149, v146, v54, v53
	v_exp_f32_e32 v55, v55
	v_sub_f32_e32 v68, v72, v148
	v_sub_f32_e32 v44, v44, v149
	v_exp_f32_e32 v68, v68
	v_sub_f32_e32 v69, v73, v148
	v_exp_f32_e32 v44, v44
	v_sub_f32_e32 v45, v45, v149
	v_add_f32_e32 v29, 0, v28
	v_exp_f32_e32 v69, v69
	v_sub_f32_e32 v70, v74, v148
	v_exp_f32_e32 v45, v45
	v_sub_f32_e32 v46, v46, v149
	v_add_f32_e32 v29, v30, v29
	v_exp_f32_e32 v70, v70
	v_sub_f32_e32 v71, v75, v148
	v_exp_f32_e32 v46, v46
	v_sub_f32_e32 v47, v47, v149
	v_add_f32_e32 v29, v31, v29
	v_exp_f32_e32 v71, v71
	v_exp_f32_e32 v47, v47
	v_sub_f32_e32 v20, v20, v149
	v_add_f32_e32 v29, v55, v29
	v_sub_f32_e32 v53, v146, v149
	v_exp_f32_e32 v20, v20
	v_sub_f32_e32 v21, v21, v149
	v_add_f32_e32 v29, v68, v29
	v_exp_f32_e32 v54, v53
	v_add_f32_e32 v53, 0, v44
	v_exp_f32_e32 v21, v21
	v_add_f32_e32 v29, v69, v29
	v_add_f32_e32 v53, v45, v53
	v_add_f32_e32 v29, v70, v29
	v_add_f32_e32 v53, v46, v53
	v_add_f32_e32 v144, v71, v29
	v_cvt_pk_bf16_f32 v29, v31, v55
	v_add_f32_e32 v53, v47, v53
	v_cndmask_b32_e64 v55, v20, 0, s[46:47]
	v_add_f32_e32 v20, v55, v53
	v_cndmask_b32_e64 v53, v21, 0, s[48:49]
	v_sub_f32_e32 v21, v22, v149
	v_exp_f32_e32 v21, v21
	v_cvt_pk_bf16_f32 v28, v28, v30
	v_cvt_pk_bf16_f32 v30, v68, v69
	v_add_f32_e32 v20, v53, v20
	v_cndmask_b32_e64 v68, v21, 0, s[50:51]
	v_sub_f32_e32 v21, v23, v149
	v_exp_f32_e32 v21, v21
	v_add_f32_e32 v20, v68, v20
	v_fmac_f32_e32 v144, v145, v52
	v_cvt_pk_bf16_f32 v31, v70, v71
	v_cndmask_b32_e64 v23, v21, 0, s[52:53]
	v_add_f32_e32 v145, v23, v20
	v_cvt_pk_bf16_f32 v20, v44, v45
	v_cvt_pk_bf16_f32 v21, v46, v47
	v_pk_mul_f32 v[46:47], v[94:95], v[52:53] op_sel_hi:[1,0]
	v_pk_mul_f32 v[44:45], v[92:93], v[52:53] op_sel_hi:[1,0]
	v_cvt_pk_bf16_f32 v22, v55, v53
	v_cvt_pk_bf16_f32 v23, v68, v23
	s_waitcnt lgkmcnt(10)
	v_mfma_f32_16x16x32_bf16 v[96:99], v[140:143], v[28:31], v[44:47]
	v_fmac_f32_e32 v145, v147, v54
	s_nop 1
	v_pk_mul_f32 v[46:47], v[102:103], v[54:55] op_sel_hi:[1,0]
	v_pk_mul_f32 v[44:45], v[100:101], v[54:55] op_sel_hi:[1,0]
	s_nop 1
	v_mfma_f32_16x16x32_bf16 v[100:103], v[140:143], v[20:23], v[44:47]
	s_nop 2
	v_mul_f32_e64 v46, v106, v52
	v_mul_f32_e64 v47, v107, v52
	v_pk_mul_f32 v[44:45], v[104:105], v[52:53] op_sel_hi:[1,0]
	s_waitcnt lgkmcnt(8)
	s_nop 0
	v_mfma_f32_16x16x32_bf16 v[104:107], v[136:139], v[28:31], v[44:47]
	s_nop 2
	v_mul_f32_e64 v46, v110, v54
	v_mul_f32_e64 v47, v111, v54
	v_pk_mul_f32 v[44:45], v[108:109], v[54:55] op_sel_hi:[1,0]
	s_nop 1
	v_mfma_f32_16x16x32_bf16 v[108:111], v[136:139], v[20:23], v[44:47]
	s_nop 2
	v_mul_f32_e64 v46, v114, v52
	v_mul_f32_e64 v47, v115, v52
	v_pk_mul_f32 v[44:45], v[112:113], v[52:53] op_sel_hi:[1,0]
	s_waitcnt lgkmcnt(6)
	s_nop 0
	v_mfma_f32_16x16x32_bf16 v[112:115], v[132:135], v[28:31], v[44:47]
	s_nop 2
	v_mul_f32_e64 v46, v118, v54
	v_mul_f32_e64 v47, v119, v54
	v_pk_mul_f32 v[44:45], v[116:117], v[54:55] op_sel_hi:[1,0]
	s_nop 1
	v_mfma_f32_16x16x32_bf16 v[116:119], v[132:135], v[20:23], v[44:47]
	s_nop 2
	v_mul_f32_e64 v46, v122, v52
	v_mul_f32_e64 v47, v123, v52
	v_pk_mul_f32 v[44:45], v[120:121], v[52:53] op_sel_hi:[1,0]
	s_waitcnt lgkmcnt(4)
	s_nop 0
	v_mfma_f32_16x16x32_bf16 v[120:123], v[128:131], v[28:31], v[44:47]
	v_mul_f32_e64 v30, v126, v54
	v_mul_f32_e64 v31, v127, v54
	v_pk_mul_f32 v[28:29], v[124:125], v[54:55] op_sel_hi:[1,0]
	s_nop 1
	v_mfma_f32_16x16x32_bf16 v[124:127], v[128:131], v[20:23], v[28:31]
	v_add_u32_e32 v20, s76, v222
	v_med3_i32 v20, v20, 0, s75
	v_lshl_add_u32 v20, v20, 9, v152
	global_load_dwordx4 v[68:71], v20, s[98:99]
	v_add_u32_e32 v20, s76, v223
	v_med3_i32 v20, v20, 0, s75
	v_lshl_add_u32 v20, v20, 9, v152
	global_load_dwordx4 v[72:75], v20, s[98:99]
	v_add_u32_e32 v20, s76, v224
	v_med3_i32 v20, v20, 0, s75
	v_lshl_add_u32 v20, v20, 9, v152
	global_load_dwordx4 v[76:79], v20, s[98:99]
	v_add_u32_e32 v20, s76, v225
	v_med3_i32 v20, v20, 0, s75
	v_lshl_add_u32 v20, v20, 9, v152
	global_load_dwordx4 v[92:95], v20, s[98:99]
	v_add_u32_e32 v20, s76, v226
	v_med3_i32 v20, v20, 0, s75
	v_lshl_add_u32 v20, v20, 9, v158
	global_load_dwordx4 v[52:55], v20, s[100:101]
	global_load_dwordx4 v[44:47], v20, s[100:101] offset:64
	v_add_u32_e32 v20, s76, v227
	v_med3_i32 v20, v20, 0, s75
	v_lshl_add_u32 v20, v20, 9, v158
	global_load_dwordx4 v[28:31], v20, s[100:101]
	s_nop 0
	global_load_dwordx4 v[20:23], v20, s[100:101] offset:64
	ds_read_b64_tr_b16 v[142:143], v169 offset:6912
	ds_read_b64_tr_b16 v[140:141], v169 offset:4608
	ds_read_b64_tr_b16 v[136:137], v169 offset:4640
	ds_read_b64_tr_b16 v[138:139], v169 offset:6944
	ds_read_b64_tr_b16 v[132:133], v169 offset:4672
	ds_read_b64_tr_b16 v[134:135], v169 offset:6976
	ds_read_b64_tr_b16 v[128:129], v169 offset:4704
	ds_read_b64_tr_b16 v[130:131], v169 offset:7008
	s_waitcnt vmcnt(15)
	ds_write_b128 v241, v[60:63]
	s_waitcnt vmcnt(14)
	ds_write_b128 v242, v[80:83]
	s_waitcnt vmcnt(13)
	ds_write_b128 v243, v[84:87]
	s_waitcnt vmcnt(12)
	ds_write_b128 v244, v[88:91]
	v_mfma_f32_16x16x32_bf16 v[60:63], v[64:67], v[4:7], 0
	v_mfma_f32_16x16x32_bf16 v[80:83], v[40:43], v[4:7], 0
	v_mfma_f32_16x16x32_bf16 v[40:43], v[40:43], v[12:15], 0
	v_mfma_f32_16x16x32_bf16 v[60:63], v[48:51], v[8:11], v[60:63]
	v_mfma_f32_16x16x32_bf16 v[80:83], v[16:19], v[8:11], v[80:83]
	v_mfma_f32_16x16x32_bf16 v[16:19], v[16:19], v[0:3], v[40:43]
	s_nop 4
	v_sub_u32_e32 v40, v199, v176
	v_mfma_f32_16x16x32_bf16 v[64:67], v[64:67], v[12:15], 0
	v_add_u32_e32 v43, 1, v40
	v_cmp_gt_u32_e64 s[0:1], v43, v175
	v_cmp_gt_u32_e32 vcc, v40, v175
	s_nop 0
	v_cndmask_b32_e64 v61, v61, v246, s[0:1]
	s_nop 0
	v_cndmask_b32_e32 v60, v60, v246, vcc
	v_max_f32_e32 v42, 0xf149f2ca, v60
	v_mfma_f32_16x16x32_bf16 v[48:51], v[48:51], v[0:3], v[64:67]
	v_max_f32_e32 v42, v42, v61
	v_add_u32_e32 v43, 2, v40
	v_cmp_gt_u32_e64 s[22:23], v43, v175
	v_add_u32_e32 v64, 3, v40
	v_cmp_gt_u32_e64 s[24:25], v64, v175
	v_cndmask_b32_e64 v62, v62, v246, s[22:23]
	v_sub_u32_e32 v41, v199, v181
	v_cndmask_b32_e64 v63, v63, v246, s[24:25]
	v_max3_f32 v42, v42, v62, v63
	v_add_u32_e32 v43, 16, v40
	v_add_u32_e32 v64, 17, v40
	v_cmp_gt_u32_e64 s[26:27], v43, v175
	v_cmp_gt_u32_e64 s[28:29], v64, v175
	v_cmp_gt_u32_e64 s[38:39], v41, v252
	v_cndmask_b32_e64 v80, v80, v246, s[26:27]
	v_cndmask_b32_e64 v81, v81, v246, s[28:29]
	v_max3_f32 v42, v42, v80, v81
	v_add_u32_e32 v43, 18, v40
	v_add_u32_e32 v40, 19, v40
	v_cmp_gt_u32_e64 s[30:31], v43, v175
	v_cmp_gt_u32_e64 s[34:35], v40, v175
	v_add_u32_e32 v64, 3, v41
	v_cndmask_b32_e64 v82, v82, v246, s[30:31]
	v_cndmask_b32_e64 v83, v83, v246, s[34:35]
	v_max3_f32 v40, v42, v82, v83
	v_add_u32_e32 v43, 1, v41
	v_cmp_gt_u32_e64 s[40:41], v43, v252
	v_cndmask_b32_e64 v48, v48, v246, s[38:39]
	v_max_f32_e32 v42, 0xf149f2ca, v48
	v_cndmask_b32_e64 v49, v49, v246, s[40:41]
	v_max_f32_e32 v42, v42, v49
	v_add_u32_e32 v43, 2, v41
	v_cmp_gt_u32_e64 s[42:43], v43, v252
	v_cmp_gt_u32_e64 s[44:45], v64, v252
	s_nop 0
	v_cndmask_b32_e64 v50, v50, v246, s[42:43]
	v_cndmask_b32_e64 v51, v51, v246, s[44:45]
	v_max3_f32 v42, v42, v50, v51
	v_add_u32_e32 v43, 16, v41
	v_add_u32_e32 v64, 17, v41
	v_cmp_gt_u32_e64 s[46:47], v43, v252
	v_cmp_gt_u32_e64 s[48:49], v64, v252
	s_nop 0
	v_cndmask_b32_e64 v16, v16, v246, s[46:47]
	v_cndmask_b32_e64 v17, v17, v246, s[48:49]
	v_max3_f32 v42, v42, v16, v17
	v_add_u32_e32 v43, 18, v41
	v_add_u32_e32 v41, 19, v41
	v_cmp_gt_u32_e64 s[50:51], v43, v252
	v_cmp_gt_u32_e64 s[52:53], v41, v252
	s_nop 0
	v_cndmask_b32_e64 v18, v18, v246, s[50:51]
	v_cndmask_b32_e64 v19, v19, v246, s[52:53]
	v_max3_f32 v41, v42, v18, v19
	v_mov_b32_e32 v42, v40
	v_mov_b32_e32 v43, v40
	s_nop 1
	v_permlane32_swap_b32_e32 v42, v43
	v_max3_f32 v40, v40, v42, v43
	v_mov_b32_e32 v42, v41
	v_mov_b32_e32 v43, v41
	s_nop 1
	v_permlane32_swap_b32_e32 v42, v43
	v_max3_f32 v41, v41, v42, v43
	v_mov_b32_e32 v42, v40
	v_mov_b32_e32 v43, v40
	s_nop 1
	v_permlane16_swap_b32_e32 v42, v43
	v_max_f32_e32 v40, v40, v42
	v_max3_f32 v147, v148, v40, v43
	v_sub_f32_e32 v40, v148, v147
	v_exp_f32_e32 v84, v40
	v_sub_f32_e32 v40, v60, v147
	v_exp_f32_e32 v40, v40
	v_mov_b32_e32 v42, v41
	v_mov_b32_e32 v64, v41
	s_nop 1
	v_permlane16_swap_b32_e32 v42, v64
	v_cndmask_b32_e64 v85, v40, 0, vcc
	v_sub_f32_e32 v40, v61, v147
	v_exp_f32_e32 v40, v40
	v_max_f32_e32 v65, v41, v42
	v_max3_f32 v146, v149, v65, v64
	v_cndmask_b32_e64 v61, v40, 0, s[0:1]
	v_sub_f32_e32 v40, v62, v147
	v_exp_f32_e32 v40, v40
	v_sub_f32_e32 v48, v48, v146
	v_sub_f32_e32 v16, v16, v146
	v_exp_f32_e32 v48, v48
	v_cndmask_b32_e64 v62, v40, 0, s[22:23]
	v_sub_f32_e32 v40, v63, v147
	v_exp_f32_e32 v40, v40
	v_exp_f32_e32 v16, v16
	v_cndmask_b32_e64 v86, v48, 0, s[38:39]
	v_sub_f32_e32 v48, v49, v146
	v_cndmask_b32_e64 v63, v40, 0, s[24:25]
	v_sub_f32_e32 v40, v80, v147
	v_exp_f32_e32 v40, v40
	v_cndmask_b32_e64 v90, v16, 0, s[46:47]
	v_sub_f32_e32 v16, v17, v146
	v_exp_f32_e32 v48, v48
	v_cndmask_b32_e64 v80, v40, 0, s[26:27]
	v_sub_f32_e32 v40, v81, v147
	v_exp_f32_e32 v40, v40
	v_exp_f32_e32 v16, v16
	v_cndmask_b32_e64 v87, v48, 0, s[40:41]
	v_sub_f32_e32 v48, v50, v146
	v_cndmask_b32_e64 v81, v40, 0, s[28:29]
	v_sub_f32_e32 v40, v82, v147
	v_exp_f32_e32 v40, v40
	v_cndmask_b32_e64 v91, v16, 0, s[48:49]
	v_sub_f32_e32 v16, v18, v146
	v_exp_f32_e32 v48, v48
	v_exp_f32_e32 v16, v16
	v_cndmask_b32_e64 v82, v40, 0, s[30:31]
	v_sub_f32_e32 v40, v83, v147
	v_exp_f32_e32 v40, v40
	v_cndmask_b32_e64 v88, v48, 0, s[42:43]
	v_sub_f32_e32 v48, v51, v146
	v_cndmask_b32_e64 v148, v16, 0, s[50:51]
	v_sub_f32_e32 v16, v19, v146
	v_sub_f32_e32 v60, v149, v146
	v_exp_f32_e32 v48, v48
	v_exp_f32_e32 v16, v16
	v_exp_f32_e32 v60, v60
	v_cndmask_b32_e64 v83, v40, 0, s[34:35]
	v_cvt_pk_bf16_f32 v40, v85, v61
	v_cvt_pk_bf16_f32 v41, v62, v63
	v_cvt_pk_bf16_f32 v42, v80, v81
	v_cvt_pk_bf16_f32 v43, v82, v83
	v_cndmask_b32_e64 v89, v48, 0, s[44:45]
	v_cndmask_b32_e64 v149, v16, 0, s[52:53]
	v_pk_mul_f32 v[50:51], v[98:99], v[84:85] op_sel_hi:[1,0]
	v_pk_mul_f32 v[48:49], v[96:97], v[84:85] op_sel_hi:[1,0]
	v_cvt_pk_bf16_f32 v16, v86, v87
	v_cvt_pk_bf16_f32 v17, v88, v89
	v_cvt_pk_bf16_f32 v18, v90, v91
	v_cvt_pk_bf16_f32 v19, v148, v149
	s_waitcnt lgkmcnt(10)
	v_mfma_f32_16x16x32_bf16 v[64:67], v[140:143], v[40:43], v[48:51]
	s_cselect_b64 s[38:39], -1, 0
	s_add_i32 s0, s76, 0xfffffc00
	s_min_i32 s1, s0, 0
	v_pk_mul_f32 v[50:51], v[102:103], v[60:61] op_sel_hi:[1,0]
	v_pk_mul_f32 v[48:49], v[100:101], v[60:61] op_sel_hi:[1,0]
	s_sub_i32 s1, 15, s1
	s_ashr_i32 s1, s1, 4
	v_mfma_f32_16x16x32_bf16 v[100:103], v[140:143], v[16:19], v[48:51]
	s_sub_i32 s0, s75, s0
	s_ashr_i32 s0, s0, 4
	s_or_b32 s40, s76, 8
	v_pk_mul_f32 v[50:51], v[106:107], v[84:85] op_sel_hi:[1,0]
	v_pk_mul_f32 v[48:49], v[104:105], v[84:85] op_sel_hi:[1,0]
	s_lshl_b32 s56, s56, 7
	s_add_i32 s71, s71, s78
	s_waitcnt lgkmcnt(8)
	v_mfma_f32_16x16x32_bf16 v[104:107], v[136:139], v[40:43], v[48:51]
	s_nop 2
	v_mul_f32_e64 v50, v110, v60
	v_mul_f32_e64 v51, v111, v60
	v_pk_mul_f32 v[48:49], v[108:109], v[60:61] op_sel_hi:[1,0]
	s_nop 1
	v_mfma_f32_16x16x32_bf16 v[108:111], v[136:139], v[16:19], v[48:51]
	s_nop 2
	v_mul_f32_e64 v50, v114, v84
	v_mul_f32_e64 v51, v115, v84
	v_pk_mul_f32 v[48:49], v[112:113], v[84:85] op_sel_hi:[1,0]
	s_waitcnt lgkmcnt(6)
	s_nop 0
	v_mfma_f32_16x16x32_bf16 v[112:115], v[132:135], v[40:43], v[48:51]
	s_nop 2
	v_mul_f32_e64 v50, v118, v60
	v_mul_f32_e64 v51, v119, v60
	v_pk_mul_f32 v[48:49], v[116:117], v[60:61] op_sel_hi:[1,0]
	s_nop 1
	v_mfma_f32_16x16x32_bf16 v[116:119], v[132:135], v[16:19], v[48:51]
	s_nop 2
	v_mul_f32_e64 v50, v122, v84
	v_mul_f32_e64 v51, v123, v84
	v_pk_mul_f32 v[48:49], v[120:121], v[84:85] op_sel_hi:[1,0]
	s_waitcnt lgkmcnt(4)
	s_nop 0
	v_mfma_f32_16x16x32_bf16 v[120:123], v[128:131], v[40:43], v[48:51]
	v_mul_f32_e64 v42, v126, v60
	v_mul_f32_e64 v43, v127, v60
	v_pk_mul_f32 v[40:41], v[124:125], v[60:61] op_sel_hi:[1,0]
	s_nop 1
	v_mfma_f32_16x16x32_bf16 v[124:127], v[128:131], v[16:19], v[40:43]
	v_add_f32_e32 v16, 0, v86
	v_add_f32_e32 v16, v87, v16
	v_add_f32_e32 v16, v88, v16
	v_add_f32_e32 v16, v89, v16
	v_add_f32_e32 v16, v90, v16
	v_add_f32_e32 v16, v91, v16
	v_add_f32_e32 v16, v148, v16
	v_add_f32_e32 v151, v149, v16
	v_add_f32_e32 v16, 0, v85
	v_add_f32_e32 v16, v61, v16
	v_add_f32_e32 v16, v62, v16
	v_add_f32_e32 v16, v63, v16
	v_add_f32_e32 v16, v80, v16
	v_add_f32_e32 v16, v81, v16
	v_add_f32_e32 v16, v82, v16
	v_fmac_f32_e32 v151, v145, v60
	v_add_f32_e32 v145, v83, v16
	v_add_u32_e32 v16, s76, v213
	v_fmac_f32_e32 v145, v144, v84
	v_ashrrev_i32_e32 v148, 4, v250
	v_med3_i32 v16, v16, 0, s75
	v_lshl_add_u32 v16, v16, 9, v152
	global_load_dwordx4 v[80:83], v16, s[98:99]
	v_add_u32_e32 v16, s76, v215
	v_max_i32_e32 v150, s1, v148
	s_nop 0
	v_med3_i32 v16, v16, 0, s75
	v_lshl_add_u32 v16, v16, 9, v152
	global_load_dwordx4 v[84:87], v16, s[98:99]
	v_add_u32_e32 v16, s76, v217
	v_med3_i32 v16, v16, 0, s75
	v_lshl_add_u32 v16, v16, 9, v152
	global_load_dwordx4 v[88:91], v16, s[98:99]
	v_add_u32_e32 v16, s76, v219
	v_med3_i32 v16, v16, 0, s75
	v_lshl_add_u32 v16, v16, 9, v152
	global_load_dwordx4 v[96:99], v16, s[98:99]
	v_min_i32_e32 v16, s75, v251
	v_cndmask_b32_e64 v16, v16, 0, s[38:39]
	v_lshl_add_u32 v16, v16, 9, v158
	global_load_dwordx4 v[48:51], v16, s[100:101]
	global_load_dwordx4 v[60:63], v16, s[100:101] offset:64
	v_add_u32_e32 v16, s76, v228
	v_med3_i32 v16, v16, 0, s75
	v_lshl_add_u32 v16, v16, 9, v158
	global_load_dwordx4 v[40:43], v16, s[100:101]
	s_nop 0
	global_load_dwordx4 v[16:19], v16, s[100:101] offset:64
	ds_read_b64_tr_b16 v[142:143], v169 offset:2304
	ds_read_b64_tr_b16 v[140:141], v169
	ds_read_b64_tr_b16 v[136:137], v169 offset:32
	ds_read_b64_tr_b16 v[138:139], v169 offset:2336
	ds_read_b64_tr_b16 v[132:133], v169 offset:64
	ds_read_b64_tr_b16 v[134:135], v169 offset:2368
	ds_read_b64_tr_b16 v[128:129], v169 offset:96
	ds_read_b64_tr_b16 v[130:131], v169 offset:2400
	s_waitcnt vmcnt(15)
	ds_write_b128 v241, v[68:71] offset:4608
	s_waitcnt vmcnt(14)
	ds_write_b128 v242, v[72:75] offset:4608
	s_waitcnt vmcnt(13)
	ds_write_b128 v243, v[76:79] offset:4608
	s_waitcnt vmcnt(12)
	ds_write_b128 v244, v[92:95] offset:4608
	v_mfma_f32_16x16x32_bf16 v[72:75], v[32:35], v[4:7], 0
	v_mfma_f32_16x16x32_bf16 v[32:35], v[32:35], v[12:15], 0
	v_mfma_f32_16x16x32_bf16 v[68:71], v[56:59], v[4:7], 0
	v_mfma_f32_16x16x32_bf16 v[72:75], v[24:27], v[8:11], v[72:75]
	v_mfma_f32_16x16x32_bf16 v[24:27], v[24:27], v[0:3], v[32:35]
	v_mfma_f32_16x16x32_bf16 v[68:71], v[36:39], v[8:11], v[68:71]
	v_mfma_f32_16x16x32_bf16 v[56:59], v[56:59], v[12:15], 0
	s_nop 5
	v_add_u32_e32 v25, 0x800, v250
	v_ashrrev_i32_e32 v25, 4, v25
	v_min3_i32 v25, v25, s0, v248
	v_sub_u32_e32 v26, v154, v150
	v_sub_u32_e32 v149, v25, v150
	v_add_u32_e32 v27, 1, v26
	v_cmp_gt_u32_e64 s[0:1], v27, v149
	v_cmp_gt_u32_e32 vcc, v26, v149
	s_nop 0
	v_cndmask_b32_e64 v69, v69, v246, s[0:1]
	s_nop 0
	v_cndmask_b32_e32 v68, v68, v246, vcc
	v_max_f32_e32 v25, 0xf149f2ca, v68
	v_max_f32_e32 v25, v25, v69
	v_add_u32_e32 v27, 2, v26
	v_add_u32_e32 v32, 3, v26
	v_cmp_gt_u32_e64 s[22:23], v27, v149
	v_cmp_gt_u32_e64 s[24:25], v32, v149
	v_mfma_f32_16x16x32_bf16 v[36:39], v[36:39], v[0:3], v[56:59]
	v_cndmask_b32_e64 v70, v70, v246, s[22:23]
	v_cndmask_b32_e64 v71, v71, v246, s[24:25]
	v_max3_f32 v25, v25, v70, v71
	v_add_u32_e32 v27, 16, v26
	v_add_u32_e32 v32, 17, v26
	v_cmp_gt_u32_e64 s[26:27], v27, v149
	v_cmp_gt_u32_e64 s[28:29], v32, v149
	s_nop 0
	v_cndmask_b32_e64 v72, v72, v246, s[26:27]
	v_cndmask_b32_e64 v73, v73, v246, s[28:29]
	v_max3_f32 v25, v25, v72, v73
	v_add_u32_e32 v27, 18, v26
	v_add_u32_e32 v26, 19, v26
	v_cmp_gt_u32_e64 s[30:31], v27, v149
	v_cmp_gt_u32_e64 s[34:35], v26, v149
	s_nop 0
	v_cndmask_b32_e64 v74, v74, v246, s[30:31]
	v_cndmask_b32_e64 v75, v75, v246, s[34:35]
	v_max3_f32 v25, v25, v74, v75
	v_max_f32_e32 v26, v36, v36
	v_max_f32_e32 v26, 0xf149f2ca, v26
	v_cndmask_b32_e64 v26, v246, v26, s[36:37]
	v_cndmask_b32_e64 v27, v246, v24, s[4:5]
	v_max3_f32 v26, v26, v27, s73
	v_mov_b32_e32 v27, v25
	v_mov_b32_e32 v32, v25
	s_nop 1
	v_permlane32_swap_b32_e32 v27, v32
	v_max3_f32 v25, v25, v27, v32
	v_mov_b32_e32 v27, v26
	v_mov_b32_e32 v32, v26
	s_nop 1
	v_permlane32_swap_b32_e32 v27, v32
	v_max3_f32 v26, v26, v27, v32
	v_mov_b32_e32 v27, v25
	v_mov_b32_e32 v32, v25
	s_nop 1
	v_permlane16_swap_b32_e32 v27, v32
	v_max_f32_e32 v25, v25, v27
	v_max3_f32 v144, v147, v25, v32
	v_sub_f32_e32 v25, v147, v144
	v_exp_f32_e32 v56, v25
	v_sub_f32_e32 v25, v68, v144
	v_exp_f32_e32 v25, v25
	v_sub_f32_e32 v32, v69, v144
	v_exp_f32_e32 v32, v32
	v_sub_f32_e32 v33, v70, v144
	v_mov_b32_e32 v27, v26
	v_mov_b32_e32 v37, v26
	v_exp_f32_e32 v33, v33
	v_sub_f32_e32 v34, v71, v144
	v_permlane16_swap_b32_e32 v27, v37
	v_exp_f32_e32 v34, v34
	v_sub_f32_e32 v35, v72, v144
	v_exp_f32_e32 v35, v35
	v_sub_f32_e32 v38, v73, v144
	v_max_f32_e32 v26, v26, v27
	v_add_f32_e32 v27, 0, v25
	v_exp_f32_e32 v38, v38
	v_sub_f32_e32 v39, v74, v144
	v_add_f32_e32 v27, v32, v27
	v_exp_f32_e32 v39, v39
	v_sub_f32_e32 v57, v75, v144
	v_add_f32_e32 v27, v33, v27
	v_exp_f32_e32 v57, v57
	v_add_f32_e32 v27, v34, v27
	v_add_f32_e32 v27, v35, v27
	v_add_f32_e32 v27, v38, v27
	v_add_f32_e32 v27, v39, v27
	v_add_f32_e32 v147, v57, v27
	v_fmac_f32_e32 v147, v145, v56
	v_max3_f32 v145, v146, v26, v37
	v_cvt_pk_bf16_f32 v32, v25, v32
	v_sub_f32_e32 v25, v146, v145
	v_exp_f32_e32 v58, v25
	v_sub_f32_e32 v25, v36, v145
	v_exp_f32_e32 v25, v25
	v_sub_f32_e32 v24, v24, v145
	v_exp_f32_e32 v24, v24
	v_cvt_pk_bf16_f32 v33, v33, v34
	v_cndmask_b32_e64 v25, 0, v25, s[36:37]
	v_cvt_pk_bf16_f32 v34, v35, v38
	v_cvt_pk_bf16_f32 v35, v39, v57
	v_add_f32_e32 v26, 0, v25
	v_cndmask_b32_e64 v27, 0, v24, s[4:5]
	v_pk_mul_f32 v[38:39], v[66:67], v[56:57] op_sel_hi:[1,0]
	v_pk_mul_f32 v[36:37], v[64:65], v[56:57] op_sel_hi:[1,0]
	v_add_f32_e32 v146, v27, v26
	v_cvt_pk_bf16_f32 v24, v25, 0
	v_cvt_pk_bf16_f32 v26, v27, 0
	v_mov_b32_e32 v25, v153
	v_mov_b32_e32 v27, v153
	s_waitcnt lgkmcnt(10)
	v_mfma_f32_16x16x32_bf16 v[76:79], v[140:143], v[32:35], v[36:39]
	v_fmac_f32_e32 v146, v151, v58
	s_nop 1
	v_pk_mul_f32 v[38:39], v[102:103], v[58:59] op_sel_hi:[1,0]
	v_pk_mul_f32 v[36:37], v[100:101], v[58:59] op_sel_hi:[1,0]
	s_nop 1
	v_mfma_f32_16x16x32_bf16 v[100:103], v[140:143], v[24:27], v[36:39]
	s_nop 2
	v_mul_f32_e64 v38, v106, v56
	v_mul_f32_e64 v39, v107, v56
	v_pk_mul_f32 v[36:37], v[104:105], v[56:57] op_sel_hi:[1,0]
	s_waitcnt lgkmcnt(8)
	s_nop 0
	v_mfma_f32_16x16x32_bf16 v[104:107], v[136:139], v[32:35], v[36:39]
	s_nop 2
	v_mul_f32_e64 v38, v110, v58
	v_mul_f32_e64 v39, v111, v58
	v_pk_mul_f32 v[36:37], v[108:109], v[58:59] op_sel_hi:[1,0]
	s_nop 1
	v_mfma_f32_16x16x32_bf16 v[108:111], v[136:139], v[24:27], v[36:39]
	s_nop 2
	v_mul_f32_e64 v38, v114, v56
	v_mul_f32_e64 v39, v115, v56
	v_pk_mul_f32 v[36:37], v[112:113], v[56:57] op_sel_hi:[1,0]
	s_waitcnt lgkmcnt(6)
	s_nop 0
	v_mfma_f32_16x16x32_bf16 v[112:115], v[132:135], v[32:35], v[36:39]
	s_nop 2
	v_mul_f32_e64 v38, v118, v58
	v_mul_f32_e64 v39, v119, v58
	v_pk_mul_f32 v[36:37], v[116:117], v[58:59] op_sel_hi:[1,0]
	s_nop 1
	v_mfma_f32_16x16x32_bf16 v[116:119], v[132:135], v[24:27], v[36:39]
	s_nop 2
	v_mul_f32_e64 v38, v122, v56
	v_mul_f32_e64 v39, v123, v56
	v_pk_mul_f32 v[36:37], v[120:121], v[56:57] op_sel_hi:[1,0]
	v_add_u32_e32 v56, s76, v232
	s_waitcnt lgkmcnt(4)
	v_mfma_f32_16x16x32_bf16 v[120:123], v[128:131], v[32:35], v[36:39]
	v_mul_f32_e64 v34, v126, v58
	v_mul_f32_e64 v35, v127, v58
	v_pk_mul_f32 v[32:33], v[124:125], v[58:59] op_sel_hi:[1,0]
	v_add_u32_e32 v36, s76, v231
	s_nop 0
	v_mfma_f32_16x16x32_bf16 v[124:127], v[128:131], v[24:27], v[32:35]
	v_add_u32_e32 v24, s76, v229
	s_nop 1
	v_add_u32_e32 v32, s76, v230
	v_med3_i32 v24, v24, 0, s75
	v_med3_i32 v32, v32, 0, s75
	v_med3_i32 v36, v36, 0, s75
	v_med3_i32 v56, v56, 0, s75
	v_lshl_add_u32 v36, v36, 9, v152
	v_lshl_add_u32 v56, v56, 9, v152
	global_load_dwordx4 v[36:39], v36, s[98:99]
	global_load_dwordx4 v[92:95], v56, s[98:99]
	v_add_u32_e32 v56, s76, v233
	v_med3_i32 v56, v56, 0, s75
	v_lshl_add_u32 v24, v24, 9, v152
	v_lshl_add_u32 v32, v32, 9, v152
	v_lshl_add_u32 v56, v56, 9, v158
	global_load_dwordx4 v[24:27], v24, s[98:99]
	s_nop 0
	global_load_dwordx4 v[32:35], v32, s[98:99]
	s_nop 0
	global_load_dwordx4 v[72:75], v56, s[100:101]
	global_load_dwordx4 v[68:71], v56, s[100:101] offset:64
	v_add_u32_e32 v56, s76, v234
	v_med3_i32 v56, v56, 0, s75
	v_lshl_add_u32 v56, v56, 9, v158
	global_load_dwordx4 v[64:67], v56, s[100:101]
	s_nop 0
	global_load_dwordx4 v[56:59], v56, s[100:101] offset:64
	ds_read_b64_tr_b16 v[142:143], v169 offset:6912
	ds_read_b64_tr_b16 v[140:141], v169 offset:4608
	ds_read_b64_tr_b16 v[136:137], v169 offset:4640
	ds_read_b64_tr_b16 v[138:139], v169 offset:6944
	ds_read_b64_tr_b16 v[132:133], v169 offset:4672
	ds_read_b64_tr_b16 v[134:135], v169 offset:6976
	ds_read_b64_tr_b16 v[128:129], v169 offset:4704
	ds_read_b64_tr_b16 v[130:131], v169 offset:7008
	s_waitcnt vmcnt(15)
	ds_write_b128 v241, v[80:83]
	s_waitcnt vmcnt(14)
	ds_write_b128 v242, v[84:87]
	s_waitcnt vmcnt(13)
	ds_write_b128 v243, v[88:91]
	s_waitcnt vmcnt(12)
	ds_write_b128 v244, v[96:99]
	v_mfma_f32_16x16x32_bf16 v[80:83], v[52:55], v[4:7], 0
	v_mfma_f32_16x16x32_bf16 v[84:87], v[28:31], v[4:7], 0
	v_mfma_f32_16x16x32_bf16 v[28:31], v[28:31], v[12:15], 0
	v_mfma_f32_16x16x32_bf16 v[80:83], v[44:47], v[8:11], v[80:83]
	v_mfma_f32_16x16x32_bf16 v[84:87], v[20:23], v[8:11], v[84:87]
	v_mfma_f32_16x16x32_bf16 v[20:23], v[20:23], v[0:3], v[28:31]
	v_mfma_f32_16x16x32_bf16 v[52:55], v[52:55], v[12:15], 0
	v_mfma_f32_16x16x32_bf16 v[44:47], v[44:47], v[0:3], v[52:55]
	s_nop 5
	v_sub_u32_e32 v21, v187, v150
	v_add_u32_e32 v23, 1, v21
	v_cmp_gt_u32_e64 s[0:1], v23, v149
	v_cmp_gt_u32_e32 vcc, v21, v149
	s_nop 0
	v_cndmask_b32_e64 v81, v81, v246, s[0:1]
	s_nop 0
	v_cndmask_b32_e32 v80, v80, v246, vcc
	v_max_f32_e32 v22, 0xf149f2ca, v80
	v_max_f32_e32 v22, v22, v81
	v_add_u32_e32 v23, 2, v21
	v_add_u32_e32 v28, 3, v21
	v_cmp_gt_u32_e64 s[22:23], v23, v149
	v_cmp_gt_u32_e64 s[24:25], v28, v149
	s_nop 0
	v_cndmask_b32_e64 v82, v82, v246, s[22:23]
	v_cndmask_b32_e64 v83, v83, v246, s[24:25]
	v_max3_f32 v22, v22, v82, v83
	v_add_u32_e32 v23, 16, v21
	v_add_u32_e32 v28, 17, v21
	v_cmp_gt_u32_e64 s[26:27], v23, v149
	v_cmp_gt_u32_e64 s[28:29], v28, v149
	s_nop 0
	v_cndmask_b32_e64 v84, v84, v246, s[26:27]
	v_cndmask_b32_e64 v85, v85, v246, s[28:29]
	v_max3_f32 v22, v22, v84, v85
	v_add_u32_e32 v23, 18, v21
	v_add_u32_e32 v21, 19, v21
	v_cmp_gt_u32_e64 s[30:31], v23, v149
	v_cmp_gt_u32_e64 s[34:35], v21, v149
	s_nop 0
	v_cndmask_b32_e64 v86, v86, v246, s[30:31]
	v_cndmask_b32_e64 v87, v87, v246, s[34:35]
	v_max3_f32 v21, v22, v86, v87
	v_max_f32_e32 v22, v44, v44
	v_max_f32_e32 v22, 0xf149f2ca, v22
	v_cndmask_b32_e64 v22, v246, v22, s[6:7]
	v_cndmask_b32_e64 v23, v246, v20, s[8:9]
	v_max3_f32 v22, v22, v23, s73
	v_mov_b32_e32 v23, v21
	v_mov_b32_e32 v28, v21
	s_nop 1
	v_permlane32_swap_b32_e32 v23, v28
	v_max3_f32 v21, v21, v23, v28
	v_mov_b32_e32 v23, v22
	v_mov_b32_e32 v28, v22
	s_nop 1
	v_permlane32_swap_b32_e32 v23, v28
	v_max3_f32 v22, v22, v23, v28
	v_mov_b32_e32 v23, v21
	v_mov_b32_e32 v28, v21
	s_nop 1
	v_permlane16_swap_b32_e32 v23, v28
	v_max_f32_e32 v21, v21, v23
	v_max3_f32 v175, v144, v21, v28
	v_sub_f32_e32 v21, v144, v175
	v_exp_f32_e32 v144, v21
	v_sub_f32_e32 v21, v80, v175
	v_sub_f32_e32 v28, v81, v175
	v_mov_b32_e32 v23, v22
	v_mov_b32_e32 v29, v22
	v_exp_f32_e32 v21, v21
	v_exp_f32_e32 v28, v28
	v_permlane16_swap_b32_e32 v23, v29
	v_sub_f32_e32 v30, v82, v175
	v_exp_f32_e32 v30, v30
	v_sub_f32_e32 v31, v83, v175
	v_max_f32_e32 v22, v22, v23
	v_exp_f32_e32 v31, v31
	v_sub_f32_e32 v45, v84, v175
	v_exp_f32_e32 v45, v45
	v_sub_f32_e32 v46, v85, v175
	v_max3_f32 v176, v145, v22, v29
	v_add_f32_e32 v23, 0, v21
	v_exp_f32_e32 v46, v46
	v_sub_f32_e32 v47, v86, v175
	v_cvt_pk_bf16_f32 v80, v21, v28
	v_sub_f32_e32 v21, v145, v176
	v_add_f32_e32 v23, v28, v23
	v_exp_f32_e32 v47, v47
	v_sub_f32_e32 v52, v87, v175
	v_exp_f32_e32 v84, v21
	v_sub_f32_e32 v21, v44, v176
	v_add_f32_e32 v23, v30, v23
	v_exp_f32_e32 v52, v52
	v_exp_f32_e32 v21, v21
	v_sub_f32_e32 v20, v20, v176
	v_add_f32_e32 v23, v31, v23
	v_exp_f32_e32 v20, v20
	v_add_f32_e32 v23, v45, v23
	v_add_f32_e32 v23, v46, v23
	v_add_f32_e32 v23, v47, v23
	v_cndmask_b32_e64 v21, 0, v21, s[6:7]
	v_add_f32_e32 v151, v52, v23
	v_add_f32_e32 v22, 0, v21
	v_cndmask_b32_e64 v23, 0, v20, s[8:9]
	v_fmac_f32_e32 v151, v147, v144
	v_cvt_pk_bf16_f32 v81, v30, v31
	v_add_f32_e32 v147, v23, v22
	v_cvt_pk_bf16_f32 v20, v21, 0
	v_cvt_pk_bf16_f32 v22, v23, 0
	v_mov_b32_e32 v21, v153
	v_mov_b32_e32 v23, v153
	v_pk_mul_f32 v[30:31], v[78:79], v[144:145] op_sel_hi:[1,0]
	v_pk_mul_f32 v[28:29], v[76:77], v[144:145] op_sel_hi:[1,0]
	v_pk_mul_f32 v[78:79], v[110:111], v[84:85] op_sel_hi:[1,0]
	v_pk_mul_f32 v[76:77], v[108:109], v[84:85] op_sel_hi:[1,0]
	v_cvt_pk_bf16_f32 v82, v45, v46
	v_cvt_pk_bf16_f32 v83, v47, v52
	s_waitcnt lgkmcnt(8)
	v_mfma_f32_16x16x32_bf16 v[88:91], v[136:139], v[20:23], v[76:79]
	v_mul_f32_e64 v46, v102, v84
	v_mul_f32_e64 v47, v103, v84
	v_pk_mul_f32 v[44:45], v[100:101], v[84:85] op_sel_hi:[1,0]
	v_pk_mul_f32 v[54:55], v[106:107], v[144:145] op_sel_hi:[1,0]
	v_pk_mul_f32 v[78:79], v[114:115], v[144:145] op_sel_hi:[1,0]
	v_pk_mul_f32 v[76:77], v[112:113], v[144:145] op_sel_hi:[1,0]
	v_pk_mul_f32 v[52:53], v[104:105], v[144:145] op_sel_hi:[1,0]
	v_mfma_f32_16x16x32_bf16 v[44:47], v[140:143], v[20:23], v[44:47]
	v_fmac_f32_e32 v147, v146, v84
	s_waitcnt lgkmcnt(6)
	v_mfma_f32_16x16x32_bf16 v[96:99], v[132:135], v[80:83], v[76:79]
	s_nop 2
	v_mul_f32_e64 v78, v118, v84
	v_mul_f32_e64 v79, v119, v84
	v_pk_mul_f32 v[76:77], v[116:117], v[84:85] op_sel_hi:[1,0]
	v_mfma_f32_16x16x32_bf16 v[28:31], v[140:143], v[80:83], v[28:31]
	s_nop 0
	v_mfma_f32_16x16x32_bf16 v[100:103], v[132:135], v[20:23], v[76:79]
	s_nop 2
	v_mul_f32_e64 v78, v122, v144
	v_mul_f32_e64 v79, v123, v144
	v_pk_mul_f32 v[76:77], v[120:121], v[144:145] op_sel_hi:[1,0]
	v_mfma_f32_16x16x32_bf16 v[52:55], v[136:139], v[80:83], v[52:55]
	s_waitcnt lgkmcnt(4)
	v_mfma_f32_16x16x32_bf16 v[104:107], v[128:131], v[80:83], v[76:79]
	s_nop 2
	v_mul_f32_e64 v78, v126, v84
	v_mul_f32_e64 v79, v127, v84
	v_pk_mul_f32 v[76:77], v[124:125], v[84:85] op_sel_hi:[1,0]
	s_nop 1
	v_mfma_f32_16x16x32_bf16 v[108:111], v[128:131], v[20:23], v[76:79]
	v_add_u32_e32 v20, s76, v235
	v_med3_i32 v20, v20, 0, s75
	v_lshl_add_u32 v20, v20, 9, v152
	global_load_dwordx4 v[112:115], v20, s[98:99]
	v_add_u32_e32 v20, s76, v236
	v_med3_i32 v20, v20, 0, s75
	v_lshl_add_u32 v20, v20, 9, v152
	global_load_dwordx4 v[116:119], v20, s[98:99]
	v_add_u32_e32 v20, s76, v237
	v_med3_i32 v20, v20, 0, s75
	v_lshl_add_u32 v20, v20, 9, v152
	global_load_dwordx4 v[120:123], v20, s[98:99]
	v_add_u32_e32 v20, s76, v238
	v_med3_i32 v20, v20, 0, s75
	v_lshl_add_u32 v20, v20, 9, v152
	global_load_dwordx4 v[124:127], v20, s[98:99]
	v_add_u32_e32 v20, s76, v239
	v_med3_i32 v20, v20, 0, s75
	v_lshl_add_u32 v20, v20, 9, v158
	global_load_dwordx4 v[84:87], v20, s[100:101]
	global_load_dwordx4 v[80:83], v20, s[100:101] offset:64
	v_add_u32_e32 v20, s76, v240
	s_addk_i32 s76, 0xfc08
	s_nop 0
	v_med3_i32 v20, v20, 0, s75
	v_lshl_add_u32 v20, v20, 9, v158
	global_load_dwordx4 v[76:79], v20, s[100:101]
	s_nop 0
	global_load_dwordx4 v[20:23], v20, s[100:101] offset:64
	ds_read_b64_tr_b16 v[142:143], v169 offset:2304
	ds_read_b64_tr_b16 v[140:141], v169
	ds_read_b64_tr_b16 v[136:137], v169 offset:32
	ds_read_b64_tr_b16 v[138:139], v169 offset:2336
	ds_read_b64_tr_b16 v[132:133], v169 offset:64
	ds_read_b64_tr_b16 v[134:135], v169 offset:2368
	ds_read_b64_tr_b16 v[128:129], v169 offset:96
	ds_read_b64_tr_b16 v[130:131], v169 offset:2400
	s_waitcnt vmcnt(13)
	ds_write_b128 v241, v[24:27] offset:4608
	s_waitcnt vmcnt(12)
	ds_write_b128 v242, v[32:35] offset:4608
	ds_write_b128 v243, v[36:39] offset:4608
	ds_write_b128 v244, v[92:95] offset:4608
	v_mfma_f32_16x16x32_bf16 v[36:39], v[48:51], v[12:15], 0
	v_mfma_f32_16x16x32_bf16 v[24:27], v[48:51], v[4:7], 0
	v_mfma_f32_16x16x32_bf16 v[36:39], v[60:63], v[0:3], v[36:39]
	v_mfma_f32_16x16x32_bf16 v[32:35], v[40:43], v[4:7], 0
	v_mfma_f32_16x16x32_bf16 v[38:41], v[40:43], v[12:15], 0
	v_mfma_f32_16x16x32_bf16 v[24:27], v[60:63], v[8:11], v[24:27]
	v_mfma_f32_16x16x32_bf16 v[32:35], v[16:19], v[8:11], v[32:35]
	v_mfma_f32_16x16x32_bf16 v[16:19], v[16:19], v[0:3], v[38:41]
	s_nop 7
	v_sub_u32_e32 v17, v192, v150
	v_add_u32_e32 v19, 1, v17
	v_cmp_gt_u32_e64 s[0:1], v19, v149
	v_cmp_gt_u32_e32 vcc, v17, v149
	s_nop 0
	v_cndmask_b32_e64 v25, v25, v246, s[0:1]
	s_nop 0
	v_cndmask_b32_e32 v24, v24, v246, vcc
	v_max_f32_e32 v18, 0xf149f2ca, v24
	v_max_f32_e32 v18, v18, v25
	v_add_u32_e32 v19, 2, v17
	v_add_u32_e32 v37, 3, v17
	v_cmp_gt_u32_e64 s[22:23], v19, v149
	v_cmp_gt_u32_e64 s[24:25], v37, v149
	s_nop 0
	v_cndmask_b32_e64 v26, v26, v246, s[22:23]
	v_cndmask_b32_e64 v27, v27, v246, s[24:25]
	v_max3_f32 v18, v18, v26, v27
	v_add_u32_e32 v19, 16, v17
	v_add_u32_e32 v37, 17, v17
	v_cmp_gt_u32_e64 s[26:27], v19, v149
	v_cmp_gt_u32_e64 s[28:29], v37, v149
	s_nop 0
	v_cndmask_b32_e64 v32, v32, v246, s[26:27]
	v_cndmask_b32_e64 v33, v33, v246, s[28:29]
	v_max3_f32 v18, v18, v32, v33
	v_add_u32_e32 v19, 18, v17
	v_add_u32_e32 v17, 19, v17
	v_cmp_gt_u32_e64 s[30:31], v19, v149
	v_cmp_gt_u32_e64 s[34:35], v17, v149
	s_nop 0
	v_cndmask_b32_e64 v34, v34, v246, s[30:31]
	v_cndmask_b32_e64 v35, v35, v246, s[34:35]
	v_max3_f32 v17, v18, v34, v35
	v_max_f32_e32 v18, v36, v36
	v_max_f32_e32 v18, 0xf149f2ca, v18
	v_cndmask_b32_e64 v18, v246, v18, s[10:11]
	v_cndmask_b32_e64 v19, v246, v16, s[12:13]
	v_max3_f32 v18, v18, v19, s73
	v_mov_b32_e32 v19, v17
	v_mov_b32_e32 v37, v17
	s_nop 1
	v_permlane32_swap_b32_e32 v19, v37
	v_max3_f32 v17, v17, v19, v37
	v_mov_b32_e32 v19, v18
	v_mov_b32_e32 v37, v18
	s_nop 1
	v_permlane32_swap_b32_e32 v19, v37
	v_max3_f32 v18, v18, v19, v37
	v_mov_b32_e32 v19, v17
	v_mov_b32_e32 v37, v17
	s_nop 1
	v_permlane16_swap_b32_e32 v19, v37
	v_max_f32_e32 v17, v17, v19
	v_max3_f32 v145, v175, v17, v37
	v_sub_f32_e32 v17, v175, v145
	v_exp_f32_e32 v38, v17
	v_sub_f32_e32 v17, v24, v145
	v_exp_f32_e32 v17, v17
	v_mov_b32_e32 v19, v18
	v_mov_b32_e32 v39, v18
	s_nop 1
	v_permlane16_swap_b32_e32 v19, v39
	v_cndmask_b32_e64 v37, v17, 0, vcc
	v_sub_f32_e32 v17, v25, v145
	v_exp_f32_e32 v17, v17
	v_max_f32_e32 v18, v18, v19
	v_max3_f32 v144, v176, v18, v39
	v_cndmask_b32_e64 v60, v17, 0, s[0:1]
	v_sub_f32_e32 v17, v26, v145
	v_exp_f32_e32 v17, v17
	v_sub_f32_e32 v16, v16, v144
	v_exp_f32_e32 v16, v16
	v_cvt_pk_bf16_f32 v24, v37, v60
	v_cndmask_b32_e64 v61, v17, 0, s[22:23]
	v_sub_f32_e32 v17, v27, v145
	v_exp_f32_e32 v17, v17
	v_cndmask_b32_e64 v39, 0, v16, s[12:13]
	v_pk_mul_f32 v[30:31], v[30:31], v[38:39] op_sel_hi:[1,0]
	v_pk_mul_f32 v[28:29], v[28:29], v[38:39] op_sel_hi:[1,0]
	v_cndmask_b32_e64 v62, v17, 0, s[24:25]
	v_sub_f32_e32 v17, v32, v145
	v_exp_f32_e32 v17, v17
	v_cvt_pk_bf16_f32 v25, v61, v62
	v_cvt_pk_bf16_f32 v18, v39, 0
	v_mov_b32_e32 v19, v153
	v_cndmask_b32_e64 v63, v17, 0, s[26:27]
	v_sub_f32_e32 v17, v33, v145
	v_exp_f32_e32 v17, v17
	s_nop 0
	v_cndmask_b32_e64 v33, v17, 0, s[28:29]
	v_sub_f32_e32 v17, v34, v145
	v_exp_f32_e32 v17, v17
	v_cvt_pk_bf16_f32 v26, v63, v33
	v_cndmask_b32_e64 v34, v17, 0, s[30:31]
	v_sub_f32_e32 v17, v35, v145
	v_exp_f32_e32 v17, v17
	s_nop 0
	v_cndmask_b32_e64 v35, v17, 0, s[34:35]
	v_sub_f32_e32 v17, v176, v144
	v_exp_f32_e32 v32, v17
	v_sub_f32_e32 v17, v36, v144
	v_exp_f32_e32 v17, v17
	v_cvt_pk_bf16_f32 v27, v34, v35
	v_cndmask_b32_e64 v36, 0, v17, s[10:11]
	v_cvt_pk_bf16_f32 v16, v36, 0
	v_mov_b32_e32 v17, v153
	s_waitcnt lgkmcnt(10)
	v_mfma_f32_16x16x32_bf16 v[40:43], v[140:143], v[24:27], v[28:31]
	s_nop 2
	v_mul_f32_e64 v30, v46, v32
	v_mul_f32_e64 v31, v47, v32
	v_pk_mul_f32 v[28:29], v[44:45], v[32:33] op_sel_hi:[1,0]
	s_nop 1
	v_mfma_f32_16x16x32_bf16 v[44:47], v[140:143], v[16:19], v[28:31]
	s_nop 2
	v_mul_f32_e64 v30, v54, v38
	v_mul_f32_e64 v31, v55, v38
	v_pk_mul_f32 v[28:29], v[52:53], v[38:39] op_sel_hi:[1,0]
	s_waitcnt lgkmcnt(8)
	s_nop 0
	v_mfma_f32_16x16x32_bf16 v[48:51], v[136:139], v[24:27], v[28:31]
	s_nop 2
	v_mul_f32_e64 v30, v90, v32
	v_mul_f32_e64 v31, v91, v32
	v_pk_mul_f32 v[28:29], v[88:89], v[32:33] op_sel_hi:[1,0]
	s_nop 1
	v_mfma_f32_16x16x32_bf16 v[52:55], v[136:139], v[16:19], v[28:31]
	s_nop 2
	v_mul_f32_e64 v30, v98, v38
	v_mul_f32_e64 v31, v99, v38
	v_pk_mul_f32 v[28:29], v[96:97], v[38:39] op_sel_hi:[1,0]
	s_waitcnt lgkmcnt(6)
	s_nop 0
	v_mfma_f32_16x16x32_bf16 v[88:91], v[132:135], v[24:27], v[28:31]
	s_nop 2
	v_mul_f32_e64 v30, v102, v32
	v_mul_f32_e64 v31, v103, v32
	v_pk_mul_f32 v[28:29], v[100:101], v[32:33] op_sel_hi:[1,0]
	s_nop 1
	v_mfma_f32_16x16x32_bf16 v[100:103], v[132:135], v[16:19], v[28:31]
	s_nop 2
	v_mul_f32_e64 v30, v106, v38
	v_mul_f32_e64 v31, v107, v38
	v_pk_mul_f32 v[28:29], v[104:105], v[38:39] op_sel_hi:[1,0]
	s_waitcnt lgkmcnt(4)
	s_nop 0
	v_mfma_f32_16x16x32_bf16 v[104:107], v[128:131], v[24:27], v[28:31]
	v_mul_f32_e64 v26, v110, v32
	v_mul_f32_e64 v27, v111, v32
	v_pk_mul_f32 v[24:25], v[108:109], v[32:33] op_sel_hi:[1,0]
	s_nop 1
	v_mfma_f32_16x16x32_bf16 v[108:111], v[128:131], v[16:19], v[24:27]
	v_add_f32_e32 v16, 0, v36
	v_add_f32_e32 v146, v39, v16
	v_add_f32_e32 v16, 0, v37
	v_add_f32_e32 v16, v60, v16
	v_add_f32_e32 v16, v61, v16
	v_add_f32_e32 v16, v62, v16
	v_add_f32_e32 v16, v63, v16
	v_add_f32_e32 v16, v33, v16
	v_add_f32_e32 v16, v34, v16
	v_fmac_f32_e32 v146, v147, v32
	v_add_f32_e32 v147, v35, v16
	v_add_u32_e32 v16, s40, v214
	v_add_u32_e32 v24, s40, v216
	v_med3_i32 v16, v16, 0, s75
	v_med3_i32 v24, v24, 0, s75
	v_lshl_add_u32 v16, v16, 9, v152
	v_lshl_add_u32 v24, v24, 9, v152
	global_load_dwordx4 v[16:19], v16, s[98:99]
	v_or_b32_e32 v32, 0xfffffd00, v167
	global_load_dwordx4 v[60:63], v24, s[98:99]
	v_add_u32_e32 v24, s40, v218
	v_add_u32_e32 v32, s40, v32
	v_med3_i32 v24, v24, 0, s75
	v_lshl_add_u32 v24, v24, 9, v152
	global_load_dwordx4 v[92:95], v24, s[98:99]
	v_add_u32_e32 v24, s40, v220
	v_fmac_f32_e32 v147, v151, v38
	s_nop 0
	v_med3_i32 v24, v24, 0, s75
	v_lshl_add_u32 v24, v24, 9, v152
	global_load_dwordx4 v[96:99], v24, s[98:99]
	v_add_u32_e32 v24, s40, v221
	v_med3_i32 v24, v24, 0, s75
	v_med3_i32 v32, v32, 0, s75
	v_lshl_add_u32 v28, v24, 9, v158
	v_lshl_add_u32 v36, v32, 9, v158
	global_load_dwordx4 v[24:27], v28, s[100:101]
	s_nop 0
	global_load_dwordx4 v[28:31], v28, s[100:101] offset:64
	s_nop 0
	global_load_dwordx4 v[32:35], v36, s[100:101]
	s_nop 0
	global_load_dwordx4 v[36:39], v36, s[100:101] offset:64
	ds_read_b64_tr_b16 v[142:143], v169 offset:6912
	ds_read_b64_tr_b16 v[140:141], v169 offset:4608
	ds_read_b64_tr_b16 v[132:133], v169 offset:4640
	ds_read_b64_tr_b16 v[134:135], v169 offset:6944
	ds_read_b64_tr_b16 v[128:129], v169 offset:4672
	ds_read_b64_tr_b16 v[130:131], v169 offset:6976
	ds_read_b64_tr_b16 v[136:137], v169 offset:4704
	ds_read_b64_tr_b16 v[138:139], v169 offset:7008
	s_waitcnt vmcnt(15)
	ds_write_b128 v241, v[112:115]
	s_waitcnt vmcnt(14)
	ds_write_b128 v242, v[116:119]
	s_waitcnt vmcnt(13)
	ds_write_b128 v243, v[120:123]
	s_waitcnt vmcnt(12)
	ds_write_b128 v244, v[124:127]
	v_mfma_f32_16x16x32_bf16 v[112:115], v[72:75], v[4:7], 0
	v_mfma_f32_16x16x32_bf16 v[116:119], v[64:67], v[4:7], 0
	v_mfma_f32_16x16x32_bf16 v[64:67], v[64:67], v[12:15], 0
	v_mfma_f32_16x16x32_bf16 v[112:115], v[68:71], v[8:11], v[112:115]
	v_mfma_f32_16x16x32_bf16 v[116:119], v[56:59], v[8:11], v[116:119]
	v_mfma_f32_16x16x32_bf16 v[56:59], v[56:59], v[0:3], v[64:67]
	v_mfma_f32_16x16x32_bf16 v[72:75], v[72:75], v[12:15], 0
	v_mfma_f32_16x16x32_bf16 v[68:71], v[68:71], v[0:3], v[72:75]
	s_nop 5
	v_sub_u32_e32 v57, v197, v150
	v_add_u32_e32 v59, 1, v57
	v_cmp_gt_u32_e64 s[0:1], v59, v149
	v_cmp_gt_u32_e32 vcc, v57, v149
	s_nop 0
	v_cndmask_b32_e64 v113, v113, v246, s[0:1]
	s_nop 0
	v_cndmask_b32_e32 v112, v112, v246, vcc
	v_max_f32_e32 v58, 0xf149f2ca, v112
	v_max_f32_e32 v58, v58, v113
	v_add_u32_e32 v59, 2, v57
	v_add_u32_e32 v64, 3, v57
	v_cmp_gt_u32_e64 s[22:23], v59, v149
	v_cmp_gt_u32_e64 s[24:25], v64, v149
	s_nop 0
	v_cndmask_b32_e64 v114, v114, v246, s[22:23]
	v_cndmask_b32_e64 v115, v115, v246, s[24:25]
	v_max3_f32 v58, v58, v114, v115
	v_add_u32_e32 v59, 16, v57
	v_add_u32_e32 v64, 17, v57
	v_cmp_gt_u32_e64 s[26:27], v59, v149
	v_cmp_gt_u32_e64 s[28:29], v64, v149
	s_nop 0
	v_cndmask_b32_e64 v116, v116, v246, s[26:27]
	v_cndmask_b32_e64 v117, v117, v246, s[28:29]
	v_max3_f32 v58, v58, v116, v117
	v_add_u32_e32 v59, 18, v57
	v_add_u32_e32 v57, 19, v57
	v_cmp_gt_u32_e64 s[30:31], v59, v149
	v_cmp_gt_u32_e64 s[34:35], v57, v149
	s_nop 0
	v_cndmask_b32_e64 v118, v118, v246, s[30:31]
	v_cndmask_b32_e64 v119, v119, v246, s[34:35]
	v_max3_f32 v57, v58, v118, v119
	v_max_f32_e32 v58, v68, v68
	v_max_f32_e32 v58, 0xf149f2ca, v58
	v_cndmask_b32_e64 v58, v246, v58, s[14:15]
	v_cndmask_b32_e64 v59, v246, v56, s[16:17]
	v_max3_f32 v58, v58, v59, s73
	v_mov_b32_e32 v59, v57
	v_mov_b32_e32 v64, v57
	s_nop 1
	v_permlane32_swap_b32_e32 v59, v64
	v_max3_f32 v57, v57, v59, v64
	v_mov_b32_e32 v59, v58
	v_mov_b32_e32 v64, v58
	s_nop 1
	v_permlane32_swap_b32_e32 v59, v64
	v_max3_f32 v58, v58, v59, v64
	v_mov_b32_e32 v59, v57
	v_mov_b32_e32 v64, v57
	s_nop 1
	v_permlane16_swap_b32_e32 v59, v64
	v_max_f32_e32 v57, v57, v59
	v_max3_f32 v175, v145, v57, v64
	v_sub_f32_e32 v57, v145, v175
	v_exp_f32_e32 v72, v57
	v_sub_f32_e32 v57, v112, v175
	v_exp_f32_e32 v57, v57
	v_sub_f32_e32 v64, v113, v175
	v_mov_b32_e32 v59, v58
	v_mov_b32_e32 v69, v58
	v_exp_f32_e32 v64, v64
	s_nop 0
	v_permlane16_swap_b32_e32 v59, v69
	v_sub_f32_e32 v65, v114, v175
	v_max_f32_e32 v58, v58, v59
	v_exp_f32_e32 v65, v65
	v_sub_f32_e32 v66, v115, v175
	v_add_f32_e32 v59, 0, v57
	v_exp_f32_e32 v66, v66
	v_sub_f32_e32 v67, v116, v175
	v_max3_f32 v177, v144, v58, v69
	v_add_f32_e32 v59, v64, v59
	v_exp_f32_e32 v67, v67
	v_sub_f32_e32 v70, v117, v175
	v_cvt_pk_bf16_f32 v64, v57, v64
	v_sub_f32_e32 v57, v144, v177
	v_exp_f32_e32 v70, v70
	v_sub_f32_e32 v71, v118, v175
	v_sub_f32_e32 v73, v119, v175
	v_exp_f32_e32 v74, v57
	v_sub_f32_e32 v57, v68, v177
	v_exp_f32_e32 v71, v71
	v_exp_f32_e32 v73, v73
	v_exp_f32_e32 v57, v57
	v_sub_f32_e32 v56, v56, v177
	v_add_f32_e32 v59, v65, v59
	v_exp_f32_e32 v56, v56
	v_add_f32_e32 v59, v66, v59
	v_add_f32_e32 v59, v67, v59
	v_add_f32_e32 v59, v70, v59
	v_cndmask_b32_e64 v57, 0, v57, s[14:15]
	v_add_f32_e32 v59, v71, v59
	v_cvt_pk_bf16_f32 v65, v65, v66
	v_cvt_pk_bf16_f32 v66, v67, v70
	v_cvt_pk_bf16_f32 v67, v71, v73
	v_add_f32_e32 v58, 0, v57
	v_cndmask_b32_e64 v56, 0, v56, s[16:17]
	v_pk_mul_f32 v[42:43], v[42:43], v[72:73] op_sel_hi:[1,0]
	v_pk_mul_f32 v[40:41], v[40:41], v[72:73] op_sel_hi:[1,0]
	v_add_f32_e32 v176, v73, v59
	v_add_f32_e32 v178, v56, v58
	v_cvt_pk_bf16_f32 v68, v57, 0
	v_cvt_pk_bf16_f32 v70, v56, 0
	v_mov_b32_e32 v69, v153
	v_mov_b32_e32 v71, v153
	s_waitcnt lgkmcnt(10)
	v_mfma_f32_16x16x32_bf16 v[56:59], v[140:143], v[64:67], v[40:43]
	v_fmac_f32_e32 v176, v147, v72
	v_fmac_f32_e32 v178, v146, v74
	s_nop 0
	v_pk_mul_f32 v[42:43], v[46:47], v[74:75] op_sel_hi:[1,0]
	v_pk_mul_f32 v[40:41], v[44:45], v[74:75] op_sel_hi:[1,0]
	s_nop 1
	v_mfma_f32_16x16x32_bf16 v[112:115], v[140:143], v[68:71], v[40:43]
	s_nop 2
	v_mul_f32_e64 v42, v50, v72
	v_mul_f32_e64 v43, v51, v72
	v_pk_mul_f32 v[40:41], v[48:49], v[72:73] op_sel_hi:[1,0]
	v_add_u32_e32 v48, s40, v227
	v_min_i32_e32 v49, s75, v48
	s_waitcnt lgkmcnt(8)
	v_mfma_f32_16x16x32_bf16 v[116:119], v[132:135], v[64:67], v[40:43]
	s_nop 2
	v_mul_f32_e64 v42, v54, v74
	v_mul_f32_e64 v43, v55, v74
	v_pk_mul_f32 v[40:41], v[52:53], v[74:75] op_sel_hi:[1,0]
	s_nop 1
	v_mfma_f32_16x16x32_bf16 v[120:123], v[132:135], v[68:71], v[40:43]
	s_nop 2
	v_mul_f32_e64 v42, v90, v72
	v_mul_f32_e64 v43, v91, v72
	v_pk_mul_f32 v[40:41], v[88:89], v[72:73] op_sel_hi:[1,0]
	s_waitcnt lgkmcnt(6)
	s_nop 0
	v_mfma_f32_16x16x32_bf16 v[124:127], v[128:131], v[64:67], v[40:43]
	s_nop 2
	v_mul_f32_e64 v42, v102, v74
	v_mul_f32_e64 v43, v103, v74
	v_pk_mul_f32 v[40:41], v[100:101], v[74:75] op_sel_hi:[1,0]
	s_nop 1
	v_mfma_f32_16x16x32_bf16 v[128:131], v[128:131], v[68:71], v[40:43]
	s_nop 2
	v_mul_f32_e64 v42, v106, v72
	v_mul_f32_e64 v43, v107, v72
	v_pk_mul_f32 v[40:41], v[104:105], v[72:73] op_sel_hi:[1,0]
	s_waitcnt lgkmcnt(4)
	s_nop 0
	v_mfma_f32_16x16x32_bf16 v[132:135], v[136:139], v[64:67], v[40:43]
	s_nop 2
	v_mul_f32_e64 v42, v110, v74
	v_mul_f32_e64 v43, v111, v74
	v_pk_mul_f32 v[40:41], v[108:109], v[74:75] op_sel_hi:[1,0]
	s_nop 1
	v_mfma_f32_16x16x32_bf16 v[136:139], v[136:139], v[68:71], v[40:43]
	s_nop 2
	v_add_u32_e32 v40, s40, v222
	v_med3_i32 v40, v40, 0, s75
	v_lshl_add_u32 v40, v40, 9, v152
	global_load_dwordx4 v[64:67], v40, s[98:99]
	v_add_u32_e32 v40, s40, v223
	v_med3_i32 v40, v40, 0, s75
	v_lshl_add_u32 v40, v40, 9, v152
	global_load_dwordx4 v[68:71], v40, s[98:99]
	v_add_u32_e32 v40, s40, v224
	v_med3_i32 v40, v40, 0, s75
	v_lshl_add_u32 v40, v40, 9, v152
	global_load_dwordx4 v[72:75], v40, s[98:99]
	v_add_u32_e32 v40, s40, v225
	v_med3_i32 v40, v40, 0, s75
	v_lshl_add_u32 v40, v40, 9, v152
	global_load_dwordx4 v[88:91], v40, s[98:99]
	v_add_u32_e32 v40, s40, v226
	v_med3_i32 v40, v40, 0, s75
	v_cmp_lt_i32_e32 vcc, -1, v48
	s_nop 1
	v_cndmask_b32_e32 v48, 0, v49, vcc
	v_lshl_add_u32 v44, v40, 9, v158
	v_lshl_add_u32 v52, v48, 9, v158
	global_load_dwordx4 v[40:43], v44, s[100:101]
	s_nop 0
	global_load_dwordx4 v[44:47], v44, s[100:101] offset:64
	s_nop 0
	global_load_dwordx4 v[48:51], v52, s[100:101]
	s_nop 0
	global_load_dwordx4 v[52:55], v52, s[100:101] offset:64
	ds_read_b64_tr_b16 v[102:103], v169 offset:2304
	ds_read_b64_tr_b16 v[100:101], v169
	ds_read_b64_tr_b16 v[108:109], v169 offset:32
	ds_read_b64_tr_b16 v[110:111], v169 offset:2336
	ds_read_b64_tr_b16 v[144:145], v169 offset:64
	ds_read_b64_tr_b16 v[146:147], v169 offset:2368
	ds_read_b64_tr_b16 v[140:141], v169 offset:96
	ds_read_b64_tr_b16 v[142:143], v169 offset:2400
	s_waitcnt vmcnt(15)
	ds_write_b128 v241, v[16:19] offset:4608
	s_waitcnt vmcnt(14)
	ds_write_b128 v242, v[60:63] offset:4608
	s_waitcnt vmcnt(13)
	ds_write_b128 v243, v[92:95] offset:4608
	s_waitcnt vmcnt(12)
	ds_write_b128 v244, v[96:99] offset:4608
	v_mfma_f32_16x16x32_bf16 v[16:19], v[84:87], v[4:7], 0
	v_mfma_f32_16x16x32_bf16 v[60:63], v[76:79], v[4:7], 0
	v_mfma_f32_16x16x32_bf16 v[76:79], v[76:79], v[12:15], 0
	v_mfma_f32_16x16x32_bf16 v[16:19], v[80:83], v[8:11], v[16:19]
	v_mfma_f32_16x16x32_bf16 v[60:63], v[20:23], v[8:11], v[60:63]
	v_mfma_f32_16x16x32_bf16 v[20:23], v[20:23], v[0:3], v[76:79]
	v_mfma_f32_16x16x32_bf16 v[84:87], v[84:87], v[12:15], 0
	v_mfma_f32_16x16x32_bf16 v[80:83], v[80:83], v[0:3], v[84:87]
	s_nop 5
	v_sub_u32_e32 v21, v198, v150
	v_add_u32_e32 v23, 1, v21
	v_cmp_gt_u32_e64 s[0:1], v23, v149
	v_cmp_gt_u32_e32 vcc, v21, v149
	s_nop 0
	v_cndmask_b32_e64 v17, v17, v246, s[0:1]
	s_nop 0
	v_cndmask_b32_e32 v16, v16, v246, vcc
	v_max_f32_e32 v22, 0xf149f2ca, v16
	v_max_f32_e32 v22, v22, v17
	v_add_u32_e32 v23, 2, v21
	v_add_u32_e32 v76, 3, v21
	v_cmp_gt_u32_e64 s[22:23], v23, v149
	v_cmp_gt_u32_e64 s[24:25], v76, v149
	s_nop 0
	v_cndmask_b32_e64 v18, v18, v246, s[22:23]
	v_cndmask_b32_e64 v19, v19, v246, s[24:25]
	v_max3_f32 v22, v22, v18, v19
	v_add_u32_e32 v23, 16, v21
	v_add_u32_e32 v76, 17, v21
	v_cmp_gt_u32_e64 s[26:27], v23, v149
	v_cmp_gt_u32_e64 s[28:29], v76, v149
	s_nop 0
	v_cndmask_b32_e64 v60, v60, v246, s[26:27]
	v_cndmask_b32_e64 v61, v61, v246, s[28:29]
	v_max3_f32 v22, v22, v60, v61
	v_add_u32_e32 v23, 18, v21
	v_add_u32_e32 v21, 19, v21
	v_cmp_gt_u32_e64 s[30:31], v23, v149
	v_cmp_gt_u32_e64 s[34:35], v21, v149
	s_nop 0
	v_cndmask_b32_e64 v62, v62, v246, s[30:31]
	v_cndmask_b32_e64 v63, v63, v246, s[34:35]
	v_max3_f32 v21, v22, v62, v63
	v_max_f32_e32 v22, v80, v80
	v_max_f32_e32 v22, 0xf149f2ca, v22
	v_cndmask_b32_e64 v22, v246, v22, s[18:19]
	v_cndmask_b32_e64 v23, v246, v20, s[20:21]
	v_max3_f32 v22, v22, v23, s73
	v_mov_b32_e32 v23, v21
	v_mov_b32_e32 v76, v21
	s_nop 1
	v_permlane32_swap_b32_e32 v23, v76
	v_max3_f32 v21, v21, v23, v76
	v_mov_b32_e32 v23, v22
	v_mov_b32_e32 v76, v22
	s_nop 1
	v_permlane32_swap_b32_e32 v23, v76
	v_max3_f32 v22, v22, v23, v76
	v_mov_b32_e32 v23, v21
	v_mov_b32_e32 v76, v21
	s_nop 1
	v_permlane16_swap_b32_e32 v23, v76
	v_max_f32_e32 v21, v21, v23
	v_max3_f32 v151, v175, v21, v76
	v_sub_f32_e32 v16, v16, v151
	v_mov_b32_e32 v23, v22
	v_mov_b32_e32 v77, v22
	v_exp_f32_e32 v16, v16
	v_sub_f32_e32 v17, v17, v151
	v_permlane16_swap_b32_e32 v23, v77
	v_exp_f32_e32 v17, v17
	v_sub_f32_e32 v18, v18, v151
	v_exp_f32_e32 v18, v18
	v_sub_f32_e32 v19, v19, v151
	v_max_f32_e32 v22, v22, v23
	v_exp_f32_e32 v19, v19
	v_sub_f32_e32 v23, v60, v151
	v_sub_f32_e32 v21, v175, v151
	v_exp_f32_e32 v23, v23
	v_sub_f32_e32 v60, v61, v151
	v_exp_f32_e32 v76, v21
	v_add_f32_e32 v21, 0, v16
	v_exp_f32_e32 v60, v60
	v_sub_f32_e32 v61, v62, v151
	v_add_f32_e32 v21, v17, v21
	v_exp_f32_e32 v61, v61
	v_sub_f32_e32 v62, v63, v151
	v_add_f32_e32 v21, v18, v21
	v_exp_f32_e32 v62, v62
	v_add_f32_e32 v21, v19, v21
	v_add_f32_e32 v21, v23, v21
	v_add_f32_e32 v21, v60, v21
	v_add_f32_e32 v21, v61, v21
	v_max3_f32 v175, v177, v22, v77
	v_add_f32_e32 v149, v62, v21
	v_sub_f32_e32 v21, v177, v175
	v_cvt_pk_bf16_f32 v16, v16, v17
	v_cvt_pk_bf16_f32 v17, v18, v19
	v_cvt_pk_bf16_f32 v18, v23, v60
	v_exp_f32_e32 v60, v21
	v_sub_f32_e32 v21, v80, v175
	v_exp_f32_e32 v21, v21
	v_sub_f32_e32 v20, v20, v175
	v_exp_f32_e32 v20, v20
	v_cvt_pk_bf16_f32 v19, v61, v62
	v_cndmask_b32_e64 v21, 0, v21, s[18:19]
	v_add_f32_e32 v22, 0, v21
	v_cndmask_b32_e64 v23, 0, v20, s[20:21]
	v_pk_mul_f32 v[58:59], v[58:59], v[76:77] op_sel_hi:[1,0]
	v_pk_mul_f32 v[56:57], v[56:57], v[76:77] op_sel_hi:[1,0]
	v_add_f32_e32 v150, v23, v22
	v_cvt_pk_bf16_f32 v20, v21, 0
	v_cvt_pk_bf16_f32 v22, v23, 0
	v_mov_b32_e32 v21, v153
	v_mov_b32_e32 v23, v153
	s_waitcnt lgkmcnt(10)
	v_mfma_f32_16x16x32_bf16 v[96:99], v[100:103], v[16:19], v[56:59]
	v_fmac_f32_e32 v149, v176, v76
	v_fmac_f32_e32 v150, v178, v60
	s_min_i32 s0, s76, 0
	v_pk_mul_f32 v[58:59], v[114:115], v[60:61] op_sel_hi:[1,0]
	v_pk_mul_f32 v[56:57], v[112:113], v[60:61] op_sel_hi:[1,0]
	s_sub_i32 s0, 15, s0
	s_sub_i32 s1, s75, s76
	v_mfma_f32_16x16x32_bf16 v[100:103], v[100:103], v[20:23], v[56:59]
	s_ashr_i32 s0, s0, 4
	s_ashr_i32 s1, s1, 4
	s_cmpk_lt_i32 s71, 0x3000
	v_pk_mul_f32 v[58:59], v[118:119], v[76:77] op_sel_hi:[1,0]
	v_pk_mul_f32 v[56:57], v[116:117], v[76:77] op_sel_hi:[1,0]
	s_waitcnt lgkmcnt(8)
	s_nop 0
	v_mfma_f32_16x16x32_bf16 v[104:107], v[108:111], v[16:19], v[56:59]
	s_nop 2
	v_mul_f32_e64 v58, v122, v60
	v_mul_f32_e64 v59, v123, v60
	v_pk_mul_f32 v[56:57], v[120:121], v[60:61] op_sel_hi:[1,0]
	s_nop 1
	v_mfma_f32_16x16x32_bf16 v[108:111], v[108:111], v[20:23], v[56:59]
	s_nop 2
	v_mul_f32_e64 v58, v126, v76
	v_mul_f32_e64 v59, v127, v76
	v_pk_mul_f32 v[56:57], v[124:125], v[76:77] op_sel_hi:[1,0]
	s_waitcnt lgkmcnt(6)
	s_nop 0
	v_mfma_f32_16x16x32_bf16 v[112:115], v[144:147], v[16:19], v[56:59]
	s_nop 2
	v_mul_f32_e64 v58, v130, v60
	v_mul_f32_e64 v59, v131, v60
	v_pk_mul_f32 v[56:57], v[128:129], v[60:61] op_sel_hi:[1,0]
	s_nop 1
	v_mfma_f32_16x16x32_bf16 v[116:119], v[144:147], v[20:23], v[56:59]
	v_max_i32_e32 v145, s0, v148
	s_nop 1
	v_pk_mul_f32 v[58:59], v[134:135], v[76:77] op_sel_hi:[1,0]
	v_pk_mul_f32 v[56:57], v[132:133], v[76:77] op_sel_hi:[1,0]
	s_waitcnt lgkmcnt(4)
	s_nop 0
	v_mfma_f32_16x16x32_bf16 v[120:123], v[140:143], v[16:19], v[56:59]
	v_mul_f32_e64 v18, v138, v60
	v_mul_f32_e64 v19, v139, v60
	v_pk_mul_f32 v[16:17], v[136:137], v[60:61] op_sel_hi:[1,0]
	v_add_u32_e32 v56, s40, v228
	s_nop 0
	v_mfma_f32_16x16x32_bf16 v[124:127], v[140:143], v[20:23], v[16:19]
	s_nop 1
	s_nop 0
	v_add_u32_e32 v16, s40, v213
	v_med3_i32 v16, v16, 0, s75
	v_lshl_add_u32 v16, v16, 9, v152
	global_load_dwordx4 v[76:79], v16, s[98:99]
	v_add_u32_e32 v16, s40, v215
	v_med3_i32 v16, v16, 0, s75
	v_lshl_add_u32 v16, v16, 9, v152
	global_load_dwordx4 v[80:83], v16, s[98:99]
	v_add_u32_e32 v16, s40, v217
	v_med3_i32 v16, v16, 0, s75
	v_lshl_add_u32 v16, v16, 9, v152
	global_load_dwordx4 v[84:87], v16, s[98:99]
	v_add_u32_e32 v16, s40, v219
	v_med3_i32 v16, v16, 0, s75
	v_lshl_add_u32 v16, v16, 9, v152
	global_load_dwordx4 v[92:95], v16, s[98:99]
	v_or_b32_e32 v16, s40, v167
	v_min_i32_e32 v16, s75, v16
	v_cndmask_b32_e64 v16, v16, 0, s[38:39]
	v_med3_i32 v56, v56, 0, s75
	v_lshl_add_u32 v20, v16, 9, v158
	v_lshl_add_u32 v60, v56, 9, v158
	global_load_dwordx4 v[16:19], v20, s[100:101]
	s_nop 0
	global_load_dwordx4 v[20:23], v20, s[100:101] offset:64
	s_nop 0
	global_load_dwordx4 v[56:59], v60, s[100:101]
	s_nop 0
	global_load_dwordx4 v[60:63], v60, s[100:101] offset:64
	ds_read_b64_tr_b16 v[132:133], v169 offset:6912
	ds_read_b64_tr_b16 v[130:131], v169 offset:4608
	ds_read_b64_tr_b16 v[134:135], v169 offset:4640
	ds_read_b64_tr_b16 v[136:137], v169 offset:6944
	ds_read_b64_tr_b16 v[138:139], v169 offset:4672
	ds_read_b64_tr_b16 v[140:141], v169 offset:6976
	ds_read_b64_tr_b16 v[176:177], v169 offset:4704
	ds_read_b64_tr_b16 v[178:179], v169 offset:7008
	s_waitcnt vmcnt(15)
	ds_write_b128 v241, v[64:67]
	s_waitcnt vmcnt(14)
	ds_write_b128 v242, v[68:71]
	s_waitcnt vmcnt(13)
	ds_write_b128 v243, v[72:75]
	s_waitcnt vmcnt(12)
	ds_write_b128 v244, v[88:91]
	v_mfma_f32_16x16x32_bf16 v[64:67], v[24:27], v[4:7], 0
	v_mfma_f32_16x16x32_bf16 v[64:67], v[28:31], v[8:11], v[64:67]
	v_mfma_f32_16x16x32_bf16 v[24:27], v[24:27], v[12:15], 0
	v_mfma_f32_16x16x32_bf16 v[66:69], v[32:35], v[4:7], 0
	v_mfma_f32_16x16x32_bf16 v[24:27], v[28:31], v[0:3], v[24:27]
	v_mfma_f32_16x16x32_bf16 v[28:31], v[32:35], v[12:15], 0
	v_add_u32_e32 v32, 0x7f8, v249
	v_ashrrev_i32_e32 v32, 4, v32
	v_min3_i32 v32, v32, s1, v248
	v_mfma_f32_16x16x32_bf16 v[66:69], v[36:39], v[8:11], v[66:69]
	v_sub_u32_e32 v144, v32, v145
	v_max_f32_e32 v32, v64, v64
	v_sub_u32_e32 v33, v154, v145
	v_max_f32_e32 v32, 0xf149f2ca, v32
	v_cndmask_b32_e64 v32, v246, v32, s[36:37]
	s_nop 2
	v_cndmask_b32_e64 v34, v246, v66, s[4:5]
	v_add_u32_e32 v35, 1, v33
	v_max3_f32 v32, v32, v34, s73
	v_cmp_gt_u32_e64 s[0:1], v35, v144
	v_cmp_gt_u32_e32 vcc, v33, v144
	s_nop 0
	v_cndmask_b32_e64 v25, v25, v246, s[0:1]
	s_nop 0
	v_cndmask_b32_e32 v24, v24, v246, vcc
	v_max_f32_e32 v34, 0xf149f2ca, v24
	v_mfma_f32_16x16x32_bf16 v[28:31], v[36:39], v[0:3], v[28:31]
	v_max_f32_e32 v34, v34, v25
	v_add_u32_e32 v35, 2, v33
	v_add_u32_e32 v36, 3, v33
	v_cmp_gt_u32_e64 s[22:23], v35, v144
	v_cmp_gt_u32_e64 s[24:25], v36, v144
	s_nop 0
	v_cndmask_b32_e64 v26, v26, v246, s[22:23]
	v_cndmask_b32_e64 v27, v27, v246, s[24:25]
	v_max3_f32 v34, v34, v26, v27
	v_add_u32_e32 v35, 16, v33
	v_add_u32_e32 v36, 17, v33
	v_cmp_gt_u32_e64 s[26:27], v35, v144
	v_cmp_gt_u32_e64 s[28:29], v36, v144
	s_nop 0
	v_cndmask_b32_e64 v28, v28, v246, s[26:27]
	v_cndmask_b32_e64 v29, v29, v246, s[28:29]
	v_max3_f32 v34, v34, v28, v29
	v_add_u32_e32 v35, 18, v33
	v_add_u32_e32 v33, 19, v33
	v_cmp_gt_u32_e64 s[30:31], v35, v144
	v_cmp_gt_u32_e64 s[34:35], v33, v144
	s_nop 0
	v_cndmask_b32_e64 v30, v30, v246, s[30:31]
	v_cndmask_b32_e64 v31, v31, v246, s[34:35]
	v_max3_f32 v33, v34, v30, v31
	v_mov_b32_e32 v34, v32
	v_mov_b32_e32 v35, v32
	s_nop 1
	v_permlane32_swap_b32_e32 v34, v35
	v_max3_f32 v32, v32, v34, v35
	v_mov_b32_e32 v34, v33
	v_mov_b32_e32 v35, v33
	s_nop 1
	v_permlane32_swap_b32_e32 v34, v35
	v_max3_f32 v33, v33, v34, v35
	v_mov_b32_e32 v34, v32
	v_mov_b32_e32 v35, v32
	s_nop 1
	v_permlane16_swap_b32_e32 v34, v35
	v_max_f32_e32 v32, v32, v34
	v_mov_b32_e32 v34, v33
	v_mov_b32_e32 v37, v33
	s_nop 1
	v_permlane16_swap_b32_e32 v34, v37
	v_max_f32_e32 v38, v33, v34
	v_max3_f32 v128, v175, v38, v37
	v_sub_f32_e32 v24, v24, v128
	v_exp_f32_e32 v24, v24
	v_sub_f32_e32 v37, v175, v128
	v_exp_f32_e32 v38, v37
	v_max3_f32 v129, v151, v32, v35
	v_cndmask_b32_e64 v37, v24, 0, vcc
	v_sub_f32_e32 v24, v25, v128
	v_exp_f32_e32 v24, v24
	v_sub_f32_e32 v32, v151, v129
	v_exp_f32_e32 v36, v32
	v_sub_f32_e32 v32, v64, v129
	v_cndmask_b32_e64 v65, v24, 0, s[0:1]
	v_sub_f32_e32 v24, v26, v128
	v_exp_f32_e32 v32, v32
	v_exp_f32_e32 v24, v24
	v_mov_b32_e32 v33, v153
	v_mov_b32_e32 v35, v153
	v_cndmask_b32_e64 v39, 0, v32, s[36:37]
	v_sub_f32_e32 v32, v66, v129
	v_cndmask_b32_e64 v66, v24, 0, s[22:23]
	v_sub_f32_e32 v24, v27, v128
	v_exp_f32_e32 v24, v24
	v_exp_f32_e32 v32, v32
	v_cndmask_b32_e64 v67, v24, 0, s[24:25]
	v_sub_f32_e32 v24, v28, v128
	v_exp_f32_e32 v24, v24
	v_cndmask_b32_e64 v64, 0, v32, s[4:5]
	v_cvt_pk_bf16_f32 v32, v39, 0
	v_cvt_pk_bf16_f32 v34, v64, 0
	v_cndmask_b32_e64 v68, v24, 0, s[26:27]
	v_sub_f32_e32 v24, v29, v128
	v_exp_f32_e32 v24, v24
	v_pk_mul_f32 v[28:29], v[96:97], v[36:37] op_sel_hi:[1,0]
	v_cvt_pk_bf16_f32 v25, v66, v67
	v_cndmask_b32_e64 v69, v24, 0, s[28:29]
	v_sub_f32_e32 v24, v30, v128
	v_exp_f32_e32 v24, v24
	v_cvt_pk_bf16_f32 v26, v68, v69
	v_cndmask_b32_e64 v70, v24, 0, s[30:31]
	v_sub_f32_e32 v24, v31, v128
	v_exp_f32_e32 v24, v24
	v_pk_mul_f32 v[30:31], v[98:99], v[36:37] op_sel_hi:[1,0]
	v_cndmask_b32_e64 v71, v24, 0, s[34:35]
	v_cvt_pk_bf16_f32 v24, v37, v65
	v_cvt_pk_bf16_f32 v27, v70, v71
	s_waitcnt lgkmcnt(10)
	v_mfma_f32_16x16x32_bf16 v[96:99], v[130:133], v[32:35], v[28:31]
	s_nop 2
	v_mul_f32_e64 v30, v102, v38
	v_mul_f32_e64 v31, v103, v38
	v_pk_mul_f32 v[28:29], v[100:101], v[38:39] op_sel_hi:[1,0]
	s_nop 1
	v_mfma_f32_16x16x32_bf16 v[100:103], v[130:133], v[24:27], v[28:31]
	s_nop 2
	v_mul_f32_e64 v30, v106, v36
	v_mul_f32_e64 v31, v107, v36
	v_pk_mul_f32 v[28:29], v[104:105], v[36:37] op_sel_hi:[1,0]
	s_waitcnt lgkmcnt(8)
	s_nop 0
	v_mfma_f32_16x16x32_bf16 v[104:107], v[134:137], v[32:35], v[28:31]
	s_nop 2
	v_mul_f32_e64 v30, v110, v38
	v_mul_f32_e64 v31, v111, v38
	v_pk_mul_f32 v[28:29], v[108:109], v[38:39] op_sel_hi:[1,0]
	s_nop 1
	v_mfma_f32_16x16x32_bf16 v[108:111], v[134:137], v[24:27], v[28:31]
	s_nop 2
	v_mul_f32_e64 v30, v114, v36
	v_mul_f32_e64 v31, v115, v36
	v_pk_mul_f32 v[28:29], v[112:113], v[36:37] op_sel_hi:[1,0]
	s_waitcnt lgkmcnt(6)
	s_nop 0
	v_mfma_f32_16x16x32_bf16 v[112:115], v[138:141], v[32:35], v[28:31]
	s_nop 2
	v_mul_f32_e64 v30, v118, v38
	v_mul_f32_e64 v31, v119, v38
	v_pk_mul_f32 v[28:29], v[116:117], v[38:39] op_sel_hi:[1,0]
	s_nop 1
	v_mfma_f32_16x16x32_bf16 v[116:119], v[138:141], v[24:27], v[28:31]
	s_nop 2
	v_mul_f32_e64 v30, v122, v36
	v_mul_f32_e64 v31, v123, v36
	v_pk_mul_f32 v[28:29], v[120:121], v[36:37] op_sel_hi:[1,0]
	s_waitcnt lgkmcnt(4)
	s_nop 0
	v_mfma_f32_16x16x32_bf16 v[120:123], v[176:179], v[32:35], v[28:31]
	v_add_u32_e32 v32, s40, v234
	s_nop 0
	s_nop 0
	v_pk_mul_f32 v[30:31], v[126:127], v[38:39] op_sel_hi:[1,0]
	v_pk_mul_f32 v[28:29], v[124:125], v[38:39] op_sel_hi:[1,0]
	s_nop 1
	v_mfma_f32_16x16x32_bf16 v[124:127], v[176:179], v[24:27], v[28:31]
	v_add_f32_e32 v24, 0, v37
	v_add_f32_e32 v24, v65, v24
	v_add_f32_e32 v24, v66, v24
	v_add_f32_e32 v24, v67, v24
	v_add_f32_e32 v24, v68, v24
	v_add_f32_e32 v24, v69, v24
	v_add_f32_e32 v24, v70, v24
	v_add_f32_e32 v130, v71, v24
	v_add_f32_e32 v24, 0, v39
	v_add_f32_e32 v131, v64, v24
	v_add_u32_e32 v24, s40, v229
	v_fmac_f32_e32 v131, v149, v36
	v_fmac_f32_e32 v130, v150, v38
	v_med3_i32 v24, v24, 0, s75
	v_lshl_add_u32 v24, v24, 9, v152
	global_load_dwordx4 v[64:67], v24, s[98:99]
	v_add_u32_e32 v24, s40, v230
	v_med3_i32 v24, v24, 0, s75
	v_lshl_add_u32 v24, v24, 9, v152
	global_load_dwordx4 v[68:71], v24, s[98:99]
	v_add_u32_e32 v24, s40, v231
	v_med3_i32 v24, v24, 0, s75
	v_lshl_add_u32 v24, v24, 9, v152
	global_load_dwordx4 v[72:75], v24, s[98:99]
	v_add_u32_e32 v24, s40, v232
	v_med3_i32 v24, v24, 0, s75
	v_lshl_add_u32 v24, v24, 9, v152
	global_load_dwordx4 v[88:91], v24, s[98:99]
	v_add_u32_e32 v24, s40, v233
	v_med3_i32 v24, v24, 0, s75
	v_med3_i32 v32, v32, 0, s75
	v_lshl_add_u32 v28, v24, 9, v158
	v_lshl_add_u32 v36, v32, 9, v158
	global_load_dwordx4 v[24:27], v28, s[100:101]
	s_nop 0
	global_load_dwordx4 v[28:31], v28, s[100:101] offset:64
	s_nop 0
	global_load_dwordx4 v[32:35], v36, s[100:101]
	s_nop 0
	global_load_dwordx4 v[36:39], v36, s[100:101] offset:64
	ds_read_b64_tr_b16 v[134:135], v169 offset:2304
	ds_read_b64_tr_b16 v[132:133], v169
	ds_read_b64_tr_b16 v[136:137], v169 offset:32
	ds_read_b64_tr_b16 v[138:139], v169 offset:2336
	ds_read_b64_tr_b16 v[140:141], v169 offset:64
	ds_read_b64_tr_b16 v[142:143], v169 offset:2368
	ds_read_b64_tr_b16 v[176:177], v169 offset:96
	ds_read_b64_tr_b16 v[178:179], v169 offset:2400
	s_waitcnt vmcnt(15)
	ds_write_b128 v241, v[76:79] offset:4608
	s_waitcnt vmcnt(14)
	ds_write_b128 v242, v[80:83] offset:4608
	s_waitcnt vmcnt(13)
	ds_write_b128 v243, v[84:87] offset:4608
	s_waitcnt vmcnt(12)
	ds_write_b128 v244, v[92:95] offset:4608
	v_mfma_f32_16x16x32_bf16 v[76:79], v[40:43], v[4:7], 0
	v_mfma_f32_16x16x32_bf16 v[76:79], v[44:47], v[8:11], v[76:79]
	v_mfma_f32_16x16x32_bf16 v[78:81], v[48:51], v[4:7], 0
	v_mfma_f32_16x16x32_bf16 v[40:43], v[40:43], v[12:15], 0
	s_nop 5
	v_mov_b32_e32 v77, v153
	v_mfma_f32_16x16x32_bf16 v[78:81], v[52:55], v[8:11], v[78:81]
	v_mfma_f32_16x16x32_bf16 v[40:43], v[44:47], v[0:3], v[40:43]
	v_mfma_f32_16x16x32_bf16 v[44:47], v[48:51], v[12:15], 0
	v_max_f32_e32 v49, v76, v76
	v_sub_u32_e32 v48, v187, v145
	v_max_f32_e32 v49, 0xf149f2ca, v49
	v_cndmask_b32_e64 v49, v246, v49, s[6:7]
	s_nop 1
	v_cndmask_b32_e64 v50, v246, v78, s[8:9]
	v_add_u32_e32 v51, 1, v48
	v_max3_f32 v49, v49, v50, s73
	v_cmp_gt_u32_e64 s[0:1], v51, v144
	v_cmp_gt_u32_e32 vcc, v48, v144
	s_nop 0
	v_cndmask_b32_e64 v41, v41, v246, s[0:1]
	s_nop 0
	v_cndmask_b32_e32 v40, v40, v246, vcc
	v_max_f32_e32 v50, 0xf149f2ca, v40
	v_mfma_f32_16x16x32_bf16 v[44:47], v[52:55], v[0:3], v[44:47]
	v_max_f32_e32 v50, v50, v41
	v_add_u32_e32 v51, 2, v48
	v_add_u32_e32 v52, 3, v48
	v_cmp_gt_u32_e64 s[22:23], v51, v144
	v_cmp_gt_u32_e64 s[24:25], v52, v144
	v_mov_b32_e32 v79, v153
	v_cndmask_b32_e64 v42, v42, v246, s[22:23]
	v_cndmask_b32_e64 v43, v43, v246, s[24:25]
	v_max3_f32 v50, v50, v42, v43
	v_add_u32_e32 v51, 16, v48
	v_add_u32_e32 v52, 17, v48
	v_cmp_gt_u32_e64 s[26:27], v51, v144
	v_cmp_gt_u32_e64 s[28:29], v52, v144
	s_nop 0
	v_cndmask_b32_e64 v44, v44, v246, s[26:27]
	v_cndmask_b32_e64 v45, v45, v246, s[28:29]
	v_max3_f32 v50, v50, v44, v45
	v_add_u32_e32 v51, 18, v48
	v_add_u32_e32 v48, 19, v48
	v_cmp_gt_u32_e64 s[30:31], v51, v144
	v_cmp_gt_u32_e64 s[34:35], v48, v144
	s_nop 0
	v_cndmask_b32_e64 v46, v46, v246, s[30:31]
	v_cndmask_b32_e64 v47, v47, v246, s[34:35]
	v_max3_f32 v48, v50, v46, v47
	v_mov_b32_e32 v50, v49
	v_mov_b32_e32 v51, v49
	s_nop 1
	v_permlane32_swap_b32_e32 v50, v51
	v_max3_f32 v49, v49, v50, v51
	v_mov_b32_e32 v50, v48
	v_mov_b32_e32 v51, v48
	s_nop 1
	v_permlane32_swap_b32_e32 v50, v51
	v_max3_f32 v48, v48, v50, v51
	v_mov_b32_e32 v50, v49
	v_mov_b32_e32 v51, v49
	s_nop 1
	v_permlane16_swap_b32_e32 v50, v51
	v_max_f32_e32 v49, v49, v50
	v_mov_b32_e32 v50, v48
	v_mov_b32_e32 v52, v48
	s_nop 1
	v_permlane16_swap_b32_e32 v50, v52
	v_max_f32_e32 v48, v48, v50
	v_max3_f32 v148, v128, v48, v52
	v_sub_f32_e32 v40, v40, v148
	v_exp_f32_e32 v40, v40
	v_sub_f32_e32 v41, v41, v148
	v_exp_f32_e32 v41, v41
	v_sub_f32_e32 v42, v42, v148
	v_exp_f32_e32 v42, v42
	v_sub_f32_e32 v43, v43, v148
	v_exp_f32_e32 v43, v43
	v_sub_f32_e32 v44, v44, v148
	v_max3_f32 v146, v129, v49, v51
	v_sub_f32_e32 v48, v128, v148
	v_exp_f32_e32 v44, v44
	v_sub_f32_e32 v45, v45, v148
	v_sub_f32_e32 v49, v129, v146
	v_exp_f32_e32 v86, v48
	v_add_f32_e32 v48, 0, v40
	v_exp_f32_e32 v45, v45
	v_sub_f32_e32 v46, v46, v148
	v_sub_f32_e32 v47, v47, v148
	v_exp_f32_e32 v84, v49
	v_sub_f32_e32 v49, v76, v146
	v_sub_f32_e32 v51, v78, v146
	v_add_f32_e32 v48, v41, v48
	v_exp_f32_e32 v46, v46
	v_exp_f32_e32 v47, v47
	v_exp_f32_e32 v49, v49
	v_exp_f32_e32 v51, v51
	v_add_f32_e32 v48, v42, v48
	v_add_f32_e32 v48, v43, v48
	v_add_f32_e32 v48, v44, v48
	v_add_f32_e32 v48, v45, v48
	v_cndmask_b32_e64 v49, 0, v49, s[6:7]
	v_cndmask_b32_e64 v51, 0, v51, s[8:9]
	v_add_f32_e32 v48, v46, v48
	v_cvt_pk_bf16_f32 v40, v40, v41
	v_cvt_pk_bf16_f32 v41, v42, v43
	v_cvt_pk_bf16_f32 v42, v44, v45
	v_cvt_pk_bf16_f32 v43, v46, v47
	v_pk_mul_f32 v[82:83], v[110:111], v[86:87] op_sel_hi:[1,0]
	v_pk_mul_f32 v[80:81], v[108:109], v[86:87] op_sel_hi:[1,0]
	v_add_f32_e32 v50, 0, v49
	v_cvt_pk_bf16_f32 v76, v49, 0
	v_cvt_pk_bf16_f32 v78, v51, 0
	v_add_f32_e32 v149, v47, v48
	v_pk_mul_f32 v[46:47], v[98:99], v[84:85] op_sel_hi:[1,0]
	v_pk_mul_f32 v[44:45], v[96:97], v[84:85] op_sel_hi:[1,0]
	s_waitcnt lgkmcnt(8)
	v_mfma_f32_16x16x32_bf16 v[96:99], v[136:139], v[40:43], v[80:83]
	v_add_f32_e32 v147, v51, v50
	v_pk_mul_f32 v[50:51], v[102:103], v[86:87] op_sel_hi:[1,0]
	v_pk_mul_f32 v[48:49], v[100:101], v[86:87] op_sel_hi:[1,0]
	v_pk_mul_f32 v[82:83], v[114:115], v[84:85] op_sel_hi:[1,0]
	v_pk_mul_f32 v[80:81], v[112:113], v[84:85] op_sel_hi:[1,0]
	v_pk_mul_f32 v[54:55], v[106:107], v[84:85] op_sel_hi:[1,0]
	v_pk_mul_f32 v[52:53], v[104:105], v[84:85] op_sel_hi:[1,0]
	s_waitcnt lgkmcnt(6)
	v_mfma_f32_16x16x32_bf16 v[100:103], v[140:143], v[76:79], v[80:83]
	v_fmac_f32_e32 v147, v131, v84
	v_fmac_f32_e32 v149, v130, v86
	s_nop 0
	v_pk_mul_f32 v[82:83], v[118:119], v[86:87] op_sel_hi:[1,0]
	v_pk_mul_f32 v[80:81], v[116:117], v[86:87] op_sel_hi:[1,0]
	v_mfma_f32_16x16x32_bf16 v[44:47], v[132:135], v[76:79], v[44:47]
	s_nop 0
	v_mfma_f32_16x16x32_bf16 v[104:107], v[140:143], v[40:43], v[80:83]
	s_nop 2
	v_mul_f32_e64 v82, v122, v84
	v_mul_f32_e64 v83, v123, v84
	v_pk_mul_f32 v[80:81], v[120:121], v[84:85] op_sel_hi:[1,0]
	v_mfma_f32_16x16x32_bf16 v[52:55], v[136:139], v[76:79], v[52:55]
	v_add_u32_e32 v84, s40, v240
	s_waitcnt lgkmcnt(4)
	v_mfma_f32_16x16x32_bf16 v[108:111], v[176:179], v[76:79], v[80:83]
	v_mul_f32_e64 v78, v126, v86
	v_mul_f32_e64 v79, v127, v86
	v_pk_mul_f32 v[76:77], v[124:125], v[86:87] op_sel_hi:[1,0]
	v_mfma_f32_16x16x32_bf16 v[48:51], v[132:135], v[40:43], v[48:51]
	s_nop 0
	v_mfma_f32_16x16x32_bf16 v[112:115], v[176:179], v[40:43], v[76:79]
	v_add_u32_e32 v40, s40, v235
	s_nop 1
	v_add_u32_e32 v76, s40, v236
	v_med3_i32 v40, v40, 0, s75
	v_med3_i32 v76, v76, 0, s75
	v_lshl_add_u32 v40, v40, 9, v152
	v_lshl_add_u32 v76, v76, 9, v152
	global_load_dwordx4 v[40:43], v40, s[98:99]
	s_nop 0
	global_load_dwordx4 v[116:119], v76, s[98:99]
	v_add_u32_e32 v76, s40, v237
	v_med3_i32 v76, v76, 0, s75
	v_lshl_add_u32 v76, v76, 9, v152
	global_load_dwordx4 v[120:123], v76, s[98:99]
	v_add_u32_e32 v76, s40, v238
	v_med3_i32 v76, v76, 0, s75
	v_lshl_add_u32 v76, v76, 9, v152
	global_load_dwordx4 v[124:127], v76, s[98:99]
	v_add_u32_e32 v76, s40, v239
	v_med3_i32 v76, v76, 0, s75
	v_med3_i32 v84, v84, 0, s75
	v_lshl_add_u32 v80, v76, 9, v158
	v_lshl_add_u32 v84, v84, 9, v158
	global_load_dwordx4 v[76:79], v80, s[100:101]
	s_nop 0
	global_load_dwordx4 v[80:83], v80, s[100:101] offset:64
	s_nop 0
	global_load_dwordx4 v[92:95], v84, s[100:101]
	s_nop 0
	global_load_dwordx4 v[84:87], v84, s[100:101] offset:64
	ds_read_b64_tr_b16 v[142:143], v169 offset:6912
	ds_read_b64_tr_b16 v[140:141], v169 offset:4608
	ds_read_b64_tr_b16 v[136:137], v169 offset:4640
	ds_read_b64_tr_b16 v[138:139], v169 offset:6944
	ds_read_b64_tr_b16 v[132:133], v169 offset:4672
	ds_read_b64_tr_b16 v[134:135], v169 offset:6976
	ds_read_b64_tr_b16 v[128:129], v169 offset:4704
	ds_read_b64_tr_b16 v[130:131], v169 offset:7008
	s_waitcnt vmcnt(15)
	ds_write_b128 v241, v[64:67]
	s_waitcnt vmcnt(14)
	ds_write_b128 v242, v[68:71]
	s_waitcnt vmcnt(13)
	ds_write_b128 v243, v[72:75]
	s_waitcnt vmcnt(12)
	ds_write_b128 v244, v[88:91]
	v_mfma_f32_16x16x32_bf16 v[64:67], v[16:19], v[4:7], 0
	v_mfma_f32_16x16x32_bf16 v[64:67], v[20:23], v[8:11], v[64:67]
	v_mfma_f32_16x16x32_bf16 v[66:69], v[56:59], v[4:7], 0
	v_mfma_f32_16x16x32_bf16 v[16:19], v[16:19], v[12:15], 0
	v_mfma_f32_16x16x32_bf16 v[66:69], v[60:63], v[8:11], v[66:69]
	v_mfma_f32_16x16x32_bf16 v[16:19], v[20:23], v[0:3], v[16:19]
	v_mfma_f32_16x16x32_bf16 v[20:23], v[56:59], v[12:15], 0
	s_nop 2
	v_max_f32_e32 v57, v64, v64
	v_sub_u32_e32 v56, v192, v145
	v_max_f32_e32 v57, 0xf149f2ca, v57
	v_cndmask_b32_e64 v57, v246, v57, s[10:11]
	v_cndmask_b32_e64 v58, v246, v66, s[12:13]
	v_add_u32_e32 v59, 1, v56
	v_max3_f32 v57, v57, v58, s73
	v_cmp_gt_u32_e64 s[0:1], v59, v144
	v_cmp_gt_u32_e32 vcc, v56, v144
	s_nop 0
	v_cndmask_b32_e64 v17, v17, v246, s[0:1]
	s_nop 0
	v_cndmask_b32_e32 v16, v16, v246, vcc
	v_max_f32_e32 v58, 0xf149f2ca, v16
	v_mfma_f32_16x16x32_bf16 v[20:23], v[60:63], v[0:3], v[20:23]
	v_max_f32_e32 v58, v58, v17
	v_add_u32_e32 v59, 2, v56
	v_add_u32_e32 v60, 3, v56
	v_cmp_gt_u32_e64 s[22:23], v59, v144
	v_cmp_gt_u32_e64 s[24:25], v60, v144
	v_mov_b32_e32 v61, v153
	v_cndmask_b32_e64 v18, v18, v246, s[22:23]
	v_cndmask_b32_e64 v19, v19, v246, s[24:25]
	v_max3_f32 v58, v58, v18, v19
	v_add_u32_e32 v59, 16, v56
	v_add_u32_e32 v60, 17, v56
	v_cmp_gt_u32_e64 s[26:27], v59, v144
	v_cmp_gt_u32_e64 s[28:29], v60, v144
	v_mov_b32_e32 v63, v153
	v_cndmask_b32_e64 v20, v20, v246, s[26:27]
	v_cndmask_b32_e64 v60, v21, v246, s[28:29]
	v_max3_f32 v58, v58, v20, v60
	v_add_u32_e32 v59, 18, v56
	v_add_u32_e32 v56, 19, v56
	v_cmp_gt_u32_e64 s[30:31], v59, v144
	v_cmp_gt_u32_e64 s[34:35], v56, v144
	s_nop 0
	v_cndmask_b32_e64 v22, v22, v246, s[30:31]
	v_cndmask_b32_e64 v23, v23, v246, s[34:35]
	v_max3_f32 v56, v58, v22, v23
	v_mov_b32_e32 v58, v57
	v_mov_b32_e32 v59, v57
	s_nop 1
	v_permlane32_swap_b32_e32 v58, v59
	v_max3_f32 v57, v57, v58, v59
	v_mov_b32_e32 v58, v56
	v_mov_b32_e32 v59, v56
	s_nop 1
	v_permlane32_swap_b32_e32 v58, v59
	v_max3_f32 v56, v56, v58, v59
	v_mov_b32_e32 v58, v57
	v_mov_b32_e32 v59, v57
	s_nop 1
	v_permlane16_swap_b32_e32 v58, v59
	v_max_f32_e32 v57, v57, v58
	v_mov_b32_e32 v58, v56
	v_mov_b32_e32 v65, v56
	s_nop 1
	v_permlane16_swap_b32_e32 v58, v65
	v_max_f32_e32 v56, v56, v58
	v_max3_f32 v151, v148, v56, v65
	v_sub_f32_e32 v16, v16, v151
	v_exp_f32_e32 v16, v16
	v_sub_f32_e32 v17, v17, v151
	v_max3_f32 v150, v146, v57, v59
	v_exp_f32_e32 v17, v17
	v_sub_f32_e32 v18, v18, v151
	v_sub_f32_e32 v57, v146, v150
	v_exp_f32_e32 v18, v18
	v_sub_f32_e32 v19, v19, v151
	v_exp_f32_e32 v68, v57
	v_sub_f32_e32 v57, v64, v150
	v_exp_f32_e32 v19, v19
	v_sub_f32_e32 v20, v20, v151
	v_exp_f32_e32 v57, v57
	v_sub_f32_e32 v59, v66, v150
	v_sub_f32_e32 v56, v148, v151
	v_exp_f32_e32 v20, v20
	v_sub_f32_e32 v21, v21, v151
	v_exp_f32_e32 v59, v59
	v_exp_f32_e32 v72, v56
	v_add_f32_e32 v56, 0, v16
	v_exp_f32_e32 v21, v21
	v_sub_f32_e32 v22, v22, v151
	v_add_f32_e32 v56, v17, v56
	v_exp_f32_e32 v22, v22
	v_sub_f32_e32 v23, v23, v151
	v_add_f32_e32 v56, v18, v56
	v_exp_f32_e32 v23, v23
	v_cndmask_b32_e64 v57, 0, v57, s[10:11]
	v_add_f32_e32 v56, v19, v56
	v_add_f32_e32 v58, 0, v57
	v_cndmask_b32_e64 v59, 0, v59, s[12:13]
	v_add_f32_e32 v56, v20, v56
	v_cndmask_b32_e64 v21, v21, 0, s[28:29]
	v_add_f32_e32 v146, v59, v58
	v_add_f32_e32 v56, v21, v56
	v_fmac_f32_e32 v146, v147, v68
	v_cvt_pk_bf16_f32 v60, v57, 0
	v_cvt_pk_bf16_f32 v62, v59, 0
	v_add_f32_e32 v56, v22, v56
	v_cvt_pk_bf16_f32 v64, v16, v17
	v_cvt_pk_bf16_f32 v65, v18, v19
	v_pk_mul_f32 v[18:19], v[46:47], v[68:69] op_sel_hi:[1,0]
	v_pk_mul_f32 v[16:17], v[44:45], v[68:69] op_sel_hi:[1,0]
	v_pk_mul_f32 v[46:47], v[54:55], v[68:69] op_sel_hi:[1,0]
	v_pk_mul_f32 v[44:45], v[52:53], v[68:69] op_sel_hi:[1,0]
	v_pk_mul_f32 v[54:55], v[102:103], v[68:69] op_sel_hi:[1,0]
	v_pk_mul_f32 v[52:53], v[100:101], v[68:69] op_sel_hi:[1,0]
	v_pk_mul_f32 v[70:71], v[110:111], v[68:69] op_sel_hi:[1,0]
	v_pk_mul_f32 v[68:69], v[108:109], v[68:69] op_sel_hi:[1,0]
	v_add_f32_e32 v147, v23, v56
	v_cvt_pk_bf16_f32 v66, v20, v21
	v_cvt_pk_bf16_f32 v67, v22, v23
	s_waitcnt lgkmcnt(10)
	v_mfma_f32_16x16x32_bf16 v[16:19], v[140:143], v[60:63], v[16:19]
	v_mul_f32_e64 v22, v50, v72
	v_mul_f32_e64 v23, v51, v72
	v_pk_mul_f32 v[20:21], v[48:49], v[72:73] op_sel_hi:[1,0]
	v_pk_mul_f32 v[50:51], v[98:99], v[72:73] op_sel_hi:[1,0]
	s_waitcnt lgkmcnt(8)
	v_mfma_f32_16x16x32_bf16 v[44:47], v[136:139], v[60:63], v[44:47]
	v_mul_f32_e64 v48, v96, v72
	v_mul_f32_e64 v49, v97, v72
	v_pk_mul_f32 v[58:59], v[106:107], v[72:73] op_sel_hi:[1,0]
	v_pk_mul_f32 v[56:57], v[104:105], v[72:73] op_sel_hi:[1,0]
	s_waitcnt lgkmcnt(6)
	v_mfma_f32_16x16x32_bf16 v[52:55], v[132:135], v[60:63], v[52:55]
	v_fmac_f32_e32 v147, v149, v72
	s_waitcnt lgkmcnt(4)
	v_mfma_f32_16x16x32_bf16 v[60:63], v[128:131], v[60:63], v[68:71]
	s_nop 2
	v_mul_f32_e64 v70, v114, v72
	v_mul_f32_e64 v71, v115, v72
	v_pk_mul_f32 v[68:69], v[112:113], v[72:73] op_sel_hi:[1,0]
	v_mfma_f32_16x16x32_bf16 v[20:23], v[140:143], v[64:67], v[20:23]
	v_mfma_f32_16x16x32_bf16 v[48:51], v[136:139], v[64:67], v[48:51]
	v_mfma_f32_16x16x32_bf16 v[56:59], v[132:135], v[64:67], v[56:59]
	v_mfma_f32_16x16x32_bf16 v[64:67], v[128:131], v[64:67], v[68:71]
	ds_read_b64_tr_b16 v[98:99], v169 offset:2304
	ds_read_b64_tr_b16 v[96:97], v169
	ds_read_b64_tr_b16 v[88:89], v169 offset:32
	ds_read_b64_tr_b16 v[90:91], v169 offset:2336
	ds_read_b64_tr_b16 v[72:73], v169 offset:64
	ds_read_b64_tr_b16 v[74:75], v169 offset:2368
	ds_read_b64_tr_b16 v[68:69], v169 offset:96
	ds_read_b64_tr_b16 v[70:71], v169 offset:2400
	s_waitcnt vmcnt(7)
	ds_write_b128 v241, v[40:43] offset:4608
	s_waitcnt vmcnt(6)
	ds_write_b128 v242, v[116:119] offset:4608
	s_waitcnt vmcnt(5)
	ds_write_b128 v243, v[120:123] offset:4608
	s_waitcnt vmcnt(4)
	ds_write_b128 v244, v[124:127] offset:4608
	v_mfma_f32_16x16x32_bf16 v[40:43], v[24:27], v[4:7], 0
	v_mfma_f32_16x16x32_bf16 v[100:103], v[32:35], v[4:7], 0
	v_mfma_f32_16x16x32_bf16 v[24:27], v[24:27], v[12:15], 0
	v_mfma_f32_16x16x32_bf16 v[40:43], v[28:31], v[8:11], v[40:43]
	v_mfma_f32_16x16x32_bf16 v[100:103], v[36:39], v[8:11], v[100:103]
	v_mfma_f32_16x16x32_bf16 v[24:27], v[28:31], v[0:3], v[24:27]
	s_nop 5
	v_mov_b32_e32 v41, v153
	v_mov_b32_e32 v43, v153
	v_mfma_f32_16x16x32_bf16 v[28:31], v[32:35], v[12:15], 0
	v_max_f32_e32 v33, v40, v40
	v_sub_u32_e32 v32, v197, v145
	v_max_f32_e32 v33, 0xf149f2ca, v33
	v_cndmask_b32_e64 v33, v246, v33, s[14:15]
	v_cndmask_b32_e64 v34, v246, v100, s[16:17]
	v_add_u32_e32 v35, 1, v32
	v_max3_f32 v33, v33, v34, s73
	v_cmp_gt_u32_e64 s[0:1], v35, v144
	v_cmp_gt_u32_e32 vcc, v32, v144
	s_nop 0
	v_cndmask_b32_e64 v25, v25, v246, s[0:1]
	s_nop 0
	v_cndmask_b32_e32 v24, v24, v246, vcc
	v_max_f32_e32 v34, 0xf149f2ca, v24
	v_mfma_f32_16x16x32_bf16 v[28:31], v[36:39], v[0:3], v[28:31]
	v_max_f32_e32 v34, v34, v25
	v_add_u32_e32 v35, 2, v32
	v_add_u32_e32 v36, 3, v32
	v_cmp_gt_u32_e64 s[22:23], v35, v144
	v_cmp_gt_u32_e64 s[24:25], v36, v144
	s_nop 0
	v_cndmask_b32_e64 v26, v26, v246, s[22:23]
	v_cndmask_b32_e64 v27, v27, v246, s[24:25]
	v_max3_f32 v34, v34, v26, v27
	v_add_u32_e32 v35, 16, v32
	v_add_u32_e32 v36, 17, v32
	v_cmp_gt_u32_e64 s[26:27], v35, v144
	v_cmp_gt_u32_e64 s[28:29], v36, v144
	s_nop 0
	v_cndmask_b32_e64 v28, v28, v246, s[26:27]
	v_cndmask_b32_e64 v29, v29, v246, s[28:29]
	v_max3_f32 v34, v34, v28, v29
	v_add_u32_e32 v35, 18, v32
	v_add_u32_e32 v32, 19, v32
	v_cmp_gt_u32_e64 s[30:31], v35, v144
	v_cmp_gt_u32_e64 s[34:35], v32, v144
	s_nop 0
	v_cndmask_b32_e64 v30, v30, v246, s[30:31]
	v_cndmask_b32_e64 v31, v31, v246, s[34:35]
	v_max3_f32 v32, v34, v30, v31
	v_mov_b32_e32 v34, v33
	v_mov_b32_e32 v35, v33
	s_nop 1
	v_permlane32_swap_b32_e32 v34, v35
	v_max3_f32 v33, v33, v34, v35
	v_mov_b32_e32 v34, v32
	v_mov_b32_e32 v35, v32
	s_nop 1
	v_permlane32_swap_b32_e32 v34, v35
	v_max3_f32 v32, v32, v34, v35
	v_mov_b32_e32 v34, v33
	v_mov_b32_e32 v35, v33
	s_nop 1
	v_permlane16_swap_b32_e32 v34, v35
	v_max_f32_e32 v33, v33, v34
	v_max3_f32 v101, v150, v33, v35
	v_sub_f32_e32 v33, v150, v101
	v_exp_f32_e32 v106, v33
	v_sub_f32_e32 v33, v40, v101
	v_mov_b32_e32 v34, v32
	v_mov_b32_e32 v36, v32
	v_exp_f32_e32 v33, v33
	s_nop 0
	v_permlane16_swap_b32_e32 v34, v36
	v_max_f32_e32 v32, v32, v34
	v_cndmask_b32_e64 v107, 0, v33, s[14:15]
	v_sub_f32_e32 v33, v100, v101
	v_max3_f32 v100, v151, v32, v36
	v_sub_f32_e32 v24, v24, v100
	v_exp_f32_e32 v24, v24
	v_exp_f32_e32 v33, v33
	v_sub_f32_e32 v32, v151, v100
	v_exp_f32_e32 v108, v32
	v_cndmask_b32_e64 v110, v24, 0, vcc
	v_sub_f32_e32 v24, v25, v100
	v_exp_f32_e32 v24, v24
	v_cndmask_b32_e64 v109, 0, v33, s[16:17]
	v_cvt_pk_bf16_f32 v40, v107, 0
	v_cvt_pk_bf16_f32 v42, v109, 0
	v_cndmask_b32_e64 v111, v24, 0, s[0:1]
	v_sub_f32_e32 v24, v26, v100
	v_exp_f32_e32 v24, v24
	v_pk_mul_f32 v[18:19], v[18:19], v[106:107] op_sel_hi:[1,0]
	v_pk_mul_f32 v[16:17], v[16:17], v[106:107] op_sel_hi:[1,0]
	v_pk_mul_f32 v[34:35], v[54:55], v[106:107] op_sel_hi:[1,0]
	v_cndmask_b32_e64 v112, v24, 0, s[22:23]
	v_sub_f32_e32 v24, v27, v100
	v_exp_f32_e32 v24, v24
	v_pk_mul_f32 v[26:27], v[46:47], v[106:107] op_sel_hi:[1,0]
	v_pk_mul_f32 v[32:33], v[52:53], v[106:107] op_sel_hi:[1,0]
	v_pk_mul_f32 v[46:47], v[62:63], v[106:107] op_sel_hi:[1,0]
	v_cndmask_b32_e64 v113, v24, 0, s[24:25]
	v_sub_f32_e32 v24, v28, v100
	v_exp_f32_e32 v24, v24
	s_waitcnt lgkmcnt(10)
	v_mfma_f32_16x16x32_bf16 v[16:19], v[96:99], v[40:43], v[16:19]
	v_cvt_pk_bf16_f32 v102, v110, v111
	v_cvt_pk_bf16_f32 v103, v112, v113
	v_cndmask_b32_e64 v114, v24, 0, s[26:27]
	v_sub_f32_e32 v24, v29, v100
	v_exp_f32_e32 v24, v24
	s_waitcnt lgkmcnt(6)
	v_mfma_f32_16x16x32_bf16 v[32:35], v[72:75], v[40:43], v[32:35]
	v_mul_f32_e64 v28, v48, v108
	v_mul_f32_e64 v29, v49, v108
	v_add_f32_e32 v48, 0, v110
	v_cndmask_b32_e64 v115, v24, 0, s[28:29]
	v_sub_f32_e32 v24, v30, v100
	v_exp_f32_e32 v24, v24
	v_add_f32_e32 v48, v111, v48
	v_add_f32_e32 v48, v112, v48
	v_add_f32_e32 v48, v113, v48
	v_cndmask_b32_e64 v116, v24, 0, s[30:31]
	v_sub_f32_e32 v24, v31, v100
	v_exp_f32_e32 v24, v24
	v_add_f32_e32 v48, v114, v48
	v_add_f32_e32 v48, v115, v48
	v_cvt_pk_bf16_f32 v104, v114, v115
	v_cndmask_b32_e64 v117, v24, 0, s[34:35]
	v_pk_mul_f32 v[24:25], v[44:45], v[106:107] op_sel_hi:[1,0]
	v_pk_mul_f32 v[44:45], v[60:61], v[106:107] op_sel_hi:[1,0]
	v_cvt_pk_bf16_f32 v105, v116, v117
	v_mfma_f32_16x16x32_bf16 v[24:27], v[88:91], v[40:43], v[24:27]
	v_add_f32_e32 v48, v116, v48
	v_pk_mul_f32 v[38:39], v[58:59], v[108:109] op_sel_hi:[1,0]
	v_pk_mul_f32 v[36:37], v[56:57], v[108:109] op_sel_hi:[1,0]
	s_waitcnt lgkmcnt(4)
	v_mfma_f32_16x16x32_bf16 v[40:43], v[68:71], v[40:43], v[44:47]
	v_mul_f32_e64 v30, v50, v108
	v_mul_f32_e64 v31, v51, v108
	v_pk_mul_f32 v[22:23], v[22:23], v[108:109] op_sel_hi:[1,0]
	v_pk_mul_f32 v[20:21], v[20:21], v[108:109] op_sel_hi:[1,0]
	v_pk_mul_f32 v[46:47], v[66:67], v[108:109] op_sel_hi:[1,0]
	v_pk_mul_f32 v[44:45], v[64:65], v[108:109] op_sel_hi:[1,0]
	s_waitcnt vmcnt(3)
	v_mfma_f32_16x16x32_bf16 v[64:67], v[76:79], v[4:7], 0
	s_waitcnt vmcnt(1)
	v_mfma_f32_16x16x32_bf16 v[4:7], v[92:95], v[4:7], 0
	v_mfma_f32_16x16x32_bf16 v[64:67], v[80:83], v[8:11], v[64:67]
	s_waitcnt vmcnt(0)
	v_mfma_f32_16x16x32_bf16 v[8:11], v[84:87], v[8:11], v[4:7]
	v_mfma_f32_16x16x32_bf16 v[4:7], v[76:79], v[12:15], 0
	v_mfma_f32_16x16x32_bf16 v[10:13], v[92:95], v[12:15], 0
	s_nop 5
	v_sub_u32_e32 v9, v198, v145
	v_cmp_gt_u32_e64 s[34:35], v9, v144
	v_mov_b32_e32 v15, v153
	v_mfma_f32_16x16x32_bf16 v[4:7], v[80:83], v[0:3], v[4:7]
	v_mfma_f32_16x16x32_bf16 v[0:3], v[84:87], v[0:3], v[10:13]
	s_nop 2
	v_max_f32_e32 v10, v64, v64
	v_max_f32_e32 v10, 0xf149f2ca, v10
	v_cndmask_b32_e64 v10, v246, v10, s[18:19]
	v_cndmask_b32_e64 v11, v246, v8, s[20:21]
	v_add_u32_e32 v12, 1, v9
	v_max3_f32 v10, v10, v11, s73
	v_cmp_gt_u32_e64 s[30:31], v12, v144
	v_cndmask_b32_e64 v4, v4, v246, s[34:35]
	v_max_f32_e32 v11, 0xf149f2ca, v4
	v_cndmask_b32_e64 v5, v5, v246, s[30:31]
	v_max_f32_e32 v11, v11, v5
	v_add_u32_e32 v12, 2, v9
	v_add_u32_e32 v13, 3, v9
	v_cmp_gt_u32_e64 s[28:29], v12, v144
	v_cmp_gt_u32_e64 s[26:27], v13, v144
	v_mfma_f32_16x16x32_bf16 v[44:47], v[68:71], v[102:105], v[44:47]
	v_cndmask_b32_e64 v6, v6, v246, s[28:29]
	v_cndmask_b32_e64 v7, v7, v246, s[26:27]
	v_max3_f32 v11, v11, v6, v7
	v_add_u32_e32 v12, 16, v9
	v_add_u32_e32 v13, 17, v9
	v_cmp_gt_u32_e64 s[24:25], v12, v144
	v_cmp_gt_u32_e64 s[22:23], v13, v144
	v_add_f32_e32 v68, v117, v48
	v_cndmask_b32_e64 v0, v0, v246, s[24:25]
	v_cndmask_b32_e64 v13, v1, v246, s[22:23]
	v_max3_f32 v11, v11, v0, v13
	v_add_u32_e32 v12, 18, v9
	v_add_u32_e32 v9, 19, v9
	v_cmp_gt_u32_e64 s[0:1], v12, v144
	v_cmp_gt_u32_e32 vcc, v9, v144
	v_add_f32_e32 v48, 0, v107
	v_cndmask_b32_e64 v2, v2, v246, s[0:1]
	v_cndmask_b32_e64 v3, v3, v246, vcc
	v_max3_f32 v9, v11, v2, v3
	v_mov_b32_e32 v11, v10
	v_mov_b32_e32 v12, v10
	s_nop 1
	v_permlane32_swap_b32_e32 v11, v12
	v_max3_f32 v10, v10, v11, v12
	v_mov_b32_e32 v11, v9
	v_mov_b32_e32 v12, v9
	s_nop 1
	v_permlane32_swap_b32_e32 v11, v12
	v_max3_f32 v9, v9, v11, v12
	v_mov_b32_e32 v11, v10
	v_mov_b32_e32 v12, v10
	s_nop 1
	v_permlane16_swap_b32_e32 v11, v12
	v_max_f32_e32 v10, v10, v11
	v_mov_b32_e32 v11, v9
	v_mov_b32_e32 v67, v9
	s_nop 1
	v_permlane16_swap_b32_e32 v11, v67
	v_max3_f32 v10, v101, v10, v12
	v_max_f32_e32 v9, v9, v11
	v_sub_f32_e32 v11, v101, v10
	v_exp_f32_e32 v66, v11
	v_sub_f32_e32 v11, v64, v10
	v_exp_f32_e32 v11, v11
	v_sub_f32_e32 v8, v8, v10
	v_exp_f32_e32 v8, v8
	v_add_f32_e32 v69, v109, v48
	v_cndmask_b32_e64 v11, 0, v11, s[18:19]
	v_add_f32_e32 v12, 0, v11
	v_cndmask_b32_e64 v8, 0, v8, s[20:21]
	v_fmac_f32_e32 v69, v146, v106
	v_add_f32_e32 v65, v8, v12
	v_cvt_pk_bf16_f32 v14, v8, 0
	v_max3_f32 v8, v100, v9, v67
	v_fmac_f32_e32 v65, v69, v66
	v_sub_f32_e32 v4, v4, v8
	v_cvt_pk_bf16_f32 v12, v11, 0
	v_exp_f32_e32 v4, v4
	v_sub_f32_e32 v5, v5, v8
	v_pk_mul_f32 v[10:11], v[34:35], v[66:67] op_sel_hi:[1,0]
	ds_bpermute_b32 v34, v170, v65
	v_exp_f32_e32 v5, v5
	v_sub_f32_e32 v6, v6, v8
	v_exp_f32_e32 v6, v6
	v_sub_f32_e32 v7, v7, v8
	v_exp_f32_e32 v7, v7
	v_sub_f32_e32 v0, v0, v8
	v_sub_f32_e32 v9, v100, v8
	v_exp_f32_e32 v0, v0
	v_sub_f32_e32 v1, v1, v8
	v_mfma_f32_16x16x32_bf16 v[36:39], v[72:75], v[102:105], v[36:39]
	v_exp_f32_e32 v72, v9
	v_add_f32_e32 v9, 0, v4
	v_exp_f32_e32 v1, v1
	v_sub_f32_e32 v2, v2, v8
	s_waitcnt lgkmcnt(0)
	v_add_f32_e32 v34, v65, v34
	v_add_f32_e32 v9, v5, v9
	v_exp_f32_e32 v2, v2
	v_sub_f32_e32 v3, v3, v8
	ds_bpermute_b32 v35, v171, v34
	v_add_f32_e32 v9, v6, v9
	v_exp_f32_e32 v3, v3
	v_add_f32_e32 v9, v7, v9
	v_add_f32_e32 v9, v0, v9
	v_cndmask_b32_e64 v1, v1, 0, s[22:23]
	ds_read_b64_tr_b16 v[62:63], v169 offset:6912
	ds_read_b64_tr_b16 v[60:61], v169 offset:4608
	ds_read_b64_tr_b16 v[56:57], v169 offset:4640
	ds_read_b64_tr_b16 v[58:59], v169 offset:6944
	ds_read_b64_tr_b16 v[52:53], v169 offset:4672
	ds_read_b64_tr_b16 v[54:55], v169 offset:6976
	ds_read_b64_tr_b16 v[48:49], v169 offset:4704
	ds_read_b64_tr_b16 v[50:51], v169 offset:7008
	v_add_f32_e32 v9, v1, v9
	v_add_f32_e32 v9, v2, v9
	s_waitcnt lgkmcnt(8)
	v_add_f32_e32 v34, v34, v35
	v_fmac_f32_e32 v68, v147, v108
	v_mov_b32_e32 v13, v153
	v_add_f32_e32 v64, v3, v9
	v_pk_mul_f32 v[8:9], v[32:33], v[66:67] op_sel_hi:[1,0]
	v_div_scale_f32 v35, s[0:1], v34, v34, 1.0
	v_fmac_f32_e32 v64, v68, v72
	v_cvt_pk_bf16_f32 v68, v4, v5
	v_cvt_pk_bf16_f32 v69, v6, v7
	v_pk_mul_f32 v[6:7], v[26:27], v[66:67] op_sel_hi:[1,0]
	v_pk_mul_f32 v[4:5], v[24:25], v[66:67] op_sel_hi:[1,0]
	s_waitcnt lgkmcnt(2)
	v_mfma_f32_16x16x32_bf16 v[24:27], v[52:55], v[12:15], v[8:11]
	v_cvt_pk_bf16_f32 v70, v0, v1
	v_cvt_pk_bf16_f32 v71, v2, v3
	v_pk_mul_f32 v[2:3], v[18:19], v[66:67] op_sel_hi:[1,0]
	v_pk_mul_f32 v[8:9], v[36:37], v[72:73] op_sel_hi:[1,0]
	v_rcp_f32_e32 v36, v35
	v_mfma_f32_16x16x32_bf16 v[20:23], v[96:99], v[102:105], v[20:23]
	v_mul_f32_e64 v10, v38, v72
	v_mul_f32_e64 v11, v39, v72
	v_pk_mul_f32 v[0:1], v[16:17], v[66:67] op_sel_hi:[1,0]
	v_fma_f32 v37, -v35, v36, 1.0
	v_fmac_f32_e32 v36, v37, v36
	v_div_scale_f32 v37, vcc, 1.0, v34, 1.0
	v_mul_f32_e32 v38, v37, v36
	v_fma_f32 v39, -v35, v38, v37
	v_mfma_f32_16x16x32_bf16 v[16:19], v[60:63], v[12:15], v[0:3]
	v_fmac_f32_e32 v38, v39, v36
	v_fma_f32 v35, -v35, v38, v37
	v_div_fmas_f32 v35, v35, v36, v38
	v_mfma_f32_16x16x32_bf16 v[28:31], v[88:91], v[102:105], v[28:31]
	v_mul_f32_e64 v2, v22, v72
	v_mul_f32_e64 v3, v23, v72
	v_pk_mul_f32 v[0:1], v[20:21], v[72:73] op_sel_hi:[1,0]
	v_div_fixup_f32 v34, v35, v34, 1.0
	v_mfma_f32_16x16x32_bf16 v[20:23], v[56:59], v[12:15], v[4:7]
	v_lshl_add_u64 v[32:33], v[156:157], 0, s[56:57]
	v_lshlrev_b64 v[36:37], 11, v[162:163]
	v_pk_mul_f32 v[16:17], v[16:17], v[34:35] op_sel_hi:[1,0]
	v_pk_mul_f32 v[18:19], v[18:19], v[34:35] op_sel_hi:[1,0]
	v_pk_mul_f32 v[6:7], v[30:31], v[72:73] op_sel_hi:[1,0]
	v_pk_mul_f32 v[4:5], v[28:29], v[72:73] op_sel_hi:[1,0]
	v_pk_mul_f32 v[30:31], v[42:43], v[66:67] op_sel_hi:[1,0]
	v_pk_mul_f32 v[28:29], v[40:41], v[66:67] op_sel_hi:[1,0]
	v_lshl_add_u64 v[36:37], v[32:33], 0, v[36:37]
	v_cvt_pk_bf16_f32 v16, v16, v17
	v_cvt_pk_bf16_f32 v17, v18, v19
	s_waitcnt lgkmcnt(0)
	v_mfma_f32_16x16x32_bf16 v[28:31], v[48:51], v[12:15], v[28:31]
	global_store_dwordx2 v[36:37], v[16:17], off
	v_pk_mul_f32 v[16:17], v[20:21], v[34:35] op_sel_hi:[1,0]
	v_pk_mul_f32 v[18:19], v[22:23], v[34:35] op_sel_hi:[1,0]
	v_cvt_pk_bf16_f32 v16, v16, v17
	v_cvt_pk_bf16_f32 v17, v18, v19
	global_store_dwordx2 v[36:37], v[16:17], off offset:32
	v_pk_mul_f32 v[16:17], v[24:25], v[34:35] op_sel_hi:[1,0]
	v_pk_mul_f32 v[18:19], v[26:27], v[34:35] op_sel_hi:[1,0]
	v_cvt_pk_bf16_f32 v16, v16, v17
	v_cvt_pk_bf16_f32 v17, v18, v19
	global_store_dwordx2 v[36:37], v[16:17], off offset:64
	v_pk_mul_f32 v[16:17], v[28:29], v[34:35] op_sel_hi:[1,0]
	v_pk_mul_f32 v[18:19], v[30:31], v[34:35] op_sel_hi:[1,0]
	v_cvt_pk_bf16_f32 v16, v16, v17
	v_cvt_pk_bf16_f32 v17, v18, v19
	global_store_dwordx2 v[36:37], v[16:17], off offset:96
	ds_bpermute_b32 v16, v170, v64
	v_mfma_f32_16x16x32_bf16 v[0:3], v[60:63], v[68:71], v[0:3]
	v_mul_f32_e64 v14, v46, v72
	v_mul_f32_e64 v15, v47, v72
	v_pk_mul_f32 v[12:13], v[44:45], v[72:73] op_sel_hi:[1,0]
	s_waitcnt lgkmcnt(0)
	v_add_f32_e32 v16, v64, v16
	ds_bpermute_b32 v17, v171, v16
	v_mfma_f32_16x16x32_bf16 v[4:7], v[56:59], v[68:71], v[4:7]
	s_waitcnt lgkmcnt(0)
	v_add_f32_e32 v16, v16, v17
	v_div_scale_f32 v17, s[0:1], v16, v16, 1.0
	v_rcp_f32_e32 v18, v17
	v_mfma_f32_16x16x32_bf16 v[8:11], v[52:55], v[68:71], v[8:11]
	v_fma_f32 v19, -v17, v18, 1.0
	v_fmac_f32_e32 v18, v19, v18
	v_div_scale_f32 v19, vcc, 1.0, v16, 1.0
	v_mul_f32_e32 v20, v19, v18
	v_fma_f32 v21, -v17, v20, v19
	v_fmac_f32_e32 v20, v21, v18
	v_fma_f32 v17, -v17, v20, v19
	v_div_fmas_f32 v17, v17, v18, v20
	v_div_fixup_f32 v16, v17, v16, 1.0
	v_lshlrev_b64 v[18:19], 11, v[160:161]
	v_pk_mul_f32 v[0:1], v[0:1], v[16:17] op_sel_hi:[1,0]
	v_pk_mul_f32 v[2:3], v[2:3], v[16:17] op_sel_hi:[1,0]
	v_lshl_add_u64 v[18:19], v[32:33], 0, v[18:19]
	v_cvt_pk_bf16_f32 v0, v0, v1
	v_cvt_pk_bf16_f32 v1, v2, v3
	v_mfma_f32_16x16x32_bf16 v[12:15], v[48:51], v[68:71], v[12:15]
	global_store_dwordx2 v[18:19], v[0:1], off
	v_pk_mul_f32 v[0:1], v[4:5], v[16:17] op_sel_hi:[1,0]
	v_pk_mul_f32 v[2:3], v[6:7], v[16:17] op_sel_hi:[1,0]
	v_cvt_pk_bf16_f32 v0, v0, v1
	v_cvt_pk_bf16_f32 v1, v2, v3
	global_store_dwordx2 v[18:19], v[0:1], off offset:32
	v_pk_mul_f32 v[0:1], v[8:9], v[16:17] op_sel_hi:[1,0]
	v_pk_mul_f32 v[2:3], v[10:11], v[16:17] op_sel_hi:[1,0]
	v_cvt_pk_bf16_f32 v0, v0, v1
	v_cvt_pk_bf16_f32 v1, v2, v3
	global_store_dwordx2 v[18:19], v[0:1], off offset:64
	v_pk_mul_f32 v[0:1], v[12:13], v[16:17] op_sel_hi:[1,0]
	v_pk_mul_f32 v[2:3], v[14:15], v[16:17] op_sel_hi:[1,0]
	v_cvt_pk_bf16_f32 v0, v0, v1
	v_cvt_pk_bf16_f32 v1, v2, v3
	global_store_dwordx2 v[18:19], v[0:1], off offset:96
	s_cbranch_scc1 .LBB0_246
	s_mov_b32 s76, s79
	v_readlane_b32 s72, v253, 43
	v_xor_b32_e32 v240, 32, v174
	v_xor_b32_e32 v241, 16, v174
	v_xor_b32_e32 v242, 8, v174
	v_xor_b32_e32 v243, 4, v174
	v_xor_b32_e32 v244, 2, v174
	v_xor_b32_e32 v245, 1, v174
	v_and_b32_e32 v246, 64, v174

.LBB0_1026:
	s_or_b64 exec, exec, s[0:1]
	s_add_i32 s75, s75, s53
	s_add_u32 s0, s66, s51
	s_addc_u32 s1, s67, 0
	s_add_u32 s0, s0, s52
	v_add_u32_e32 v60, s75, v60
	s_addc_u32 s1, s1, 0
	v_add_u32_e32 v61, s75, v88
	v_cndmask_b32_e64 v90, -1, v60, s[38:39]
	v_lshl_add_u64 v[74:75], v[74:75], 2, s[0:1]
	v_add_u32_e32 v60, s75, v78
	s_mov_b32 s0, 0x1000000
	v_cndmask_b32_e64 v88, -1, v61, s[46:47]
	v_add_u32_e32 v61, s75, v76
	v_cndmask_b32_e32 v91, -1, v60, vcc
	v_add_co_u32_e32 v60, vcc, s0, v74
	v_cndmask_b32_e64 v89, -1, v61, s[42:43]
	s_nop 0
	v_addc_co_u32_e32 v61, vcc, 0, v75, vcc
	global_store_dwordx4 v[60:61], v[88:91], off
	v_cmp_gt_u32_e64 s[46:47], v56, v72
	v_cmp_eq_u32_e64 s[42:43], v56, v72
	v_mov_b32_e32 v60, 0x10000
	v_cndmask_b32_e64 v79, 0, 1, s[46:47]
	v_cndmask_b32_e64 v61, 0, v60, s[42:43]
	v_or_b32_e32 v61, v61, v79
	v_cmp_gt_u32_e64 s[44:45], v57, v72
	v_cmp_eq_u32_e64 s[38:39], v57, v72
	v_cmp_gt_u32_e64 s[40:41], v58, v72
	v_addc_co_u32_e64 v61, vcc, 0, v61, s[44:45]
	v_cndmask_b32_e64 v62, 0, v60, s[38:39]
	v_cmp_eq_u32_e32 vcc, v58, v72
	v_addc_co_u32_e64 v61, s[0:1], v61, v62, s[40:41]
	s_nop 0
	v_cndmask_b32_e32 v63, 0, v60, vcc
	v_cmp_gt_u32_e64 s[0:1], v59, v72
	v_cmp_eq_u32_e64 s[36:37], v59, v72
	s_nop 0
	v_addc_co_u32_e64 v61, s[48:49], v61, v63, s[0:1]
	v_cndmask_b32_e64 v60, 0, v60, s[36:37]
	v_add_u32_e32 v76, v61, v60
	ds_bpermute_b32 v60, v82, v76
	s_waitcnt lgkmcnt(0)
	v_cndmask_b32_e64 v60, 0, v60, s[6:7]
	v_add_u32_e32 v60, v60, v76
	ds_bpermute_b32 v61, v83, v60
	s_waitcnt lgkmcnt(0)
	v_cndmask_b32_e64 v61, v61, 0, s[8:9]
	v_add_u32_e32 v60, v61, v60
	ds_bpermute_b32 v61, v84, v60
	s_waitcnt lgkmcnt(0)
	v_cndmask_b32_e64 v61, v61, 0, s[10:11]
	v_add_u32_e32 v60, v61, v60
	ds_bpermute_b32 v61, v85, v60
	s_waitcnt lgkmcnt(0)
	v_cndmask_b32_e64 v61, v61, 0, s[12:13]
	v_add_u32_e32 v60, v61, v60
	ds_bpermute_b32 v61, v86, v60
	s_waitcnt lgkmcnt(0)
	v_cndmask_b32_e64 v61, v61, 0, s[14:15]
	v_add_u32_e32 v60, v61, v60
	ds_bpermute_b32 v61, v87, v60
	s_waitcnt lgkmcnt(0)
	v_cndmask_b32_e64 v61, v61, 0, s[4:5]
	v_add_u32_e32 v88, v61, v60
	s_and_saveexec_b64 s[48:49], s[16:17]
	v_mov_b32_e32 v60, s69
	ds_write_b32 v60, v88 offset:2080
	s_or_b64 exec, exec, s[48:49]
	v_add_u32_e32 v60, v69, v68
	v_add_u32_e32 v60, v60, v70
	v_add_u32_e32 v60, v60, v71
	v_add_u32_e32 v60, v60, v64
	v_add_u32_e32 v60, v60, v65
	v_mov_b32_e32 v77, 0
	v_add_u32_e32 v60, v60, v66
	s_waitcnt lgkmcnt(0)
	s_barrier
	ds_read_b128 v[68:71], v77 offset:2080
	v_add_u32_e32 v78, v60, v67
	ds_read_b128 v[60:63], v77 offset:2096
	v_sub_u32_e32 v76, v88, v76
	v_readlane_b32 s48, v253, 16
	s_waitcnt lgkmcnt(1)
	v_cndmask_b32_e64 v67, 0, v71, s[22:23]
	v_cndmask_b32_e64 v66, 0, v70, s[20:21]
	s_waitcnt lgkmcnt(0)
	v_cndmask_b32_e64 v91, 0, v62, s[28:29]
	v_cndmask_b32_e64 v92, 0, v63, s[30:31]
	v_cndmask_b32_e64 v90, 0, v61, s[26:27]
	v_add_u32_e32 v88, v92, v91
	v_cndmask_b32_e64 v89, 0, v60, s[24:25]
	v_add_u32_e32 v88, v88, v90
	v_add_u32_e32 v88, v88, v89
	v_add_u32_e32 v67, v88, v67
	v_readlane_b32 s49, v253, 17
	v_cndmask_b32_e64 v65, 0, v69, s[18:19]
	v_add_u32_e32 v66, v67, v66
	v_cndmask_b32_e64 v64, v68, 0, s[48:49]
	v_add_u32_e32 v65, v66, v65
	v_add_u32_e32 v64, v65, v64
	v_add_u32_e32 v64, v64, v76
	v_add_u32_sdwa v65, v64, v78 dst_sel:DWORD dst_unused:UNUSED_PAD src0_sel:WORD_0 src1_sel:WORD_0
	v_add_u32_sdwa v64, v64, v78 dst_sel:DWORD dst_unused:UNUSED_PAD src0_sel:WORD_1 src1_sel:WORD_1
	s_nop 0
	v_cmp_lt_u32_e64 s[48:49], v64, v73
	v_min_u32_e32 v66, v64, v73
	s_and_b64 s[48:49], s[42:43], s[48:49]
	v_add_u32_e32 v76, v66, v65
	s_or_b64 s[48:49], s[46:47], s[48:49]
	v_cmp_gt_u32_e64 s[46:47], s50, v76
	s_and_b64 s[46:47], s[48:49], s[46:47]
	s_and_saveexec_b64 s[48:49], s[46:47]
	s_cbranch_execz .LBB0_1030
	v_lshlrev_b64 v[66:67], 2, v[76:77]
	v_lshl_add_u64 v[88:89], s[70:71], 0, v[66:67]
	v_add_u32_e32 v77, 0x800, v81
	v_lshl_add_u64 v[66:67], s[72:73], 0, v[66:67]
	global_store_dword v[88:89], v77, off
	global_store_dword v[66:67], v56, off
